# GEMM phases: first K-loop iteration peeled with SrcC=0 on first-touch MFMAs; per-tile accumulator zeroing (128 v_mov) removed
# speedup vs baseline: 1.0085x; 1.0085x over previous
; #define PG8_STAGE(bufoff, gbase, voff) do { _Pragma("unroll") for (int _i = 0; _i < 2; ++_i) \
;         __builtin_amdgcn_global_load_lds((const unsigned*)((const char*)(gbase) + (voff)[_i]), (LAS unsigned*)(lds + (bufoff) + ldsw + _i * 8192), 16, 0, 0); } while (0)
; #define PG8_LDA(dst, b, h) do { _Pragma("unroll") for (int m = 0; m < 4; ++m) _Pragma("unroll") for (int k = 0; k < 2; ++k) dst[m][k] = *(const LAS bf16x8*)(lds + PG8_SA(b, h) + aoff + m * 2048 + k * 1024); } while (0)
; #define PG8_LDB(dst, b, h) do { _Pragma("unroll") for (int n = 0; n < 2; ++n) _Pragma("unroll") for (int k = 0; k < 2; ++k) dst[n][k] = *(const LAS bf16x8*)(lds + PG8_SB(b, h) + boff + n * 2048 + k * 1024); } while (0)
; #define PG8_WAIT_V(n) asm volatile("s_waitcnt vmcnt(" #n ")" ::: "memory")
; template <class Epi>
; __device__ __forceinline__ void gemm_phase(LAS unsigned char* lds, const Gemm g, const StaticOrder& S, const Epi& E) {
;     ...
;         const bool has_next = S.next(ui + 1, nxt);
;         const char* nA = has_next ? (const char*)g.A + (size_t)nxt.pm * tstepA : cA; const char* nB = has_next ? (const char*)g.Bt + (size_t)nxt.pn * tstepB : cB;
; #pragma nounroll
;         for (int t = 0; t < nt; t += 2) {
;             const bool last = (t == nt - 2);
;             const char* a1 = cA + (size_t)(t + 1) * kstep;
;             const char* a2 = last ? nA : cA + (size_t)(t + 2) * kstep; const char* b2 = last ? nB : cB + (size_t)(t + 2) * kstep;
;             const char* a3 = a2 + kstep; const char* b3 = b2 + kstep;
;             PG8_LDB(B0, 0, 0); PG8_LDB(B1, 0, 1); PG8_SCHED; PG8_LDA(At, 0, 0); PG8_STAGE(PG8_SA(1, 1), a1 + hstepA, voffA);
;             PG8_WAIT_V(8); PG8_WAIT_L(0); PG8_BAR; PG8_MMA(0, 0, At, B0); PG8_MMA(0, 1, At, B1); PG8_BAR; PG8_SCHED;
;             PG8_LDA(At, 0, 1); PG8_STAGE(PG8_SB(0, 0), b2, voffB); PG8_STAGE(PG8_SB(0, 1), b2 + hstepB, voffB); PG8_STAGE(PG8_SA(0, 0), a2, voffA);
;             PG8_WAIT_V(8); PG8_WAIT_L(0); PG8_BAR; PG8_MMA(1, 0, At, B0); PG8_MMA(1, 1, At, B1); PG8_BAR; PG8_SCHED;
;     ...
; #pragma unroll
;         for (int a = 0; a < 2; ++a)
; #pragma unroll
;             for (int b = 0; b < 2; ++b)
; #pragma unroll
;                 for (int m = 0; m < 4; ++m)
; #pragma unroll
;                     for (int n = 0; n < 2; ++n) acc[a][b][m][n] = (f32x4){0.f, 0.f, 0.f, 0.f};
;         cur = nxt; cA = nA; cB = nB; ++ui;
.LBB0_191:
	s_ashr_i32 s65, s64, 31
	s_lshl_b64 s[68:69], s[64:65], 19
	s_add_u32 s68, s24, s68
	s_addc_u32 s69, s25, s69
	s_and_b64 s[70:71], s[4:5], exec
	s_cselect_b32 s7, s69, s75
	s_cselect_b32 s65, s68, s74
	s_ashr_i32 s63, s62, 31
	s_lshl_b64 s[70:71], s[62:63], 19
	s_add_u32 s70, s10, s70
	s_addc_u32 s71, s11, s71
	s_and_b64 s[78:79], s[4:5], exec
	s_cselect_b32 s63, s71, s77
	s_cselect_b32 s73, s70, s76
	s_add_u32 s74, s74, 0x40080
	s_addc_u32 s75, s75, 0
	s_add_u32 s87, s76, 0x100
	s_addc_u32 s88, s77, 0
	s_mov_b32 s89, -2
	ds_read_b128 v[144:147], v153
	ds_read_b128 v[158:161], v153 offset:1024
	ds_read_b128 v[162:165], v153 offset:2048
	ds_read_b128 v[166:169], v153 offset:3072
	ds_read_b128 v[170:173], v154
	ds_read_b128 v[178:181], v154 offset:1024
	ds_read_b128 v[182:185], v154 offset:2048
	ds_read_b128 v[186:189], v154 offset:3072
	s_add_u32 s76, s74, 0xfffc0080
	s_addc_u32 s77, s75, -1
	s_cmp_eq_u32 s89, 12
	s_cselect_b32 s79, s7, s77
	s_cselect_b32 s78, s65, s76
	s_cselect_b32 s77, s63, s88
	s_cselect_b32 s76, s73, s87
	v_lshl_add_u64 v[148:149], s[74:75], 0, v[136:137]
	s_add_i32 m0, s19, 0xc000
	ds_read_b128 v[190:193], v155
	ds_read_b128 v[194:197], v155 offset:1024
	ds_read_b128 v[198:201], v155 offset:2048
	ds_read_b128 v[202:205], v155 offset:3072
	ds_read_b128 v[206:209], v155 offset:4096
	ds_read_b128 v[210:213], v155 offset:5120
	ds_read_b128 v[214:217], v155 offset:6144
	ds_read_b128 v[218:221], v155 offset:7168
	global_load_lds_dwordx4 v[148:149], off
	v_lshl_add_u64 v[148:149], s[74:75], 0, v[138:139]
	s_add_i32 m0, s19, 0xe000
	s_nop 0
	global_load_lds_dwordx4 v[148:149], off
	s_waitcnt vmcnt(8)
	s_waitcnt lgkmcnt(0)
	s_barrier
	s_setprio 1
	s_waitcnt lgkmcnt(0)
	v_mfma_f32_16x16x32_bf16 v[124:127], v[144:147], v[190:193], 0
	v_mfma_f32_16x16x32_bf16 v[120:123], v[162:165], v[190:193], 0
	v_mfma_f32_16x16x32_bf16 v[108:111], v[144:147], v[198:201], 0
	v_mfma_f32_16x16x32_bf16 v[104:107], v[162:165], v[198:201], 0
	v_mfma_f32_16x16x32_bf16 v[92:95], v[144:147], v[206:209], 0
	v_mfma_f32_16x16x32_bf16 v[88:91], v[162:165], v[206:209], 0
	v_mfma_f32_16x16x32_bf16 v[76:79], v[144:147], v[214:217], 0
	v_mfma_f32_16x16x32_bf16 v[72:75], v[162:165], v[214:217], 0
	v_mfma_f32_16x16x32_bf16 v[124:127], v[158:161], v[194:197], v[124:127]
	v_mfma_f32_16x16x32_bf16 v[120:123], v[166:169], v[194:197], v[120:123]
	v_mfma_f32_16x16x32_bf16 v[108:111], v[158:161], v[202:205], v[108:111]
	v_mfma_f32_16x16x32_bf16 v[104:107], v[166:169], v[202:205], v[104:107]
	v_mfma_f32_16x16x32_bf16 v[92:95], v[158:161], v[210:213], v[92:95]
	v_mfma_f32_16x16x32_bf16 v[88:91], v[166:169], v[210:213], v[88:91]
	v_mfma_f32_16x16x32_bf16 v[76:79], v[158:161], v[218:221], v[76:79]
	v_mfma_f32_16x16x32_bf16 v[72:75], v[166:169], v[218:221], v[72:75]
	s_setprio 0
	s_setprio 1
	v_mfma_f32_16x16x32_bf16 v[116:119], v[170:173], v[190:193], 0
	v_mfma_f32_16x16x32_bf16 v[112:115], v[182:185], v[190:193], 0
	v_mfma_f32_16x16x32_bf16 v[100:103], v[170:173], v[198:201], 0
	v_mfma_f32_16x16x32_bf16 v[96:99], v[182:185], v[198:201], 0
	v_mfma_f32_16x16x32_bf16 v[84:87], v[170:173], v[206:209], 0
	v_mfma_f32_16x16x32_bf16 v[80:83], v[182:185], v[206:209], 0
	v_mfma_f32_16x16x32_bf16 v[68:71], v[170:173], v[214:217], 0
	v_mfma_f32_16x16x32_bf16 v[64:67], v[182:185], v[214:217], 0
	v_mfma_f32_16x16x32_bf16 v[116:119], v[178:181], v[194:197], v[116:119]
	v_mfma_f32_16x16x32_bf16 v[112:115], v[186:189], v[194:197], v[112:115]
	v_mfma_f32_16x16x32_bf16 v[100:103], v[178:181], v[202:205], v[100:103]
	v_mfma_f32_16x16x32_bf16 v[96:99], v[186:189], v[202:205], v[96:99]
	v_mfma_f32_16x16x32_bf16 v[84:87], v[178:181], v[210:213], v[84:87]
	v_mfma_f32_16x16x32_bf16 v[80:83], v[186:189], v[210:213], v[80:83]
	v_mfma_f32_16x16x32_bf16 v[68:71], v[178:181], v[218:221], v[68:71]
	v_mfma_f32_16x16x32_bf16 v[64:67], v[186:189], v[218:221], v[64:67]
	s_setprio 0
	s_barrier
	s_add_i32 s90, s84, s3
	v_lshl_add_u64 v[148:149], s[76:77], 0, v[130:131]
	s_mov_b32 m0, s90
	ds_read_b128 v[190:193], v155 offset:16384
	ds_read_b128 v[194:197], v155 offset:17408
	ds_read_b128 v[198:201], v155 offset:18432
	ds_read_b128 v[202:205], v155 offset:19456
	ds_read_b128 v[206:209], v155 offset:20480
	ds_read_b128 v[210:213], v155 offset:21504
	ds_read_b128 v[214:217], v155 offset:22528
	ds_read_b128 v[218:221], v155 offset:23552
	global_load_lds_dwordx4 v[148:149], off
	s_add_i32 m0, s90, 0x2000
	s_add_u32 s90, s76, 0x40000
	v_lshl_add_u64 v[174:175], s[76:77], 0, v[134:135]
	s_addc_u32 s91, s77, 0
	s_add_i32 s92, s85, s3
	global_load_lds_dwordx4 v[174:175], off
	v_lshl_add_u64 v[222:223], s[90:91], 0, v[130:131]
	s_mov_b32 m0, s92
	v_lshl_add_u64 v[226:227], s[78:79], 0, v[132:133]
	global_load_lds_dwordx4 v[222:223], off
	v_lshl_add_u64 v[222:223], s[90:91], 0, v[134:135]
	s_add_i32 m0, s92, 0x2000
	s_nop 0
	global_load_lds_dwordx4 v[222:223], off
	v_lshl_add_u64 v[222:223], s[78:79], 0, v[128:129]
	s_mov_b32 m0, s19
	s_nop 0
	global_load_lds_dwordx4 v[222:223], off
	s_mov_b32 m0, s23
	s_nop 0
	global_load_lds_dwordx4 v[226:227], off
	s_waitcnt vmcnt(8)
	s_waitcnt lgkmcnt(0)
	s_barrier
; #define PG8_STAGE(bufoff, gbase, voff) do { _Pragma("unroll") for (int _i = 0; _i < 2; ++_i) \
;         __builtin_amdgcn_global_load_lds((const unsigned*)((const char*)(gbase) + (voff)[_i]), (LAS unsigned*)(lds + (bufoff) + ldsw + _i * 8192), 16, 0, 0); } while (0)
; #define PG8_LDA(dst, b, h) do { _Pragma("unroll") for (int m = 0; m < 4; ++m) _Pragma("unroll") for (int k = 0; k < 2; ++k) dst[m][k] = *(const LAS bf16x8*)(lds + PG8_SA(b, h) + aoff + m * 2048 + k * 1024); } while (0)
; #define PG8_LDB(dst, b, h) do { _Pragma("unroll") for (int n = 0; n < 2; ++n) _Pragma("unroll") for (int k = 0; k < 2; ++k) dst[n][k] = *(const LAS bf16x8*)(lds + PG8_SB(b, h) + boff + n * 2048 + k * 1024); } while (0)
; #define PG8_MMA(ai, bj, At, Bt) do { __builtin_amdgcn_s_setprio(1); _Pragma("unroll") for (int m = 0; m < 4; ++m) _Pragma("unroll") for (int n = 0; n < 2; ++n) _Pragma("unroll") for (int k = 0; k < 2; ++k) \
;         acc[ai][bj][m][n] = __builtin_amdgcn_mfma_f32_16x16x32_bf16(Bt[n][k], At[m][k], acc[ai][bj][m][n], 0, 0, 0); __builtin_amdgcn_s_setprio(0); } while (0)
; #define PG8_WAIT_V(n) asm volatile("s_waitcnt vmcnt(" #n ")" ::: "memory")
; #define PG8_WAIT_L(n) asm volatile("s_waitcnt lgkmcnt(" #n ")" ::: "memory")
; #define PG8_BAR __builtin_amdgcn_s_barrier()
; #define PG8_SCHED __builtin_amdgcn_sched_barrier(0)
; template <class Epi>
; __device__ __forceinline__ void gemm_phase(LAS unsigned char* lds, const Gemm g, const StaticOrder& S, const Epi& E) {
;     ...
;             PG8_WAIT_V(8); PG8_WAIT_L(0); PG8_BAR; PG8_MMA(1, 0, At, B0); PG8_MMA(1, 1, At, B1); PG8_BAR; PG8_SCHED;
;             PG8_LDB(B0, 1, 0); PG8_LDB(B1, 1, 1); PG8_SCHED; PG8_LDA(At, 1, 0); PG8_STAGE(PG8_SA(0, 1), a2 + hstepA, voffA);
;             PG8_WAIT_V(8); PG8_WAIT_L(0); PG8_BAR; PG8_MMA(0, 0, At, B0); PG8_MMA(0, 1, At, B1); PG8_BAR; PG8_SCHED;
;             PG8_LDA(At, 1, 1); PG8_STAGE(PG8_SB(1, 0), b3, voffB); PG8_STAGE(PG8_SB(1, 1), b3 + hstepB, voffB); PG8_STAGE(PG8_SA(1, 0), a3, voffA);
;             PG8_WAIT_V(8); PG8_WAIT_L(0); PG8_BAR; PG8_MMA(1, 0, At, B0); PG8_MMA(1, 1, At, B1); PG8_BAR; PG8_SCHED;
	s_setprio 1
	s_waitcnt lgkmcnt(0)
	v_mfma_f32_16x16x32_bf16 v[60:63], v[144:147], v[190:193], 0
	v_mfma_f32_16x16x32_bf16 v[56:59], v[162:165], v[190:193], 0
	v_mfma_f32_16x16x32_bf16 v[44:47], v[144:147], v[198:201], 0
	v_mfma_f32_16x16x32_bf16 v[40:43], v[162:165], v[198:201], 0
	v_mfma_f32_16x16x32_bf16 v[28:31], v[144:147], v[206:209], 0
	v_mfma_f32_16x16x32_bf16 v[24:27], v[162:165], v[206:209], 0
	v_mfma_f32_16x16x32_bf16 v[12:15], v[144:147], v[214:217], 0
	v_mfma_f32_16x16x32_bf16 v[8:11], v[162:165], v[214:217], 0
	v_mfma_f32_16x16x32_bf16 v[60:63], v[158:161], v[194:197], v[60:63]
	v_mfma_f32_16x16x32_bf16 v[56:59], v[166:169], v[194:197], v[56:59]
	v_mfma_f32_16x16x32_bf16 v[44:47], v[158:161], v[202:205], v[44:47]
	v_mfma_f32_16x16x32_bf16 v[40:43], v[166:169], v[202:205], v[40:43]
	v_mfma_f32_16x16x32_bf16 v[28:31], v[158:161], v[210:213], v[28:31]
	v_mfma_f32_16x16x32_bf16 v[24:27], v[166:169], v[210:213], v[24:27]
	v_mfma_f32_16x16x32_bf16 v[12:15], v[158:161], v[218:221], v[12:15]
	v_mfma_f32_16x16x32_bf16 v[8:11], v[166:169], v[218:221], v[8:11]
	s_setprio 0
	s_setprio 1
	v_mfma_f32_16x16x32_bf16 v[52:55], v[170:173], v[190:193], 0
	v_mfma_f32_16x16x32_bf16 v[48:51], v[182:185], v[190:193], 0
	v_mfma_f32_16x16x32_bf16 v[36:39], v[170:173], v[198:201], 0
	v_mfma_f32_16x16x32_bf16 v[32:35], v[182:185], v[198:201], 0
	v_mfma_f32_16x16x32_bf16 v[20:23], v[170:173], v[206:209], 0
	v_mfma_f32_16x16x32_bf16 v[16:19], v[182:185], v[206:209], 0
	v_mfma_f32_16x16x32_bf16 v[4:7], v[170:173], v[214:217], 0
	v_mfma_f32_16x16x32_bf16 v[0:3], v[182:185], v[214:217], 0
	v_mfma_f32_16x16x32_bf16 v[52:55], v[178:181], v[194:197], v[52:55]
	v_mfma_f32_16x16x32_bf16 v[48:51], v[186:189], v[194:197], v[48:51]
	v_mfma_f32_16x16x32_bf16 v[36:39], v[178:181], v[202:205], v[36:39]
	v_mfma_f32_16x16x32_bf16 v[32:35], v[186:189], v[202:205], v[32:35]
	v_mfma_f32_16x16x32_bf16 v[20:23], v[178:181], v[210:213], v[20:23]
	v_mfma_f32_16x16x32_bf16 v[16:19], v[186:189], v[210:213], v[16:19]
	v_mfma_f32_16x16x32_bf16 v[4:7], v[178:181], v[218:221], v[4:7]
	v_mfma_f32_16x16x32_bf16 v[0:3], v[186:189], v[218:221], v[0:3]
	s_setprio 0
	s_barrier
	s_add_i32 s90, 0, 0x18000
	v_add_u32_e32 v157, s90, v152
	s_add_i32 s91, 0, 0x1c000
	ds_read_b128 v[144:147], v157
	ds_read_b128 v[158:161], v157 offset:1024
	ds_read_b128 v[162:165], v157 offset:2048
	ds_read_b128 v[166:169], v157 offset:3072
	v_add_u32_e32 v157, s91, v152
	ds_read_b128 v[170:173], v157
	ds_read_b128 v[178:181], v157 offset:1024
	ds_read_b128 v[182:185], v157 offset:2048
	ds_read_b128 v[186:189], v157 offset:3072
	s_add_u32 s78, s78, 0x40000
	s_addc_u32 s79, s79, 0
	s_mov_b32 m0, s33
	v_lshl_add_u64 v[228:229], s[78:79], 0, v[128:129]
	ds_read_b128 v[190:193], v155 offset:32768
	ds_read_b128 v[194:197], v155 offset:33792
	ds_read_b128 v[198:201], v155 offset:34816
	ds_read_b128 v[202:205], v155 offset:35840
	ds_read_b128 v[206:209], v155 offset:36864
	ds_read_b128 v[210:213], v155 offset:37888
	ds_read_b128 v[214:217], v155 offset:38912
	ds_read_b128 v[218:221], v155 offset:39936
	global_load_lds_dwordx4 v[228:229], off
	v_lshl_add_u64 v[228:229], s[78:79], 0, v[132:133]
	s_mov_b32 m0, s35
	s_nop 0
	global_load_lds_dwordx4 v[228:229], off
	s_waitcnt vmcnt(8)
	s_waitcnt lgkmcnt(0)
	s_barrier
	s_setprio 1
	s_waitcnt lgkmcnt(0)
	v_mfma_f32_16x16x32_bf16 v[124:127], v[144:147], v[190:193], v[124:127]
	v_mfma_f32_16x16x32_bf16 v[120:123], v[162:165], v[190:193], v[120:123]
	v_mfma_f32_16x16x32_bf16 v[108:111], v[144:147], v[198:201], v[108:111]
	v_mfma_f32_16x16x32_bf16 v[104:107], v[162:165], v[198:201], v[104:107]
	v_mfma_f32_16x16x32_bf16 v[92:95], v[144:147], v[206:209], v[92:95]
	v_mfma_f32_16x16x32_bf16 v[88:91], v[162:165], v[206:209], v[88:91]
	v_mfma_f32_16x16x32_bf16 v[76:79], v[144:147], v[214:217], v[76:79]
	v_mfma_f32_16x16x32_bf16 v[72:75], v[162:165], v[214:217], v[72:75]
	v_mfma_f32_16x16x32_bf16 v[124:127], v[158:161], v[194:197], v[124:127]
	v_mfma_f32_16x16x32_bf16 v[120:123], v[166:169], v[194:197], v[120:123]
	v_mfma_f32_16x16x32_bf16 v[108:111], v[158:161], v[202:205], v[108:111]
	v_mfma_f32_16x16x32_bf16 v[104:107], v[166:169], v[202:205], v[104:107]
	v_mfma_f32_16x16x32_bf16 v[92:95], v[158:161], v[210:213], v[92:95]
	v_mfma_f32_16x16x32_bf16 v[88:91], v[166:169], v[210:213], v[88:91]
	v_mfma_f32_16x16x32_bf16 v[76:79], v[158:161], v[218:221], v[76:79]
	v_mfma_f32_16x16x32_bf16 v[72:75], v[166:169], v[218:221], v[72:75]
	s_setprio 0
	s_setprio 1
	v_mfma_f32_16x16x32_bf16 v[116:119], v[170:173], v[190:193], v[116:119]
	v_mfma_f32_16x16x32_bf16 v[112:115], v[182:185], v[190:193], v[112:115]
	v_mfma_f32_16x16x32_bf16 v[100:103], v[170:173], v[198:201], v[100:103]
	v_mfma_f32_16x16x32_bf16 v[96:99], v[182:185], v[198:201], v[96:99]
	v_mfma_f32_16x16x32_bf16 v[84:87], v[170:173], v[206:209], v[84:87]
	v_mfma_f32_16x16x32_bf16 v[80:83], v[182:185], v[206:209], v[80:83]
	v_mfma_f32_16x16x32_bf16 v[68:71], v[170:173], v[214:217], v[68:71]
	v_mfma_f32_16x16x32_bf16 v[64:67], v[182:185], v[214:217], v[64:67]
	v_mfma_f32_16x16x32_bf16 v[116:119], v[178:181], v[194:197], v[116:119]
	v_mfma_f32_16x16x32_bf16 v[112:115], v[186:189], v[194:197], v[112:115]
	v_mfma_f32_16x16x32_bf16 v[100:103], v[178:181], v[202:205], v[100:103]
	v_mfma_f32_16x16x32_bf16 v[96:99], v[186:189], v[202:205], v[96:99]
	v_mfma_f32_16x16x32_bf16 v[84:87], v[178:181], v[210:213], v[84:87]
	v_mfma_f32_16x16x32_bf16 v[80:83], v[186:189], v[210:213], v[80:83]
	v_mfma_f32_16x16x32_bf16 v[68:71], v[178:181], v[218:221], v[68:71]
	v_mfma_f32_16x16x32_bf16 v[64:67], v[186:189], v[218:221], v[64:67]
	s_setprio 0
	s_barrier
; #define PG8_STAGE(bufoff, gbase, voff) do { _Pragma("unroll") for (int _i = 0; _i < 2; ++_i) \
;         __builtin_amdgcn_global_load_lds((const unsigned*)((const char*)(gbase) + (voff)[_i]), (LAS unsigned*)(lds + (bufoff) + ldsw + _i * 8192), 16, 0, 0); } while (0)
; #define PG8_LDA(dst, b, h) do { _Pragma("unroll") for (int m = 0; m < 4; ++m) _Pragma("unroll") for (int k = 0; k < 2; ++k) dst[m][k] = *(const LAS bf16x8*)(lds + PG8_SA(b, h) + aoff + m * 2048 + k * 1024); } while (0)
; #define PG8_LDB(dst, b, h) do { _Pragma("unroll") for (int n = 0; n < 2; ++n) _Pragma("unroll") for (int k = 0; k < 2; ++k) dst[n][k] = *(const LAS bf16x8*)(lds + PG8_SB(b, h) + boff + n * 2048 + k * 1024); } while (0)
; #define PG8_WAIT_V(n) asm volatile("s_waitcnt vmcnt(" #n ")" ::: "memory")
; #define PG8_WAIT_L(n) asm volatile("s_waitcnt lgkmcnt(" #n ")" ::: "memory")
; template <class Epi>
; __device__ __forceinline__ void gemm_phase(LAS unsigned char* lds, const Gemm g, const StaticOrder& S, const Epi& E) {
;     ...
;         for (int t = 0; t < nt; t += 2) {
;             const bool last = (t == nt - 2);
;             const char* a1 = cA + (size_t)(t + 1) * kstep;
;             const char* a2 = last ? nA : cA + (size_t)(t + 2) * kstep; const char* b2 = last ? nB : cB + (size_t)(t + 2) * kstep;
;             const char* a3 = a2 + kstep; const char* b3 = b2 + kstep;
;             PG8_LDB(B0, 0, 0); PG8_LDB(B1, 0, 1); PG8_SCHED; PG8_LDA(At, 0, 0); PG8_STAGE(PG8_SA(1, 1), a1 + hstepA, voffA);
;             PG8_WAIT_V(8); PG8_WAIT_L(0); PG8_BAR; PG8_MMA(0, 0, At, B0); PG8_MMA(0, 1, At, B1); PG8_BAR; PG8_SCHED;
;             PG8_LDA(At, 0, 1); PG8_STAGE(PG8_SB(0, 0), b2, voffB); PG8_STAGE(PG8_SB(0, 1), b2 + hstepB, voffB); PG8_STAGE(PG8_SA(0, 0), a2, voffA);
;             PG8_WAIT_V(8); PG8_WAIT_L(0); PG8_BAR; PG8_MMA(1, 0, At, B0); PG8_MMA(1, 1, At, B1); PG8_BAR; PG8_SCHED;
;             PG8_LDB(B0, 1, 0); PG8_LDB(B1, 1, 1); PG8_SCHED; PG8_LDA(At, 1, 0); PG8_STAGE(PG8_SA(0, 1), a2 + hstepA, voffA);
;             PG8_WAIT_V(8); PG8_WAIT_L(0); PG8_BAR; PG8_MMA(0, 0, At, B0); PG8_MMA(0, 1, At, B1); PG8_BAR; PG8_SCHED;
;             PG8_LDA(At, 1, 1); PG8_STAGE(PG8_SB(1, 0), b3, voffB); PG8_STAGE(PG8_SB(1, 1), b3 + hstepB, voffB); PG8_STAGE(PG8_SA(1, 0), a3, voffA);
;             PG8_WAIT_V(8); PG8_WAIT_L(0); PG8_BAR; PG8_MMA(1, 0, At, B0); PG8_MMA(1, 1, At, B1); PG8_BAR; PG8_SCHED;
	s_add_i32 s78, s90, s3
	v_lshl_add_u64 v[148:149], v[148:149], 0, s[12:13]
	s_mov_b32 m0, s78
	ds_read_b128 v[190:193], v155 offset:49152
	ds_read_b128 v[194:197], v155 offset:50176
	ds_read_b128 v[198:201], v155 offset:51200
	ds_read_b128 v[202:205], v155 offset:52224
	ds_read_b128 v[206:209], v155 offset:53248
	ds_read_b128 v[210:213], v155 offset:54272
	ds_read_b128 v[214:217], v155 offset:55296
	ds_read_b128 v[218:221], v155 offset:56320
	global_load_lds_dwordx4 v[148:149], off
	s_add_i32 m0, s78, 0x2000
	s_add_u32 s76, s76, 0x40080
	v_lshl_add_u64 v[148:149], v[174:175], 0, s[12:13]
	s_addc_u32 s77, s77, 0
	s_add_i32 s78, s91, s3
	global_load_lds_dwordx4 v[148:149], off
	v_lshl_add_u64 v[148:149], s[76:77], 0, v[130:131]
	s_mov_b32 m0, s78
	s_nop 0
	global_load_lds_dwordx4 v[148:149], off
	v_lshl_add_u64 v[148:149], s[76:77], 0, v[134:135]
	s_add_i32 m0, s78, 0x2000
	s_nop 0
	global_load_lds_dwordx4 v[148:149], off
	v_lshl_add_u64 v[148:149], v[222:223], 0, s[12:13]
	s_mov_b32 m0, s57
	s_nop 0
	global_load_lds_dwordx4 v[148:149], off
	v_lshl_add_u64 v[148:149], v[226:227], 0, s[12:13]
	s_mov_b32 m0, s80
	s_nop 0
	global_load_lds_dwordx4 v[148:149], off
	s_waitcnt vmcnt(8)
	s_waitcnt lgkmcnt(0)
	s_barrier
	s_setprio 1
	s_waitcnt lgkmcnt(0)
	v_mfma_f32_16x16x32_bf16 v[60:63], v[144:147], v[190:193], v[60:63]
	v_mfma_f32_16x16x32_bf16 v[56:59], v[162:165], v[190:193], v[56:59]
	v_mfma_f32_16x16x32_bf16 v[44:47], v[144:147], v[198:201], v[44:47]
	v_mfma_f32_16x16x32_bf16 v[40:43], v[162:165], v[198:201], v[40:43]
	v_mfma_f32_16x16x32_bf16 v[28:31], v[144:147], v[206:209], v[28:31]
	v_mfma_f32_16x16x32_bf16 v[24:27], v[162:165], v[206:209], v[24:27]
	v_mfma_f32_16x16x32_bf16 v[12:15], v[144:147], v[214:217], v[12:15]
	v_mfma_f32_16x16x32_bf16 v[8:11], v[162:165], v[214:217], v[8:11]
	v_mfma_f32_16x16x32_bf16 v[60:63], v[158:161], v[194:197], v[60:63]
	v_mfma_f32_16x16x32_bf16 v[56:59], v[166:169], v[194:197], v[56:59]
	v_mfma_f32_16x16x32_bf16 v[44:47], v[158:161], v[202:205], v[44:47]
	v_mfma_f32_16x16x32_bf16 v[40:43], v[166:169], v[202:205], v[40:43]
	v_mfma_f32_16x16x32_bf16 v[28:31], v[158:161], v[210:213], v[28:31]
	v_mfma_f32_16x16x32_bf16 v[24:27], v[166:169], v[210:213], v[24:27]
	v_mfma_f32_16x16x32_bf16 v[12:15], v[158:161], v[218:221], v[12:15]
	v_mfma_f32_16x16x32_bf16 v[8:11], v[166:169], v[218:221], v[8:11]
	s_setprio 0
	s_setprio 1
	v_mfma_f32_16x16x32_bf16 v[52:55], v[170:173], v[190:193], v[52:55]
	v_mfma_f32_16x16x32_bf16 v[48:51], v[182:185], v[190:193], v[48:51]
	v_mfma_f32_16x16x32_bf16 v[36:39], v[170:173], v[198:201], v[36:39]
	v_mfma_f32_16x16x32_bf16 v[32:35], v[182:185], v[198:201], v[32:35]
	v_mfma_f32_16x16x32_bf16 v[20:23], v[170:173], v[206:209], v[20:23]
	v_mfma_f32_16x16x32_bf16 v[16:19], v[182:185], v[206:209], v[16:19]
	v_mfma_f32_16x16x32_bf16 v[4:7], v[170:173], v[214:217], v[4:7]
	v_mfma_f32_16x16x32_bf16 v[0:3], v[182:185], v[214:217], v[0:3]
	v_mfma_f32_16x16x32_bf16 v[52:55], v[178:181], v[194:197], v[52:55]
	v_mfma_f32_16x16x32_bf16 v[48:51], v[186:189], v[194:197], v[48:51]
	v_mfma_f32_16x16x32_bf16 v[36:39], v[178:181], v[202:205], v[36:39]
	v_mfma_f32_16x16x32_bf16 v[32:35], v[186:189], v[202:205], v[32:35]
	v_mfma_f32_16x16x32_bf16 v[20:23], v[178:181], v[210:213], v[20:23]
	v_mfma_f32_16x16x32_bf16 v[16:19], v[186:189], v[210:213], v[16:19]
	v_mfma_f32_16x16x32_bf16 v[4:7], v[178:181], v[218:221], v[4:7]
	v_mfma_f32_16x16x32_bf16 v[0:3], v[186:189], v[218:221], v[0:3]
	s_setprio 0
	s_barrier
	s_add_i32 s89, s89, 2
	s_add_u32 s74, s74, 0x100
	s_addc_u32 s75, s75, 0
	s_add_u32 s87, s87, 0x100
	s_addc_u32 s88, s88, 0
	s_cmp_gt_u32 s89, 13

; #define PG8_STAGE(bufoff, gbase, voff) do { _Pragma("unroll") for (int _i = 0; _i < 2; ++_i) \
;         __builtin_amdgcn_global_load_lds((const unsigned*)((const char*)(gbase) + (voff)[_i]), (LAS unsigned*)(lds + (bufoff) + ldsw + _i * 8192), 16, 0, 0); } while (0)
; #define PG8_LDA(dst, b, h) do { _Pragma("unroll") for (int m = 0; m < 4; ++m) _Pragma("unroll") for (int k = 0; k < 2; ++k) dst[m][k] = *(const LAS bf16x8*)(lds + PG8_SA(b, h) + aoff + m * 2048 + k * 1024); } while (0)
; #define PG8_LDB(dst, b, h) do { _Pragma("unroll") for (int n = 0; n < 2; ++n) _Pragma("unroll") for (int k = 0; k < 2; ++k) dst[n][k] = *(const LAS bf16x8*)(lds + PG8_SB(b, h) + boff + n * 2048 + k * 1024); } while (0)
; #define PG8_WAIT_V(n) asm volatile("s_waitcnt vmcnt(" #n ")" ::: "memory")
; template <class Epi>
; __device__ __forceinline__ void gemm_phase(LAS unsigned char* lds, const Gemm g, const StaticOrder& S, const Epi& E) {
;     ...
;         const bool has_next = S.next(ui + 1, nxt);
;         const char* nA = has_next ? (const char*)g.A + (size_t)nxt.pm * tstepA : cA; const char* nB = has_next ? (const char*)g.Bt + (size_t)nxt.pn * tstepB : cB;
; #pragma nounroll
;         for (int t = 0; t < nt; t += 2) {
;             const bool last = (t == nt - 2);
;             const char* a1 = cA + (size_t)(t + 1) * kstep;
;             const char* a2 = last ? nA : cA + (size_t)(t + 2) * kstep; const char* b2 = last ? nB : cB + (size_t)(t + 2) * kstep;
;             const char* a3 = a2 + kstep; const char* b3 = b2 + kstep;
;             PG8_LDB(B0, 0, 0); PG8_LDB(B1, 0, 1); PG8_SCHED; PG8_LDA(At, 0, 0); PG8_STAGE(PG8_SA(1, 1), a1 + hstepA, voffA);
;             PG8_WAIT_V(8); PG8_WAIT_L(0); PG8_BAR; PG8_MMA(0, 0, At, B0); PG8_MMA(0, 1, At, B1); PG8_BAR; PG8_SCHED;
;             PG8_LDA(At, 0, 1); PG8_STAGE(PG8_SB(0, 0), b2, voffB); PG8_STAGE(PG8_SB(0, 1), b2 + hstepB, voffB); PG8_STAGE(PG8_SA(0, 0), a2, voffA);
;             PG8_WAIT_V(8); PG8_WAIT_L(0); PG8_BAR; PG8_MMA(1, 0, At, B0); PG8_MMA(1, 1, At, B1); PG8_BAR; PG8_SCHED;
;     ...
; #pragma unroll
;         for (int a = 0; a < 2; ++a)
; #pragma unroll
;             for (int b = 0; b < 2; ++b)
; #pragma unroll
;                 for (int m = 0; m < 4; ++m)
; #pragma unroll
;                     for (int n = 0; n < 2; ++n) acc[a][b][m][n] = (f32x4){0.f, 0.f, 0.f, 0.f};
;         cur = nxt; cA = nA; cB = nB; ++ui;
.LBB0_456:
	s_ashr_i32 s23, s22, 31
	s_lshl_b64 s[28:29], s[22:23], 19
	s_add_u32 s28, s40, s28
	s_addc_u32 s29, s41, s29
	s_and_b64 s[30:31], s[4:5], exec
	s_cselect_b32 s1, s29, s39
	s_cselect_b32 s23, s28, s38
	s_ashr_i32 s19, s18, 31
	s_lshl_b64 s[30:31], s[18:19], 19
	s_add_u32 s30, s3, s30
	s_addc_u32 s31, s33, s31
	s_and_b64 s[52:53], s[4:5], exec
	s_cselect_b32 s19, s31, s43
	s_cselect_b32 s74, s30, s42
	s_add_u32 s38, s38, 0x40080
	s_addc_u32 s39, s39, 0
	s_add_u32 s75, s42, 0x100
	s_addc_u32 s76, s43, 0
	s_mov_b32 s77, -2
	s_waitcnt lgkmcnt(0)
	s_waitcnt vmcnt(0)
	ds_read_b128 v[128:131], v173
	ds_read_b128 v[132:135], v173 offset:1024
	ds_read_b128 v[136:139], v173 offset:2048
	ds_read_b128 v[140:143], v173 offset:3072
	ds_read_b128 v[160:163], v174
	ds_read_b128 v[164:167], v174 offset:1024
	ds_read_b128 v[178:181], v174 offset:2048
	ds_read_b128 v[182:185], v174 offset:3072
	s_add_u32 s42, s38, 0xfffc0080
	s_addc_u32 s43, s39, -1
	s_cmp_eq_u32 s77, 12
	s_cselect_b32 s53, s1, s43
	s_cselect_b32 s52, s23, s42
	s_cselect_b32 s43, s19, s76
	s_cselect_b32 s42, s74, s75
	v_lshl_add_u64 v[168:169], s[38:39], 0, v[152:153]
	s_add_i32 m0, s35, 0xc000
	ds_read_b128 v[186:189], v175
	ds_read_b128 v[190:193], v175 offset:1024
	ds_read_b128 v[194:197], v175 offset:2048
	ds_read_b128 v[198:201], v175 offset:3072
	ds_read_b128 v[202:205], v175 offset:4096
	ds_read_b128 v[206:209], v175 offset:5120
	ds_read_b128 v[210:213], v175 offset:6144
	ds_read_b128 v[214:217], v175 offset:7168
	global_load_lds_dwordx4 v[168:169], off
	v_lshl_add_u64 v[168:169], s[38:39], 0, v[154:155]
	s_add_i32 m0, s35, 0xe000
	s_nop 0
	global_load_lds_dwordx4 v[168:169], off
	s_waitcnt vmcnt(8)
	s_waitcnt lgkmcnt(0)
	s_barrier
	s_setprio 1
	s_waitcnt lgkmcnt(0)
	v_mfma_f32_16x16x32_bf16 v[124:127], v[128:131], v[186:189], 0
	v_mfma_f32_16x16x32_bf16 v[120:123], v[136:139], v[186:189], 0
	v_mfma_f32_16x16x32_bf16 v[108:111], v[128:131], v[194:197], 0
	v_mfma_f32_16x16x32_bf16 v[104:107], v[136:139], v[194:197], 0
	v_mfma_f32_16x16x32_bf16 v[92:95], v[128:131], v[202:205], 0
	v_mfma_f32_16x16x32_bf16 v[88:91], v[136:139], v[202:205], 0
	v_mfma_f32_16x16x32_bf16 v[76:79], v[128:131], v[210:213], 0
	v_mfma_f32_16x16x32_bf16 v[72:75], v[136:139], v[210:213], 0
	v_mfma_f32_16x16x32_bf16 v[124:127], v[132:135], v[190:193], v[124:127]
	v_mfma_f32_16x16x32_bf16 v[120:123], v[140:143], v[190:193], v[120:123]
	v_mfma_f32_16x16x32_bf16 v[108:111], v[132:135], v[198:201], v[108:111]
	v_mfma_f32_16x16x32_bf16 v[104:107], v[140:143], v[198:201], v[104:107]
	v_mfma_f32_16x16x32_bf16 v[92:95], v[132:135], v[206:209], v[92:95]
	v_mfma_f32_16x16x32_bf16 v[88:91], v[140:143], v[206:209], v[88:91]
	v_mfma_f32_16x16x32_bf16 v[76:79], v[132:135], v[214:217], v[76:79]
	v_mfma_f32_16x16x32_bf16 v[72:75], v[140:143], v[214:217], v[72:75]
	s_setprio 0
	s_setprio 1
	v_mfma_f32_16x16x32_bf16 v[116:119], v[160:163], v[186:189], 0
	v_mfma_f32_16x16x32_bf16 v[112:115], v[178:181], v[186:189], 0
	v_mfma_f32_16x16x32_bf16 v[100:103], v[160:163], v[194:197], 0
	v_mfma_f32_16x16x32_bf16 v[96:99], v[178:181], v[194:197], 0
	v_mfma_f32_16x16x32_bf16 v[84:87], v[160:163], v[202:205], 0
	v_mfma_f32_16x16x32_bf16 v[80:83], v[178:181], v[202:205], 0
	v_mfma_f32_16x16x32_bf16 v[68:71], v[160:163], v[210:213], 0
	v_mfma_f32_16x16x32_bf16 v[64:67], v[178:181], v[210:213], 0
	v_mfma_f32_16x16x32_bf16 v[116:119], v[164:167], v[190:193], v[116:119]
	v_mfma_f32_16x16x32_bf16 v[112:115], v[182:185], v[190:193], v[112:115]
	v_mfma_f32_16x16x32_bf16 v[100:103], v[164:167], v[198:201], v[100:103]
	v_mfma_f32_16x16x32_bf16 v[96:99], v[182:185], v[198:201], v[96:99]
	v_mfma_f32_16x16x32_bf16 v[84:87], v[164:167], v[206:209], v[84:87]
	v_mfma_f32_16x16x32_bf16 v[80:83], v[182:185], v[206:209], v[80:83]
	v_mfma_f32_16x16x32_bf16 v[68:71], v[164:167], v[214:217], v[68:71]
	v_mfma_f32_16x16x32_bf16 v[64:67], v[182:185], v[214:217], v[64:67]
	s_setprio 0
	s_barrier
	s_add_i32 s78, s72, s54
	v_lshl_add_u64 v[168:169], s[42:43], 0, v[146:147]
	s_mov_b32 m0, s78
	ds_read_b128 v[186:189], v175 offset:16384
	ds_read_b128 v[190:193], v175 offset:17408
	ds_read_b128 v[194:197], v175 offset:18432
	ds_read_b128 v[198:201], v175 offset:19456
	ds_read_b128 v[202:205], v175 offset:20480
	ds_read_b128 v[206:209], v175 offset:21504
	ds_read_b128 v[210:213], v175 offset:22528
	ds_read_b128 v[214:217], v175 offset:23552
	global_load_lds_dwordx4 v[168:169], off
	s_add_i32 m0, s78, 0x2000
	s_add_u32 s78, s42, 0x40000
	v_lshl_add_u64 v[218:219], s[42:43], 0, v[150:151]
	s_addc_u32 s79, s43, 0
	s_add_i32 s80, s73, s54
	global_load_lds_dwordx4 v[218:219], off
	v_lshl_add_u64 v[220:221], s[78:79], 0, v[146:147]
	s_mov_b32 m0, s80
	v_lshl_add_u64 v[222:223], s[52:53], 0, v[148:149]
	global_load_lds_dwordx4 v[220:221], off
	v_lshl_add_u64 v[220:221], s[78:79], 0, v[150:151]
	s_add_i32 m0, s80, 0x2000
	s_nop 0
	global_load_lds_dwordx4 v[220:221], off
	v_lshl_add_u64 v[220:221], s[52:53], 0, v[144:145]
	s_mov_b32 m0, s35
	s_nop 0
	global_load_lds_dwordx4 v[220:221], off
	s_mov_b32 m0, s55
	s_nop 0
	global_load_lds_dwordx4 v[222:223], off
	s_waitcnt vmcnt(8)
	s_waitcnt lgkmcnt(0)
	s_barrier
; #define PG8_STAGE(bufoff, gbase, voff) do { _Pragma("unroll") for (int _i = 0; _i < 2; ++_i) \
;         __builtin_amdgcn_global_load_lds((const unsigned*)((const char*)(gbase) + (voff)[_i]), (LAS unsigned*)(lds + (bufoff) + ldsw + _i * 8192), 16, 0, 0); } while (0)
; #define PG8_LDA(dst, b, h) do { _Pragma("unroll") for (int m = 0; m < 4; ++m) _Pragma("unroll") for (int k = 0; k < 2; ++k) dst[m][k] = *(const LAS bf16x8*)(lds + PG8_SA(b, h) + aoff + m * 2048 + k * 1024); } while (0)
; #define PG8_LDB(dst, b, h) do { _Pragma("unroll") for (int n = 0; n < 2; ++n) _Pragma("unroll") for (int k = 0; k < 2; ++k) dst[n][k] = *(const LAS bf16x8*)(lds + PG8_SB(b, h) + boff + n * 2048 + k * 1024); } while (0)
; #define PG8_MMA(ai, bj, At, Bt) do { __builtin_amdgcn_s_setprio(1); _Pragma("unroll") for (int m = 0; m < 4; ++m) _Pragma("unroll") for (int n = 0; n < 2; ++n) _Pragma("unroll") for (int k = 0; k < 2; ++k) \
;         acc[ai][bj][m][n] = __builtin_amdgcn_mfma_f32_16x16x32_bf16(Bt[n][k], At[m][k], acc[ai][bj][m][n], 0, 0, 0); __builtin_amdgcn_s_setprio(0); } while (0)
; #define PG8_WAIT_V(n) asm volatile("s_waitcnt vmcnt(" #n ")" ::: "memory")
; #define PG8_WAIT_L(n) asm volatile("s_waitcnt lgkmcnt(" #n ")" ::: "memory")
; #define PG8_BAR __builtin_amdgcn_s_barrier()
; #define PG8_SCHED __builtin_amdgcn_sched_barrier(0)
; template <class Epi>
; __device__ __forceinline__ void gemm_phase(LAS unsigned char* lds, const Gemm g, const StaticOrder& S, const Epi& E) {
;     ...
;             PG8_WAIT_V(8); PG8_WAIT_L(0); PG8_BAR; PG8_MMA(1, 0, At, B0); PG8_MMA(1, 1, At, B1); PG8_BAR; PG8_SCHED;
;             PG8_LDB(B0, 1, 0); PG8_LDB(B1, 1, 1); PG8_SCHED; PG8_LDA(At, 1, 0); PG8_STAGE(PG8_SA(0, 1), a2 + hstepA, voffA);
;             PG8_WAIT_V(8); PG8_WAIT_L(0); PG8_BAR; PG8_MMA(0, 0, At, B0); PG8_MMA(0, 1, At, B1); PG8_BAR; PG8_SCHED;
;             PG8_LDA(At, 1, 1); PG8_STAGE(PG8_SB(1, 0), b3, voffB); PG8_STAGE(PG8_SB(1, 1), b3 + hstepB, voffB); PG8_STAGE(PG8_SA(1, 0), a3, voffA);
;             PG8_WAIT_V(8); PG8_WAIT_L(0); PG8_BAR; PG8_MMA(1, 0, At, B0); PG8_MMA(1, 1, At, B1); PG8_BAR; PG8_SCHED;
	s_setprio 1
	s_waitcnt lgkmcnt(0)
	v_mfma_f32_16x16x32_bf16 v[60:63], v[128:131], v[186:189], 0
	v_mfma_f32_16x16x32_bf16 v[56:59], v[136:139], v[186:189], 0
	v_mfma_f32_16x16x32_bf16 v[44:47], v[128:131], v[194:197], 0
	v_mfma_f32_16x16x32_bf16 v[40:43], v[136:139], v[194:197], 0
	v_mfma_f32_16x16x32_bf16 v[28:31], v[128:131], v[202:205], 0
	v_mfma_f32_16x16x32_bf16 v[24:27], v[136:139], v[202:205], 0
	v_mfma_f32_16x16x32_bf16 v[12:15], v[128:131], v[210:213], 0
	v_mfma_f32_16x16x32_bf16 v[8:11], v[136:139], v[210:213], 0
	v_mfma_f32_16x16x32_bf16 v[60:63], v[132:135], v[190:193], v[60:63]
	v_mfma_f32_16x16x32_bf16 v[56:59], v[140:143], v[190:193], v[56:59]
	v_mfma_f32_16x16x32_bf16 v[44:47], v[132:135], v[198:201], v[44:47]
	v_mfma_f32_16x16x32_bf16 v[40:43], v[140:143], v[198:201], v[40:43]
	v_mfma_f32_16x16x32_bf16 v[28:31], v[132:135], v[206:209], v[28:31]
	v_mfma_f32_16x16x32_bf16 v[24:27], v[140:143], v[206:209], v[24:27]
	v_mfma_f32_16x16x32_bf16 v[12:15], v[132:135], v[214:217], v[12:15]
	v_mfma_f32_16x16x32_bf16 v[8:11], v[140:143], v[214:217], v[8:11]
	s_setprio 0
	s_setprio 1
	v_mfma_f32_16x16x32_bf16 v[52:55], v[160:163], v[186:189], 0
	v_mfma_f32_16x16x32_bf16 v[48:51], v[178:181], v[186:189], 0
	v_mfma_f32_16x16x32_bf16 v[36:39], v[160:163], v[194:197], 0
	v_mfma_f32_16x16x32_bf16 v[32:35], v[178:181], v[194:197], 0
	v_mfma_f32_16x16x32_bf16 v[20:23], v[160:163], v[202:205], 0
	v_mfma_f32_16x16x32_bf16 v[16:19], v[178:181], v[202:205], 0
	v_mfma_f32_16x16x32_bf16 v[4:7], v[160:163], v[210:213], 0
	v_mfma_f32_16x16x32_bf16 v[0:3], v[178:181], v[210:213], 0
	v_mfma_f32_16x16x32_bf16 v[52:55], v[164:167], v[190:193], v[52:55]
	v_mfma_f32_16x16x32_bf16 v[48:51], v[182:185], v[190:193], v[48:51]
	v_mfma_f32_16x16x32_bf16 v[36:39], v[164:167], v[198:201], v[36:39]
	v_mfma_f32_16x16x32_bf16 v[32:35], v[182:185], v[198:201], v[32:35]
	v_mfma_f32_16x16x32_bf16 v[20:23], v[164:167], v[206:209], v[20:23]
	v_mfma_f32_16x16x32_bf16 v[16:19], v[182:185], v[206:209], v[16:19]
	v_mfma_f32_16x16x32_bf16 v[4:7], v[164:167], v[214:217], v[4:7]
	v_mfma_f32_16x16x32_bf16 v[0:3], v[182:185], v[214:217], v[0:3]
	s_setprio 0
	s_barrier
	s_add_i32 s78, 0, 0x18000
	s_add_i32 s79, 0, 0x1c000
	v_add_u32_e32 v140, s78, v172
	v_add_u32_e32 v182, s79, v172
	ds_read_b128 v[128:131], v140
	ds_read_b128 v[132:135], v140 offset:1024
	ds_read_b128 v[136:139], v140 offset:2048
	ds_read_b128 v[140:143], v140 offset:3072
	ds_read_b128 v[160:163], v182
	ds_read_b128 v[164:167], v182 offset:1024
	ds_read_b128 v[178:181], v182 offset:2048
	ds_read_b128 v[182:185], v182 offset:3072
	s_add_u32 s52, s52, 0x40000
	s_addc_u32 s53, s53, 0
	s_mov_b32 m0, s56
	v_lshl_add_u64 v[226:227], s[52:53], 0, v[144:145]
	ds_read_b128 v[186:189], v175 offset:32768
	ds_read_b128 v[190:193], v175 offset:33792
	ds_read_b128 v[194:197], v175 offset:34816
	ds_read_b128 v[198:201], v175 offset:35840
	ds_read_b128 v[202:205], v175 offset:36864
	ds_read_b128 v[206:209], v175 offset:37888
	ds_read_b128 v[210:213], v175 offset:38912
	ds_read_b128 v[214:217], v175 offset:39936
	global_load_lds_dwordx4 v[226:227], off
	v_lshl_add_u64 v[226:227], s[52:53], 0, v[148:149]
	s_mov_b32 m0, s57
	s_nop 0
	global_load_lds_dwordx4 v[226:227], off
	s_waitcnt vmcnt(8)
	s_waitcnt lgkmcnt(0)
	s_barrier
	s_setprio 1
	s_waitcnt lgkmcnt(0)
	v_mfma_f32_16x16x32_bf16 v[124:127], v[128:131], v[186:189], v[124:127]
	v_mfma_f32_16x16x32_bf16 v[120:123], v[136:139], v[186:189], v[120:123]
	v_mfma_f32_16x16x32_bf16 v[108:111], v[128:131], v[194:197], v[108:111]
	v_mfma_f32_16x16x32_bf16 v[104:107], v[136:139], v[194:197], v[104:107]
	v_mfma_f32_16x16x32_bf16 v[92:95], v[128:131], v[202:205], v[92:95]
	v_mfma_f32_16x16x32_bf16 v[88:91], v[136:139], v[202:205], v[88:91]
	v_mfma_f32_16x16x32_bf16 v[76:79], v[128:131], v[210:213], v[76:79]
	v_mfma_f32_16x16x32_bf16 v[72:75], v[136:139], v[210:213], v[72:75]
	v_mfma_f32_16x16x32_bf16 v[124:127], v[132:135], v[190:193], v[124:127]
	v_mfma_f32_16x16x32_bf16 v[120:123], v[140:143], v[190:193], v[120:123]
	v_mfma_f32_16x16x32_bf16 v[108:111], v[132:135], v[198:201], v[108:111]
	v_mfma_f32_16x16x32_bf16 v[104:107], v[140:143], v[198:201], v[104:107]
	v_mfma_f32_16x16x32_bf16 v[92:95], v[132:135], v[206:209], v[92:95]
	v_mfma_f32_16x16x32_bf16 v[88:91], v[140:143], v[206:209], v[88:91]
	v_mfma_f32_16x16x32_bf16 v[76:79], v[132:135], v[214:217], v[76:79]
	v_mfma_f32_16x16x32_bf16 v[72:75], v[140:143], v[214:217], v[72:75]
	s_setprio 0
	s_setprio 1
	v_mfma_f32_16x16x32_bf16 v[116:119], v[160:163], v[186:189], v[116:119]
	v_mfma_f32_16x16x32_bf16 v[112:115], v[178:181], v[186:189], v[112:115]
	v_mfma_f32_16x16x32_bf16 v[100:103], v[160:163], v[194:197], v[100:103]
	v_mfma_f32_16x16x32_bf16 v[96:99], v[178:181], v[194:197], v[96:99]
	v_mfma_f32_16x16x32_bf16 v[84:87], v[160:163], v[202:205], v[84:87]
	v_mfma_f32_16x16x32_bf16 v[80:83], v[178:181], v[202:205], v[80:83]
	v_mfma_f32_16x16x32_bf16 v[68:71], v[160:163], v[210:213], v[68:71]
	v_mfma_f32_16x16x32_bf16 v[64:67], v[178:181], v[210:213], v[64:67]
	v_mfma_f32_16x16x32_bf16 v[116:119], v[164:167], v[190:193], v[116:119]
	v_mfma_f32_16x16x32_bf16 v[112:115], v[182:185], v[190:193], v[112:115]
	v_mfma_f32_16x16x32_bf16 v[100:103], v[164:167], v[198:201], v[100:103]
	v_mfma_f32_16x16x32_bf16 v[96:99], v[182:185], v[198:201], v[96:99]
	v_mfma_f32_16x16x32_bf16 v[84:87], v[164:167], v[206:209], v[84:87]
	v_mfma_f32_16x16x32_bf16 v[80:83], v[182:185], v[206:209], v[80:83]
	v_mfma_f32_16x16x32_bf16 v[68:71], v[164:167], v[214:217], v[68:71]
	v_mfma_f32_16x16x32_bf16 v[64:67], v[182:185], v[214:217], v[64:67]
	s_setprio 0
	s_barrier
; #define PG8_STAGE(bufoff, gbase, voff) do { _Pragma("unroll") for (int _i = 0; _i < 2; ++_i) \
;         __builtin_amdgcn_global_load_lds((const unsigned*)((const char*)(gbase) + (voff)[_i]), (LAS unsigned*)(lds + (bufoff) + ldsw + _i * 8192), 16, 0, 0); } while (0)
; #define PG8_LDA(dst, b, h) do { _Pragma("unroll") for (int m = 0; m < 4; ++m) _Pragma("unroll") for (int k = 0; k < 2; ++k) dst[m][k] = *(const LAS bf16x8*)(lds + PG8_SA(b, h) + aoff + m * 2048 + k * 1024); } while (0)
; #define PG8_LDB(dst, b, h) do { _Pragma("unroll") for (int n = 0; n < 2; ++n) _Pragma("unroll") for (int k = 0; k < 2; ++k) dst[n][k] = *(const LAS bf16x8*)(lds + PG8_SB(b, h) + boff + n * 2048 + k * 1024); } while (0)
; #define PG8_WAIT_V(n) asm volatile("s_waitcnt vmcnt(" #n ")" ::: "memory")
; #define PG8_WAIT_L(n) asm volatile("s_waitcnt lgkmcnt(" #n ")" ::: "memory")
; template <class Epi>
; __device__ __forceinline__ void gemm_phase(LAS unsigned char* lds, const Gemm g, const StaticOrder& S, const Epi& E) {
;     ...
;         for (int t = 0; t < nt; t += 2) {
;             const bool last = (t == nt - 2);
;             const char* a1 = cA + (size_t)(t + 1) * kstep;
;             const char* a2 = last ? nA : cA + (size_t)(t + 2) * kstep; const char* b2 = last ? nB : cB + (size_t)(t + 2) * kstep;
;             const char* a3 = a2 + kstep; const char* b3 = b2 + kstep;
;             PG8_LDB(B0, 0, 0); PG8_LDB(B1, 0, 1); PG8_SCHED; PG8_LDA(At, 0, 0); PG8_STAGE(PG8_SA(1, 1), a1 + hstepA, voffA);
;             PG8_WAIT_V(8); PG8_WAIT_L(0); PG8_BAR; PG8_MMA(0, 0, At, B0); PG8_MMA(0, 1, At, B1); PG8_BAR; PG8_SCHED;
;             PG8_LDA(At, 0, 1); PG8_STAGE(PG8_SB(0, 0), b2, voffB); PG8_STAGE(PG8_SB(0, 1), b2 + hstepB, voffB); PG8_STAGE(PG8_SA(0, 0), a2, voffA);
;             PG8_WAIT_V(8); PG8_WAIT_L(0); PG8_BAR; PG8_MMA(1, 0, At, B0); PG8_MMA(1, 1, At, B1); PG8_BAR; PG8_SCHED;
;             PG8_LDB(B0, 1, 0); PG8_LDB(B1, 1, 1); PG8_SCHED; PG8_LDA(At, 1, 0); PG8_STAGE(PG8_SA(0, 1), a2 + hstepA, voffA);
;             PG8_WAIT_V(8); PG8_WAIT_L(0); PG8_BAR; PG8_MMA(0, 0, At, B0); PG8_MMA(0, 1, At, B1); PG8_BAR; PG8_SCHED;
;             PG8_LDA(At, 1, 1); PG8_STAGE(PG8_SB(1, 0), b3, voffB); PG8_STAGE(PG8_SB(1, 1), b3 + hstepB, voffB); PG8_STAGE(PG8_SA(1, 0), a3, voffA);
;             PG8_WAIT_V(8); PG8_WAIT_L(0); PG8_BAR; PG8_MMA(1, 0, At, B0); PG8_MMA(1, 1, At, B1); PG8_BAR; PG8_SCHED;
	s_add_i32 s52, s78, s54
	v_lshl_add_u64 v[168:169], v[168:169], 0, s[12:13]
	s_mov_b32 m0, s52
	ds_read_b128 v[186:189], v175 offset:49152
	ds_read_b128 v[190:193], v175 offset:50176
	ds_read_b128 v[194:197], v175 offset:51200
	ds_read_b128 v[198:201], v175 offset:52224
	ds_read_b128 v[202:205], v175 offset:53248
	ds_read_b128 v[206:209], v175 offset:54272
	ds_read_b128 v[210:213], v175 offset:55296
	ds_read_b128 v[214:217], v175 offset:56320
	global_load_lds_dwordx4 v[168:169], off
	s_add_i32 m0, s52, 0x2000
	s_add_u32 s42, s42, 0x40080
	v_lshl_add_u64 v[168:169], v[218:219], 0, s[12:13]
	s_addc_u32 s43, s43, 0
	s_add_i32 s52, s79, s54
	global_load_lds_dwordx4 v[168:169], off
	v_lshl_add_u64 v[168:169], s[42:43], 0, v[146:147]
	s_mov_b32 m0, s52
	s_nop 0
	global_load_lds_dwordx4 v[168:169], off
	v_lshl_add_u64 v[168:169], s[42:43], 0, v[150:151]
	s_add_i32 m0, s52, 0x2000
	s_nop 0
	global_load_lds_dwordx4 v[168:169], off
	v_lshl_add_u64 v[168:169], v[220:221], 0, s[12:13]
	s_mov_b32 m0, s65
	s_nop 0
	global_load_lds_dwordx4 v[168:169], off
	v_lshl_add_u64 v[168:169], v[222:223], 0, s[12:13]
	s_mov_b32 m0, s68
	s_nop 0
	global_load_lds_dwordx4 v[168:169], off
	s_waitcnt vmcnt(8)
	s_waitcnt lgkmcnt(0)
	s_barrier
	s_setprio 1
	s_waitcnt lgkmcnt(0)
	v_mfma_f32_16x16x32_bf16 v[60:63], v[128:131], v[186:189], v[60:63]
	v_mfma_f32_16x16x32_bf16 v[56:59], v[136:139], v[186:189], v[56:59]
	v_mfma_f32_16x16x32_bf16 v[44:47], v[128:131], v[194:197], v[44:47]
	v_mfma_f32_16x16x32_bf16 v[40:43], v[136:139], v[194:197], v[40:43]
	v_mfma_f32_16x16x32_bf16 v[28:31], v[128:131], v[202:205], v[28:31]
	v_mfma_f32_16x16x32_bf16 v[24:27], v[136:139], v[202:205], v[24:27]
	v_mfma_f32_16x16x32_bf16 v[12:15], v[128:131], v[210:213], v[12:15]
	v_mfma_f32_16x16x32_bf16 v[8:11], v[136:139], v[210:213], v[8:11]
	v_mfma_f32_16x16x32_bf16 v[60:63], v[132:135], v[190:193], v[60:63]
	v_mfma_f32_16x16x32_bf16 v[56:59], v[140:143], v[190:193], v[56:59]
	v_mfma_f32_16x16x32_bf16 v[44:47], v[132:135], v[198:201], v[44:47]
	v_mfma_f32_16x16x32_bf16 v[40:43], v[140:143], v[198:201], v[40:43]
	v_mfma_f32_16x16x32_bf16 v[28:31], v[132:135], v[206:209], v[28:31]
	v_mfma_f32_16x16x32_bf16 v[24:27], v[140:143], v[206:209], v[24:27]
	v_mfma_f32_16x16x32_bf16 v[12:15], v[132:135], v[214:217], v[12:15]
	v_mfma_f32_16x16x32_bf16 v[8:11], v[140:143], v[214:217], v[8:11]
	s_setprio 0
	s_setprio 1
	v_mfma_f32_16x16x32_bf16 v[52:55], v[160:163], v[186:189], v[52:55]
	v_mfma_f32_16x16x32_bf16 v[48:51], v[178:181], v[186:189], v[48:51]
	v_mfma_f32_16x16x32_bf16 v[36:39], v[160:163], v[194:197], v[36:39]
	v_mfma_f32_16x16x32_bf16 v[32:35], v[178:181], v[194:197], v[32:35]
	v_mfma_f32_16x16x32_bf16 v[20:23], v[160:163], v[202:205], v[20:23]
	v_mfma_f32_16x16x32_bf16 v[16:19], v[178:181], v[202:205], v[16:19]
	v_mfma_f32_16x16x32_bf16 v[4:7], v[160:163], v[210:213], v[4:7]
	v_mfma_f32_16x16x32_bf16 v[0:3], v[178:181], v[210:213], v[0:3]
	v_mfma_f32_16x16x32_bf16 v[52:55], v[164:167], v[190:193], v[52:55]
	v_mfma_f32_16x16x32_bf16 v[48:51], v[182:185], v[190:193], v[48:51]
	v_mfma_f32_16x16x32_bf16 v[36:39], v[164:167], v[198:201], v[36:39]
	v_mfma_f32_16x16x32_bf16 v[32:35], v[182:185], v[198:201], v[32:35]
	v_mfma_f32_16x16x32_bf16 v[20:23], v[164:167], v[206:209], v[20:23]
	v_mfma_f32_16x16x32_bf16 v[16:19], v[182:185], v[206:209], v[16:19]
	v_mfma_f32_16x16x32_bf16 v[4:7], v[164:167], v[214:217], v[4:7]
	v_mfma_f32_16x16x32_bf16 v[0:3], v[182:185], v[214:217], v[0:3]
	s_setprio 0
	s_barrier
	s_add_i32 s77, s77, 2
	s_add_u32 s38, s38, 0x100
	s_addc_u32 s39, s39, 0
	s_add_u32 s75, s75, 0x100
	s_addc_u32 s76, s76, 0
	s_cmp_gt_u32 s77, 13

; #define PG8_STAGE(bufoff, gbase, voff) do { _Pragma("unroll") for (int _i = 0; _i < 2; ++_i) \
;         __builtin_amdgcn_global_load_lds((const unsigned*)((const char*)(gbase) + (voff)[_i]), (LAS unsigned*)(lds + (bufoff) + ldsw + _i * 8192), 16, 0, 0); } while (0)
; #define PG8_LDA(dst, b, h) do { _Pragma("unroll") for (int m = 0; m < 4; ++m) _Pragma("unroll") for (int k = 0; k < 2; ++k) dst[m][k] = *(const LAS bf16x8*)(lds + PG8_SA(b, h) + aoff + m * 2048 + k * 1024); } while (0)
; #define PG8_LDB(dst, b, h) do { _Pragma("unroll") for (int n = 0; n < 2; ++n) _Pragma("unroll") for (int k = 0; k < 2; ++k) dst[n][k] = *(const LAS bf16x8*)(lds + PG8_SB(b, h) + boff + n * 2048 + k * 1024); } while (0)
; #define PG8_WAIT_V(n) asm volatile("s_waitcnt vmcnt(" #n ")" ::: "memory")
; template <class Epi>
; __device__ __forceinline__ void gemm_phase(LAS unsigned char* lds, const Gemm g, const StaticOrder& S, const Epi& E) {
;     ...
;         const bool has_next = S.next(ui + 1, nxt);
;         const char* nA = has_next ? (const char*)g.A + (size_t)nxt.pm * tstepA : cA; const char* nB = has_next ? (const char*)g.Bt + (size_t)nxt.pn * tstepB : cB;
; #pragma nounroll
;         for (int t = 0; t < nt; t += 2) {
;             const bool last = (t == nt - 2);
;             const char* a1 = cA + (size_t)(t + 1) * kstep;
;             const char* a2 = last ? nA : cA + (size_t)(t + 2) * kstep; const char* b2 = last ? nB : cB + (size_t)(t + 2) * kstep;
;             const char* a3 = a2 + kstep; const char* b3 = b2 + kstep;
;             PG8_LDB(B0, 0, 0); PG8_LDB(B1, 0, 1); PG8_SCHED; PG8_LDA(At, 0, 0); PG8_STAGE(PG8_SA(1, 1), a1 + hstepA, voffA);
;             PG8_WAIT_V(8); PG8_WAIT_L(0); PG8_BAR; PG8_MMA(0, 0, At, B0); PG8_MMA(0, 1, At, B1); PG8_BAR; PG8_SCHED;
;             PG8_LDA(At, 0, 1); PG8_STAGE(PG8_SB(0, 0), b2, voffB); PG8_STAGE(PG8_SB(0, 1), b2 + hstepB, voffB); PG8_STAGE(PG8_SA(0, 0), a2, voffA);
;             PG8_WAIT_V(8); PG8_WAIT_L(0); PG8_BAR; PG8_MMA(1, 0, At, B0); PG8_MMA(1, 1, At, B1); PG8_BAR; PG8_SCHED;
;     ...
; #pragma unroll
;         for (int a = 0; a < 2; ++a)
; #pragma unroll
;             for (int b = 0; b < 2; ++b)
; #pragma unroll
;                 for (int m = 0; m < 4; ++m)
; #pragma unroll
;                     for (int n = 0; n < 2; ++n) acc[a][b][m][n] = (f32x4){0.f, 0.f, 0.f, 0.f};
;         cur = nxt; cA = nA; cB = nB; ++ui;
.LBB0_545:
	s_ashr_i32 s71, s70, 31
	s_lshl_b64 s[12:13], s[70:71], 19
	s_add_u32 s72, s24, s12
	s_addc_u32 s73, s25, s13
	s_and_b64 s[12:13], s[4:5], exec
	s_cselect_b32 s1, s73, s9
	s_cselect_b32 s7, s72, s8
	s_ashr_i32 s69, s68, 31
	s_lshl_b64 s[12:13], s[68:69], 19
	s_add_u32 s74, s3, s12
	s_addc_u32 s75, s33, s13
	s_and_b64 s[12:13], s[4:5], exec
	s_cselect_b32 s69, s75, s11
	s_cselect_b32 s71, s74, s10
	s_add_u32 s8, s8, 0x40080
	s_addc_u32 s9, s9, 0
	s_add_u32 s76, s10, 0x100
	s_addc_u32 s77, s11, 0
	s_mov_b32 s89, -2
	s_waitcnt vmcnt(0)
	ds_read_b128 v[146:149], v162
	ds_read_b128 v[166:169], v162 offset:1024
	ds_read_b128 v[170:173], v162 offset:2048
	ds_read_b128 v[178:181], v162 offset:3072
	ds_read_b128 v[182:185], v163
	ds_read_b128 v[186:189], v163 offset:1024
	ds_read_b128 v[190:193], v163 offset:2048
	ds_read_b128 v[194:197], v163 offset:3072
	s_add_u32 s10, s8, 0xfffc0080
	s_addc_u32 s11, s9, -1
	s_cmp_eq_u32 s89, 12
	s_cselect_b32 s13, s1, s11
	s_cselect_b32 s12, s7, s10
	s_cselect_b32 s11, s69, s77
	s_cselect_b32 s10, s71, s76
	v_lshl_add_u64 v[174:175], s[8:9], 0, v[138:139]
	s_add_i32 m0, s43, 0xc000
	ds_read_b128 v[198:201], v164
	ds_read_b128 v[202:205], v164 offset:1024
	ds_read_b128 v[206:209], v164 offset:2048
	ds_read_b128 v[210:213], v164 offset:3072
	ds_read_b128 v[214:217], v164 offset:4096
	ds_read_b128 v[218:221], v164 offset:5120
	ds_read_b128 v[226:229], v164 offset:6144
	ds_read_b128 v[230:233], v164 offset:7168
	global_load_lds_dwordx4 v[174:175], off
	v_lshl_add_u64 v[174:175], s[8:9], 0, v[140:141]
	s_add_i32 m0, s43, 0xe000
	s_nop 0
	global_load_lds_dwordx4 v[174:175], off
	s_waitcnt vmcnt(8)
	s_waitcnt lgkmcnt(0)
	s_barrier
	s_setprio 1
	s_waitcnt lgkmcnt(0)
	v_mfma_f32_16x16x32_bf16 v[124:127], v[146:149], v[198:201], 0
	v_mfma_f32_16x16x32_bf16 v[120:123], v[170:173], v[198:201], 0
	v_mfma_f32_16x16x32_bf16 v[112:115], v[146:149], v[206:209], 0
	v_mfma_f32_16x16x32_bf16 v[104:107], v[170:173], v[206:209], 0
	v_mfma_f32_16x16x32_bf16 v[100:103], v[146:149], v[214:217], 0
	v_mfma_f32_16x16x32_bf16 v[92:95], v[170:173], v[214:217], 0
	v_mfma_f32_16x16x32_bf16 v[84:87], v[146:149], v[226:229], 0
	v_mfma_f32_16x16x32_bf16 v[76:79], v[170:173], v[226:229], 0
	v_mfma_f32_16x16x32_bf16 v[124:127], v[166:169], v[202:205], v[124:127]
	v_mfma_f32_16x16x32_bf16 v[120:123], v[178:181], v[202:205], v[120:123]
	v_mfma_f32_16x16x32_bf16 v[112:115], v[166:169], v[210:213], v[112:115]
	v_mfma_f32_16x16x32_bf16 v[104:107], v[178:181], v[210:213], v[104:107]
	v_mfma_f32_16x16x32_bf16 v[100:103], v[166:169], v[218:221], v[100:103]
	v_mfma_f32_16x16x32_bf16 v[92:95], v[178:181], v[218:221], v[92:95]
	v_mfma_f32_16x16x32_bf16 v[84:87], v[166:169], v[230:233], v[84:87]
	v_mfma_f32_16x16x32_bf16 v[76:79], v[178:181], v[230:233], v[76:79]
	s_setprio 0
	s_setprio 1
	v_mfma_f32_16x16x32_bf16 v[116:119], v[182:185], v[198:201], 0
	v_mfma_f32_16x16x32_bf16 v[108:111], v[190:193], v[198:201], 0
	v_mfma_f32_16x16x32_bf16 v[96:99], v[182:185], v[206:209], 0
	v_mfma_f32_16x16x32_bf16 v[88:91], v[190:193], v[206:209], 0
	v_mfma_f32_16x16x32_bf16 v[80:83], v[182:185], v[214:217], 0
	v_mfma_f32_16x16x32_bf16 v[72:75], v[190:193], v[214:217], 0
	v_mfma_f32_16x16x32_bf16 v[68:71], v[182:185], v[226:229], 0
	v_mfma_f32_16x16x32_bf16 v[64:67], v[190:193], v[226:229], 0
	v_mfma_f32_16x16x32_bf16 v[116:119], v[186:189], v[202:205], v[116:119]
	v_mfma_f32_16x16x32_bf16 v[108:111], v[194:197], v[202:205], v[108:111]
	v_mfma_f32_16x16x32_bf16 v[96:99], v[186:189], v[210:213], v[96:99]
	v_mfma_f32_16x16x32_bf16 v[88:91], v[194:197], v[210:213], v[88:91]
	v_mfma_f32_16x16x32_bf16 v[80:83], v[186:189], v[218:221], v[80:83]
	v_mfma_f32_16x16x32_bf16 v[72:75], v[194:197], v[218:221], v[72:75]
	v_mfma_f32_16x16x32_bf16 v[68:71], v[186:189], v[230:233], v[68:71]
	v_mfma_f32_16x16x32_bf16 v[64:67], v[194:197], v[230:233], v[64:67]
	s_setprio 0
	s_barrier
	s_add_i32 s90, s85, s39
	v_lshl_add_u64 v[174:175], s[10:11], 0, v[130:131]
	s_mov_b32 m0, s90
	ds_read_b128 v[198:201], v164 offset:16384
	ds_read_b128 v[202:205], v164 offset:17408
	ds_read_b128 v[206:209], v164 offset:18432
	ds_read_b128 v[210:213], v164 offset:19456
	ds_read_b128 v[214:217], v164 offset:20480
	ds_read_b128 v[218:221], v164 offset:21504
	ds_read_b128 v[226:229], v164 offset:22528
	ds_read_b128 v[230:233], v164 offset:23552
	global_load_lds_dwordx4 v[174:175], off
	s_add_i32 m0, s90, 0x2000
	s_add_u32 s90, s10, 0x40000
	v_lshl_add_u64 v[222:223], s[10:11], 0, v[134:135]
	s_addc_u32 s91, s11, 0
	s_add_i32 s92, s86, s39
	global_load_lds_dwordx4 v[222:223], off
	v_lshl_add_u64 v[234:235], s[90:91], 0, v[130:131]
	s_mov_b32 m0, s92
	v_lshl_add_u64 v[236:237], s[12:13], 0, v[132:133]
	global_load_lds_dwordx4 v[234:235], off
	v_lshl_add_u64 v[234:235], s[90:91], 0, v[134:135]
	s_add_i32 m0, s92, 0x2000
	s_nop 0
	global_load_lds_dwordx4 v[234:235], off
	v_lshl_add_u64 v[234:235], s[12:13], 0, v[128:129]
	s_mov_b32 m0, s43
	s_nop 0
	global_load_lds_dwordx4 v[234:235], off
	s_mov_b32 m0, s53
	s_nop 0
	global_load_lds_dwordx4 v[236:237], off
	s_waitcnt vmcnt(8)
	s_waitcnt lgkmcnt(0)
	s_barrier
; #define PG8_STAGE(bufoff, gbase, voff) do { _Pragma("unroll") for (int _i = 0; _i < 2; ++_i) \
;         __builtin_amdgcn_global_load_lds((const unsigned*)((const char*)(gbase) + (voff)[_i]), (LAS unsigned*)(lds + (bufoff) + ldsw + _i * 8192), 16, 0, 0); } while (0)
; #define PG8_LDA(dst, b, h) do { _Pragma("unroll") for (int m = 0; m < 4; ++m) _Pragma("unroll") for (int k = 0; k < 2; ++k) dst[m][k] = *(const LAS bf16x8*)(lds + PG8_SA(b, h) + aoff + m * 2048 + k * 1024); } while (0)
; #define PG8_LDB(dst, b, h) do { _Pragma("unroll") for (int n = 0; n < 2; ++n) _Pragma("unroll") for (int k = 0; k < 2; ++k) dst[n][k] = *(const LAS bf16x8*)(lds + PG8_SB(b, h) + boff + n * 2048 + k * 1024); } while (0)
; #define PG8_MMA(ai, bj, At, Bt) do { __builtin_amdgcn_s_setprio(1); _Pragma("unroll") for (int m = 0; m < 4; ++m) _Pragma("unroll") for (int n = 0; n < 2; ++n) _Pragma("unroll") for (int k = 0; k < 2; ++k) \
;         acc[ai][bj][m][n] = __builtin_amdgcn_mfma_f32_16x16x32_bf16(Bt[n][k], At[m][k], acc[ai][bj][m][n], 0, 0, 0); __builtin_amdgcn_s_setprio(0); } while (0)
; #define PG8_WAIT_V(n) asm volatile("s_waitcnt vmcnt(" #n ")" ::: "memory")
; #define PG8_WAIT_L(n) asm volatile("s_waitcnt lgkmcnt(" #n ")" ::: "memory")
; #define PG8_BAR __builtin_amdgcn_s_barrier()
; #define PG8_SCHED __builtin_amdgcn_sched_barrier(0)
; template <class Epi>
; __device__ __forceinline__ void gemm_phase(LAS unsigned char* lds, const Gemm g, const StaticOrder& S, const Epi& E) {
;     ...
;             PG8_WAIT_V(8); PG8_WAIT_L(0); PG8_BAR; PG8_MMA(1, 0, At, B0); PG8_MMA(1, 1, At, B1); PG8_BAR; PG8_SCHED;
;             PG8_LDB(B0, 1, 0); PG8_LDB(B1, 1, 1); PG8_SCHED; PG8_LDA(At, 1, 0); PG8_STAGE(PG8_SA(0, 1), a2 + hstepA, voffA);
;             PG8_WAIT_V(8); PG8_WAIT_L(0); PG8_BAR; PG8_MMA(0, 0, At, B0); PG8_MMA(0, 1, At, B1); PG8_BAR; PG8_SCHED;
;             PG8_LDA(At, 1, 1); PG8_STAGE(PG8_SB(1, 0), b3, voffB); PG8_STAGE(PG8_SB(1, 1), b3 + hstepB, voffB); PG8_STAGE(PG8_SA(1, 0), a3, voffA);
;             PG8_WAIT_V(8); PG8_WAIT_L(0); PG8_BAR; PG8_MMA(1, 0, At, B0); PG8_MMA(1, 1, At, B1); PG8_BAR; PG8_SCHED;
	s_setprio 1
	s_waitcnt lgkmcnt(0)
	v_mfma_f32_16x16x32_bf16 v[60:63], v[146:149], v[198:201], 0
	v_mfma_f32_16x16x32_bf16 v[56:59], v[170:173], v[198:201], 0
	v_mfma_f32_16x16x32_bf16 v[52:55], v[146:149], v[206:209], 0
	v_mfma_f32_16x16x32_bf16 v[44:47], v[170:173], v[206:209], 0
	v_mfma_f32_16x16x32_bf16 v[36:39], v[146:149], v[214:217], 0
	v_mfma_f32_16x16x32_bf16 v[28:31], v[170:173], v[214:217], 0
	v_mfma_f32_16x16x32_bf16 v[20:23], v[146:149], v[226:229], 0
	v_mfma_f32_16x16x32_bf16 v[12:15], v[170:173], v[226:229], 0
	v_mfma_f32_16x16x32_bf16 v[60:63], v[166:169], v[202:205], v[60:63]
	v_mfma_f32_16x16x32_bf16 v[56:59], v[178:181], v[202:205], v[56:59]
	v_mfma_f32_16x16x32_bf16 v[52:55], v[166:169], v[210:213], v[52:55]
	v_mfma_f32_16x16x32_bf16 v[44:47], v[178:181], v[210:213], v[44:47]
	v_mfma_f32_16x16x32_bf16 v[36:39], v[166:169], v[218:221], v[36:39]
	v_mfma_f32_16x16x32_bf16 v[28:31], v[178:181], v[218:221], v[28:31]
	v_mfma_f32_16x16x32_bf16 v[20:23], v[166:169], v[230:233], v[20:23]
	v_mfma_f32_16x16x32_bf16 v[12:15], v[178:181], v[230:233], v[12:15]
	s_setprio 0
	s_setprio 1
	v_mfma_f32_16x16x32_bf16 v[48:51], v[182:185], v[198:201], 0
	v_mfma_f32_16x16x32_bf16 v[40:43], v[190:193], v[198:201], 0
	v_mfma_f32_16x16x32_bf16 v[32:35], v[182:185], v[206:209], 0
	v_mfma_f32_16x16x32_bf16 v[24:27], v[190:193], v[206:209], 0
	v_mfma_f32_16x16x32_bf16 v[16:19], v[182:185], v[214:217], 0
	v_mfma_f32_16x16x32_bf16 v[8:11], v[190:193], v[214:217], 0
	v_mfma_f32_16x16x32_bf16 v[4:7], v[182:185], v[226:229], 0
	v_mfma_f32_16x16x32_bf16 v[0:3], v[190:193], v[226:229], 0
	v_mfma_f32_16x16x32_bf16 v[48:51], v[186:189], v[202:205], v[48:51]
	v_mfma_f32_16x16x32_bf16 v[40:43], v[194:197], v[202:205], v[40:43]
	v_mfma_f32_16x16x32_bf16 v[32:35], v[186:189], v[210:213], v[32:35]
	v_mfma_f32_16x16x32_bf16 v[24:27], v[194:197], v[210:213], v[24:27]
	v_mfma_f32_16x16x32_bf16 v[16:19], v[186:189], v[218:221], v[16:19]
	v_mfma_f32_16x16x32_bf16 v[8:11], v[194:197], v[218:221], v[8:11]
	v_mfma_f32_16x16x32_bf16 v[4:7], v[186:189], v[230:233], v[4:7]
	v_mfma_f32_16x16x32_bf16 v[0:3], v[194:197], v[230:233], v[0:3]
	s_setprio 0
	s_barrier
	s_add_i32 s90, 0, 0x18000
	v_add_u32_e32 v136, s90, v161
	s_add_i32 s91, 0, 0x1c000
	ds_read_b128 v[146:149], v136
	ds_read_b128 v[166:169], v136 offset:1024
	ds_read_b128 v[170:173], v136 offset:2048
	ds_read_b128 v[178:181], v136 offset:3072
	v_add_u32_e32 v136, s91, v161
	ds_read_b128 v[182:185], v136
	ds_read_b128 v[186:189], v136 offset:1024
	ds_read_b128 v[190:193], v136 offset:2048
	ds_read_b128 v[194:197], v136 offset:3072
	s_add_u32 s12, s12, 0x40000
	s_addc_u32 s13, s13, 0
	s_mov_b32 m0, s55
	v_lshl_add_u64 v[238:239], s[12:13], 0, v[128:129]
	ds_read_b128 v[198:201], v164 offset:32768
	ds_read_b128 v[202:205], v164 offset:33792
	ds_read_b128 v[206:209], v164 offset:34816
	ds_read_b128 v[210:213], v164 offset:35840
	ds_read_b128 v[214:217], v164 offset:36864
	ds_read_b128 v[218:221], v164 offset:37888
	ds_read_b128 v[226:229], v164 offset:38912
	ds_read_b128 v[230:233], v164 offset:39936
	global_load_lds_dwordx4 v[238:239], off
	v_lshl_add_u64 v[238:239], s[12:13], 0, v[132:133]
	s_mov_b32 m0, s57
	s_nop 0
	global_load_lds_dwordx4 v[238:239], off
	s_waitcnt vmcnt(8)
	s_waitcnt lgkmcnt(0)
	s_barrier
	s_setprio 1
	s_waitcnt lgkmcnt(0)
	v_mfma_f32_16x16x32_bf16 v[124:127], v[146:149], v[198:201], v[124:127]
	v_mfma_f32_16x16x32_bf16 v[120:123], v[170:173], v[198:201], v[120:123]
	v_mfma_f32_16x16x32_bf16 v[112:115], v[146:149], v[206:209], v[112:115]
	v_mfma_f32_16x16x32_bf16 v[104:107], v[170:173], v[206:209], v[104:107]
	v_mfma_f32_16x16x32_bf16 v[100:103], v[146:149], v[214:217], v[100:103]
	v_mfma_f32_16x16x32_bf16 v[92:95], v[170:173], v[214:217], v[92:95]
	v_mfma_f32_16x16x32_bf16 v[84:87], v[146:149], v[226:229], v[84:87]
	v_mfma_f32_16x16x32_bf16 v[76:79], v[170:173], v[226:229], v[76:79]
	v_mfma_f32_16x16x32_bf16 v[124:127], v[166:169], v[202:205], v[124:127]
	v_mfma_f32_16x16x32_bf16 v[120:123], v[178:181], v[202:205], v[120:123]
	v_mfma_f32_16x16x32_bf16 v[112:115], v[166:169], v[210:213], v[112:115]
	v_mfma_f32_16x16x32_bf16 v[104:107], v[178:181], v[210:213], v[104:107]
	v_mfma_f32_16x16x32_bf16 v[100:103], v[166:169], v[218:221], v[100:103]
	v_mfma_f32_16x16x32_bf16 v[92:95], v[178:181], v[218:221], v[92:95]
	v_mfma_f32_16x16x32_bf16 v[84:87], v[166:169], v[230:233], v[84:87]
	v_mfma_f32_16x16x32_bf16 v[76:79], v[178:181], v[230:233], v[76:79]
	s_setprio 0
	s_setprio 1
	v_mfma_f32_16x16x32_bf16 v[116:119], v[182:185], v[198:201], v[116:119]
	v_mfma_f32_16x16x32_bf16 v[108:111], v[190:193], v[198:201], v[108:111]
	v_mfma_f32_16x16x32_bf16 v[96:99], v[182:185], v[206:209], v[96:99]
	v_mfma_f32_16x16x32_bf16 v[88:91], v[190:193], v[206:209], v[88:91]
	v_mfma_f32_16x16x32_bf16 v[80:83], v[182:185], v[214:217], v[80:83]
	v_mfma_f32_16x16x32_bf16 v[72:75], v[190:193], v[214:217], v[72:75]
	v_mfma_f32_16x16x32_bf16 v[68:71], v[182:185], v[226:229], v[68:71]
	v_mfma_f32_16x16x32_bf16 v[64:67], v[190:193], v[226:229], v[64:67]
	v_mfma_f32_16x16x32_bf16 v[116:119], v[186:189], v[202:205], v[116:119]
	v_mfma_f32_16x16x32_bf16 v[108:111], v[194:197], v[202:205], v[108:111]
	v_mfma_f32_16x16x32_bf16 v[96:99], v[186:189], v[210:213], v[96:99]
	v_mfma_f32_16x16x32_bf16 v[88:91], v[194:197], v[210:213], v[88:91]
	v_mfma_f32_16x16x32_bf16 v[80:83], v[186:189], v[218:221], v[80:83]
	v_mfma_f32_16x16x32_bf16 v[72:75], v[194:197], v[218:221], v[72:75]
	v_mfma_f32_16x16x32_bf16 v[68:71], v[186:189], v[230:233], v[68:71]
	v_mfma_f32_16x16x32_bf16 v[64:67], v[194:197], v[230:233], v[64:67]
	s_setprio 0
	s_barrier
; #define PG8_STAGE(bufoff, gbase, voff) do { _Pragma("unroll") for (int _i = 0; _i < 2; ++_i) \
;         __builtin_amdgcn_global_load_lds((const unsigned*)((const char*)(gbase) + (voff)[_i]), (LAS unsigned*)(lds + (bufoff) + ldsw + _i * 8192), 16, 0, 0); } while (0)
; #define PG8_LDA(dst, b, h) do { _Pragma("unroll") for (int m = 0; m < 4; ++m) _Pragma("unroll") for (int k = 0; k < 2; ++k) dst[m][k] = *(const LAS bf16x8*)(lds + PG8_SA(b, h) + aoff + m * 2048 + k * 1024); } while (0)
; #define PG8_LDB(dst, b, h) do { _Pragma("unroll") for (int n = 0; n < 2; ++n) _Pragma("unroll") for (int k = 0; k < 2; ++k) dst[n][k] = *(const LAS bf16x8*)(lds + PG8_SB(b, h) + boff + n * 2048 + k * 1024); } while (0)
; #define PG8_WAIT_V(n) asm volatile("s_waitcnt vmcnt(" #n ")" ::: "memory")
; #define PG8_WAIT_L(n) asm volatile("s_waitcnt lgkmcnt(" #n ")" ::: "memory")
; template <class Epi>
; __device__ __forceinline__ void gemm_phase(LAS unsigned char* lds, const Gemm g, const StaticOrder& S, const Epi& E) {
;     ...
;         for (int t = 0; t < nt; t += 2) {
;             const bool last = (t == nt - 2);
;             const char* a1 = cA + (size_t)(t + 1) * kstep;
;             const char* a2 = last ? nA : cA + (size_t)(t + 2) * kstep; const char* b2 = last ? nB : cB + (size_t)(t + 2) * kstep;
;             const char* a3 = a2 + kstep; const char* b3 = b2 + kstep;
;             PG8_LDB(B0, 0, 0); PG8_LDB(B1, 0, 1); PG8_SCHED; PG8_LDA(At, 0, 0); PG8_STAGE(PG8_SA(1, 1), a1 + hstepA, voffA);
;             PG8_WAIT_V(8); PG8_WAIT_L(0); PG8_BAR; PG8_MMA(0, 0, At, B0); PG8_MMA(0, 1, At, B1); PG8_BAR; PG8_SCHED;
;             PG8_LDA(At, 0, 1); PG8_STAGE(PG8_SB(0, 0), b2, voffB); PG8_STAGE(PG8_SB(0, 1), b2 + hstepB, voffB); PG8_STAGE(PG8_SA(0, 0), a2, voffA);
;             PG8_WAIT_V(8); PG8_WAIT_L(0); PG8_BAR; PG8_MMA(1, 0, At, B0); PG8_MMA(1, 1, At, B1); PG8_BAR; PG8_SCHED;
;             PG8_LDB(B0, 1, 0); PG8_LDB(B1, 1, 1); PG8_SCHED; PG8_LDA(At, 1, 0); PG8_STAGE(PG8_SA(0, 1), a2 + hstepA, voffA);
;             PG8_WAIT_V(8); PG8_WAIT_L(0); PG8_BAR; PG8_MMA(0, 0, At, B0); PG8_MMA(0, 1, At, B1); PG8_BAR; PG8_SCHED;
;             PG8_LDA(At, 1, 1); PG8_STAGE(PG8_SB(1, 0), b3, voffB); PG8_STAGE(PG8_SB(1, 1), b3 + hstepB, voffB); PG8_STAGE(PG8_SA(1, 0), a3, voffA);
;             PG8_WAIT_V(8); PG8_WAIT_L(0); PG8_BAR; PG8_MMA(1, 0, At, B0); PG8_MMA(1, 1, At, B1); PG8_BAR; PG8_SCHED;
	s_add_i32 s12, s90, s39
	v_lshl_add_u64 v[174:175], v[174:175], 0, s[30:31]
	s_mov_b32 m0, s12
	ds_read_b128 v[198:201], v164 offset:49152
	ds_read_b128 v[202:205], v164 offset:50176
	ds_read_b128 v[206:209], v164 offset:51200
	ds_read_b128 v[210:213], v164 offset:52224
	ds_read_b128 v[214:217], v164 offset:53248
	ds_read_b128 v[218:221], v164 offset:54272
	ds_read_b128 v[226:229], v164 offset:55296
	ds_read_b128 v[230:233], v164 offset:56320
	global_load_lds_dwordx4 v[174:175], off
	s_add_i32 m0, s12, 0x2000
	s_add_u32 s10, s10, 0x40080
	v_lshl_add_u64 v[174:175], v[222:223], 0, s[30:31]
	s_addc_u32 s11, s11, 0
	s_add_i32 s12, s91, s39
	global_load_lds_dwordx4 v[174:175], off
	v_lshl_add_u64 v[174:175], s[10:11], 0, v[130:131]
	s_mov_b32 m0, s12
	s_nop 0
	global_load_lds_dwordx4 v[174:175], off
	v_lshl_add_u64 v[174:175], s[10:11], 0, v[134:135]
	s_add_i32 m0, s12, 0x2000
	s_nop 0
	global_load_lds_dwordx4 v[174:175], off
	v_lshl_add_u64 v[174:175], v[234:235], 0, s[30:31]
	s_mov_b32 m0, s79
	s_nop 0
	global_load_lds_dwordx4 v[174:175], off
	v_lshl_add_u64 v[174:175], v[236:237], 0, s[30:31]
	s_mov_b32 m0, s80
	s_nop 0
	global_load_lds_dwordx4 v[174:175], off
	s_waitcnt vmcnt(8)
	s_waitcnt lgkmcnt(0)
	s_barrier
	s_setprio 1
	s_waitcnt lgkmcnt(0)
	v_mfma_f32_16x16x32_bf16 v[60:63], v[146:149], v[198:201], v[60:63]
	v_mfma_f32_16x16x32_bf16 v[56:59], v[170:173], v[198:201], v[56:59]
	v_mfma_f32_16x16x32_bf16 v[52:55], v[146:149], v[206:209], v[52:55]
	v_mfma_f32_16x16x32_bf16 v[44:47], v[170:173], v[206:209], v[44:47]
	v_mfma_f32_16x16x32_bf16 v[36:39], v[146:149], v[214:217], v[36:39]
	v_mfma_f32_16x16x32_bf16 v[28:31], v[170:173], v[214:217], v[28:31]
	v_mfma_f32_16x16x32_bf16 v[20:23], v[146:149], v[226:229], v[20:23]
	v_mfma_f32_16x16x32_bf16 v[12:15], v[170:173], v[226:229], v[12:15]
	v_mfma_f32_16x16x32_bf16 v[60:63], v[166:169], v[202:205], v[60:63]
	v_mfma_f32_16x16x32_bf16 v[56:59], v[178:181], v[202:205], v[56:59]
	v_mfma_f32_16x16x32_bf16 v[52:55], v[166:169], v[210:213], v[52:55]
	v_mfma_f32_16x16x32_bf16 v[44:47], v[178:181], v[210:213], v[44:47]
	v_mfma_f32_16x16x32_bf16 v[36:39], v[166:169], v[218:221], v[36:39]
	v_mfma_f32_16x16x32_bf16 v[28:31], v[178:181], v[218:221], v[28:31]
	v_mfma_f32_16x16x32_bf16 v[20:23], v[166:169], v[230:233], v[20:23]
	v_mfma_f32_16x16x32_bf16 v[12:15], v[178:181], v[230:233], v[12:15]
	s_setprio 0
	s_setprio 1
	v_mfma_f32_16x16x32_bf16 v[48:51], v[182:185], v[198:201], v[48:51]
	v_mfma_f32_16x16x32_bf16 v[40:43], v[190:193], v[198:201], v[40:43]
	v_mfma_f32_16x16x32_bf16 v[32:35], v[182:185], v[206:209], v[32:35]
	v_mfma_f32_16x16x32_bf16 v[24:27], v[190:193], v[206:209], v[24:27]
	v_mfma_f32_16x16x32_bf16 v[16:19], v[182:185], v[214:217], v[16:19]
	v_mfma_f32_16x16x32_bf16 v[8:11], v[190:193], v[214:217], v[8:11]
	v_mfma_f32_16x16x32_bf16 v[4:7], v[182:185], v[226:229], v[4:7]
	v_mfma_f32_16x16x32_bf16 v[0:3], v[190:193], v[226:229], v[0:3]
	v_mfma_f32_16x16x32_bf16 v[48:51], v[186:189], v[202:205], v[48:51]
	v_mfma_f32_16x16x32_bf16 v[40:43], v[194:197], v[202:205], v[40:43]
	v_mfma_f32_16x16x32_bf16 v[32:35], v[186:189], v[210:213], v[32:35]
	v_mfma_f32_16x16x32_bf16 v[24:27], v[194:197], v[210:213], v[24:27]
	v_mfma_f32_16x16x32_bf16 v[16:19], v[186:189], v[218:221], v[16:19]
	v_mfma_f32_16x16x32_bf16 v[8:11], v[194:197], v[218:221], v[8:11]
	v_mfma_f32_16x16x32_bf16 v[4:7], v[186:189], v[230:233], v[4:7]
	v_mfma_f32_16x16x32_bf16 v[0:3], v[194:197], v[230:233], v[0:3]
	s_setprio 0
	s_barrier
	s_add_i32 s89, s89, 2
	s_add_u32 s8, s8, 0x100
	s_addc_u32 s9, s9, 0
	s_add_u32 s76, s76, 0x100
	s_addc_u32 s77, s77, 0
	s_cmp_gt_u32 s89, 13

; #define PG8_STAGE(bufoff, gbase, voff) do { _Pragma("unroll") for (int _i = 0; _i < 2; ++_i) \
;         __builtin_amdgcn_global_load_lds((const unsigned*)((const char*)(gbase) + (voff)[_i]), (LAS unsigned*)(lds + (bufoff) + ldsw + _i * 8192), 16, 0, 0); } while (0)
; #define PG8_LDA(dst, b, h) do { _Pragma("unroll") for (int m = 0; m < 4; ++m) _Pragma("unroll") for (int k = 0; k < 2; ++k) dst[m][k] = *(const LAS bf16x8*)(lds + PG8_SA(b, h) + aoff + m * 2048 + k * 1024); } while (0)
; #define PG8_LDB(dst, b, h) do { _Pragma("unroll") for (int n = 0; n < 2; ++n) _Pragma("unroll") for (int k = 0; k < 2; ++k) dst[n][k] = *(const LAS bf16x8*)(lds + PG8_SB(b, h) + boff + n * 2048 + k * 1024); } while (0)
; #define PG8_MMA(ai, bj, At, Bt) do { __builtin_amdgcn_s_setprio(1); _Pragma("unroll") for (int m = 0; m < 4; ++m) _Pragma("unroll") for (int n = 0; n < 2; ++n) _Pragma("unroll") for (int k = 0; k < 2; ++k) \
;         acc[ai][bj][m][n] = __builtin_amdgcn_mfma_f32_16x16x32_bf16(Bt[n][k], At[m][k], acc[ai][bj][m][n], 0, 0, 0); __builtin_amdgcn_s_setprio(0); } while (0)
; #define PG8_WAIT_V(n) asm volatile("s_waitcnt vmcnt(" #n ")" ::: "memory")
; template <class Epi>
; __device__ __forceinline__ void gemm_phase(LAS unsigned char* lds, const Gemm g, const StaticOrder& S, const Epi& E) {
;     ...
;         const char* nA = has_next ? (const char*)g.A + (size_t)nxt.pm * tstepA : cA; const char* nB = has_next ? (const char*)g.Bt + (size_t)nxt.pn * tstepB : cB;
; #pragma nounroll
;         for (int t = 0; t < nt; t += 2) {
;             const bool last = (t == nt - 2);
;             const char* a1 = cA + (size_t)(t + 1) * kstep;
;             const char* a2 = last ? nA : cA + (size_t)(t + 2) * kstep; const char* b2 = last ? nB : cB + (size_t)(t + 2) * kstep;
;             const char* a3 = a2 + kstep; const char* b3 = b2 + kstep;
;             PG8_LDB(B0, 0, 0); PG8_LDB(B1, 0, 1); PG8_SCHED; PG8_LDA(At, 0, 0); PG8_STAGE(PG8_SA(1, 1), a1 + hstepA, voffA);
;             PG8_WAIT_V(8); PG8_WAIT_L(0); PG8_BAR; PG8_MMA(0, 0, At, B0); PG8_MMA(0, 1, At, B1); PG8_BAR; PG8_SCHED;
;             PG8_LDA(At, 0, 1); PG8_STAGE(PG8_SB(0, 0), b2, voffB); PG8_STAGE(PG8_SB(0, 1), b2 + hstepB, voffB); PG8_STAGE(PG8_SA(0, 0), a2, voffA);
;             PG8_WAIT_V(8); PG8_WAIT_L(0); PG8_BAR; PG8_MMA(1, 0, At, B0); PG8_MMA(1, 1, At, B1); PG8_BAR; PG8_SCHED;
.LBB0_791:
	s_add_u32 s0, s0, 0xb0080
	s_addc_u32 s1, s1, 0
	s_add_u32 s75, s34, 0x100
	s_addc_u32 s76, s35, 0
	s_mov_b32 s77, -2
	s_waitcnt lgkmcnt(0)
	s_waitcnt vmcnt(0)
	ds_read_b128 v[128:131], v182
	ds_read_b128 v[132:135], v182 offset:1024
	ds_read_b128 v[136:139], v182 offset:2048
	ds_read_b128 v[140:143], v182 offset:3072
	ds_read_b128 v[160:163], v183
	ds_read_b128 v[164:167], v183 offset:1024
	ds_read_b128 v[168:171], v183 offset:2048
	ds_read_b128 v[172:175], v183 offset:3072
	s_add_u32 s34, s0, 0xfff50080
	s_addc_u32 s35, s1, -1
	s_cmp_eq_u32 s77, 40
	s_cselect_b32 s39, s7, s35
	s_cselect_b32 s38, s6, s34
	s_cselect_b32 s35, s23, s76
	s_cselect_b32 s34, s22, s75
	v_lshl_add_u64 v[178:179], s[0:1], 0, v[152:153]
	s_add_i32 m0, s43, 0xc000
	ds_read_b128 v[186:189], v184
	ds_read_b128 v[190:193], v184 offset:1024
	ds_read_b128 v[194:197], v184 offset:2048
	ds_read_b128 v[198:201], v184 offset:3072
	ds_read_b128 v[202:205], v184 offset:4096
	ds_read_b128 v[206:209], v184 offset:5120
	ds_read_b128 v[210:213], v184 offset:6144
	ds_read_b128 v[214:217], v184 offset:7168
	global_load_lds_dwordx4 v[178:179], off
	v_lshl_add_u64 v[178:179], s[0:1], 0, v[154:155]
	s_add_i32 m0, s43, 0xe000
	s_nop 0
	global_load_lds_dwordx4 v[178:179], off
	s_waitcnt vmcnt(8)
	s_waitcnt lgkmcnt(0)
	s_barrier
	s_setprio 1
	s_waitcnt lgkmcnt(0)
	v_mfma_f32_16x16x32_bf16 v[124:127], v[128:131], v[186:189], 0
	v_mfma_f32_16x16x32_bf16 v[120:123], v[136:139], v[186:189], 0
	v_mfma_f32_16x16x32_bf16 v[108:111], v[128:131], v[194:197], 0
	v_mfma_f32_16x16x32_bf16 v[104:107], v[136:139], v[194:197], 0
	v_mfma_f32_16x16x32_bf16 v[92:95], v[128:131], v[202:205], 0
	v_mfma_f32_16x16x32_bf16 v[88:91], v[136:139], v[202:205], 0
	v_mfma_f32_16x16x32_bf16 v[76:79], v[128:131], v[210:213], 0
	v_mfma_f32_16x16x32_bf16 v[72:75], v[136:139], v[210:213], 0
	v_mfma_f32_16x16x32_bf16 v[124:127], v[132:135], v[190:193], v[124:127]
	v_mfma_f32_16x16x32_bf16 v[120:123], v[140:143], v[190:193], v[120:123]
	v_mfma_f32_16x16x32_bf16 v[108:111], v[132:135], v[198:201], v[108:111]
	v_mfma_f32_16x16x32_bf16 v[104:107], v[140:143], v[198:201], v[104:107]
	v_mfma_f32_16x16x32_bf16 v[92:95], v[132:135], v[206:209], v[92:95]
	v_mfma_f32_16x16x32_bf16 v[88:91], v[140:143], v[206:209], v[88:91]
	v_mfma_f32_16x16x32_bf16 v[76:79], v[132:135], v[214:217], v[76:79]
	v_mfma_f32_16x16x32_bf16 v[72:75], v[140:143], v[214:217], v[72:75]
	s_setprio 0
	s_setprio 1
	v_mfma_f32_16x16x32_bf16 v[116:119], v[160:163], v[186:189], 0
	v_mfma_f32_16x16x32_bf16 v[112:115], v[168:171], v[186:189], 0
	v_mfma_f32_16x16x32_bf16 v[100:103], v[160:163], v[194:197], 0
	v_mfma_f32_16x16x32_bf16 v[96:99], v[168:171], v[194:197], 0
	v_mfma_f32_16x16x32_bf16 v[84:87], v[160:163], v[202:205], 0
	v_mfma_f32_16x16x32_bf16 v[80:83], v[168:171], v[202:205], 0
	v_mfma_f32_16x16x32_bf16 v[68:71], v[160:163], v[210:213], 0
	v_mfma_f32_16x16x32_bf16 v[64:67], v[168:171], v[210:213], 0
	v_mfma_f32_16x16x32_bf16 v[116:119], v[164:167], v[190:193], v[116:119]
	v_mfma_f32_16x16x32_bf16 v[112:115], v[172:175], v[190:193], v[112:115]
	v_mfma_f32_16x16x32_bf16 v[100:103], v[164:167], v[198:201], v[100:103]
	v_mfma_f32_16x16x32_bf16 v[96:99], v[172:175], v[198:201], v[96:99]
	v_mfma_f32_16x16x32_bf16 v[84:87], v[164:167], v[206:209], v[84:87]
	v_mfma_f32_16x16x32_bf16 v[80:83], v[172:175], v[206:209], v[80:83]
	v_mfma_f32_16x16x32_bf16 v[68:71], v[164:167], v[214:217], v[68:71]
	v_mfma_f32_16x16x32_bf16 v[64:67], v[172:175], v[214:217], v[64:67]
	s_setprio 0
	s_barrier
	s_add_i32 s78, s69, s42
	v_lshl_add_u64 v[178:179], s[34:35], 0, v[146:147]
	s_mov_b32 m0, s78
	ds_read_b128 v[186:189], v184 offset:16384
	ds_read_b128 v[190:193], v184 offset:17408
	ds_read_b128 v[194:197], v184 offset:18432
	ds_read_b128 v[198:201], v184 offset:19456
	ds_read_b128 v[202:205], v184 offset:20480
	ds_read_b128 v[206:209], v184 offset:21504
	ds_read_b128 v[210:213], v184 offset:22528
	ds_read_b128 v[214:217], v184 offset:23552
	global_load_lds_dwordx4 v[178:179], off
	s_add_i32 m0, s78, 0x2000
	s_add_u32 s78, s34, 0xb0000
	v_lshl_add_u64 v[218:219], s[34:35], 0, v[150:151]
	s_addc_u32 s79, s35, 0
	s_add_i32 s80, s70, s42
	global_load_lds_dwordx4 v[218:219], off
	v_lshl_add_u64 v[220:221], s[78:79], 0, v[146:147]
	s_mov_b32 m0, s80
	v_lshl_add_u64 v[222:223], s[38:39], 0, v[148:149]
	global_load_lds_dwordx4 v[220:221], off
	v_lshl_add_u64 v[220:221], s[78:79], 0, v[150:151]
	s_add_i32 m0, s80, 0x2000
	s_nop 0
	global_load_lds_dwordx4 v[220:221], off
	v_lshl_add_u64 v[220:221], s[38:39], 0, v[144:145]
	s_mov_b32 m0, s43
	s_nop 0
	global_load_lds_dwordx4 v[220:221], off
	s_mov_b32 m0, s52
	s_nop 0
	global_load_lds_dwordx4 v[222:223], off
	s_waitcnt vmcnt(8)
	s_waitcnt lgkmcnt(0)
	s_barrier
; #define PG8_STAGE(bufoff, gbase, voff) do { _Pragma("unroll") for (int _i = 0; _i < 2; ++_i) \
;         __builtin_amdgcn_global_load_lds((const unsigned*)((const char*)(gbase) + (voff)[_i]), (LAS unsigned*)(lds + (bufoff) + ldsw + _i * 8192), 16, 0, 0); } while (0)
; #define PG8_LDA(dst, b, h) do { _Pragma("unroll") for (int m = 0; m < 4; ++m) _Pragma("unroll") for (int k = 0; k < 2; ++k) dst[m][k] = *(const LAS bf16x8*)(lds + PG8_SA(b, h) + aoff + m * 2048 + k * 1024); } while (0)
; #define PG8_LDB(dst, b, h) do { _Pragma("unroll") for (int n = 0; n < 2; ++n) _Pragma("unroll") for (int k = 0; k < 2; ++k) dst[n][k] = *(const LAS bf16x8*)(lds + PG8_SB(b, h) + boff + n * 2048 + k * 1024); } while (0)
; #define PG8_MMA(ai, bj, At, Bt) do { __builtin_amdgcn_s_setprio(1); _Pragma("unroll") for (int m = 0; m < 4; ++m) _Pragma("unroll") for (int n = 0; n < 2; ++n) _Pragma("unroll") for (int k = 0; k < 2; ++k) \
;         acc[ai][bj][m][n] = __builtin_amdgcn_mfma_f32_16x16x32_bf16(Bt[n][k], At[m][k], acc[ai][bj][m][n], 0, 0, 0); __builtin_amdgcn_s_setprio(0); } while (0)
; #define PG8_WAIT_V(n) asm volatile("s_waitcnt vmcnt(" #n ")" ::: "memory")
; #define PG8_WAIT_L(n) asm volatile("s_waitcnt lgkmcnt(" #n ")" ::: "memory")
; #define PG8_BAR __builtin_amdgcn_s_barrier()
; #define PG8_SCHED __builtin_amdgcn_sched_barrier(0)
; template <class Epi>
; __device__ __forceinline__ void gemm_phase(LAS unsigned char* lds, const Gemm g, const StaticOrder& S, const Epi& E) {
;     ...
;             PG8_WAIT_V(8); PG8_WAIT_L(0); PG8_BAR; PG8_MMA(1, 0, At, B0); PG8_MMA(1, 1, At, B1); PG8_BAR; PG8_SCHED;
;             PG8_LDB(B0, 1, 0); PG8_LDB(B1, 1, 1); PG8_SCHED; PG8_LDA(At, 1, 0); PG8_STAGE(PG8_SA(0, 1), a2 + hstepA, voffA);
;             PG8_WAIT_V(8); PG8_WAIT_L(0); PG8_BAR; PG8_MMA(0, 0, At, B0); PG8_MMA(0, 1, At, B1); PG8_BAR; PG8_SCHED;
;             PG8_LDA(At, 1, 1); PG8_STAGE(PG8_SB(1, 0), b3, voffB); PG8_STAGE(PG8_SB(1, 1), b3 + hstepB, voffB); PG8_STAGE(PG8_SA(1, 0), a3, voffA);
	s_setprio 1
	s_waitcnt lgkmcnt(0)
	v_mfma_f32_16x16x32_bf16 v[60:63], v[128:131], v[186:189], 0
	v_mfma_f32_16x16x32_bf16 v[56:59], v[136:139], v[186:189], 0
	v_mfma_f32_16x16x32_bf16 v[44:47], v[128:131], v[194:197], 0
	v_mfma_f32_16x16x32_bf16 v[40:43], v[136:139], v[194:197], 0
	v_mfma_f32_16x16x32_bf16 v[28:31], v[128:131], v[202:205], 0
	v_mfma_f32_16x16x32_bf16 v[24:27], v[136:139], v[202:205], 0
	v_mfma_f32_16x16x32_bf16 v[12:15], v[128:131], v[210:213], 0
	v_mfma_f32_16x16x32_bf16 v[8:11], v[136:139], v[210:213], 0
	v_mfma_f32_16x16x32_bf16 v[60:63], v[132:135], v[190:193], v[60:63]
	v_mfma_f32_16x16x32_bf16 v[56:59], v[140:143], v[190:193], v[56:59]
	v_mfma_f32_16x16x32_bf16 v[44:47], v[132:135], v[198:201], v[44:47]
	v_mfma_f32_16x16x32_bf16 v[40:43], v[140:143], v[198:201], v[40:43]
	v_mfma_f32_16x16x32_bf16 v[28:31], v[132:135], v[206:209], v[28:31]
	v_mfma_f32_16x16x32_bf16 v[24:27], v[140:143], v[206:209], v[24:27]
	v_mfma_f32_16x16x32_bf16 v[12:15], v[132:135], v[214:217], v[12:15]
	v_mfma_f32_16x16x32_bf16 v[8:11], v[140:143], v[214:217], v[8:11]
	s_setprio 0
	s_setprio 1
	v_mfma_f32_16x16x32_bf16 v[52:55], v[160:163], v[186:189], 0
	v_mfma_f32_16x16x32_bf16 v[48:51], v[168:171], v[186:189], 0
	v_mfma_f32_16x16x32_bf16 v[36:39], v[160:163], v[194:197], 0
	v_mfma_f32_16x16x32_bf16 v[32:35], v[168:171], v[194:197], 0
	v_mfma_f32_16x16x32_bf16 v[20:23], v[160:163], v[202:205], 0
	v_mfma_f32_16x16x32_bf16 v[16:19], v[168:171], v[202:205], 0
	v_mfma_f32_16x16x32_bf16 v[4:7], v[160:163], v[210:213], 0
	v_mfma_f32_16x16x32_bf16 v[0:3], v[168:171], v[210:213], 0
	v_mfma_f32_16x16x32_bf16 v[52:55], v[164:167], v[190:193], v[52:55]
	v_mfma_f32_16x16x32_bf16 v[48:51], v[172:175], v[190:193], v[48:51]
	v_mfma_f32_16x16x32_bf16 v[36:39], v[164:167], v[198:201], v[36:39]
	v_mfma_f32_16x16x32_bf16 v[32:35], v[172:175], v[198:201], v[32:35]
	v_mfma_f32_16x16x32_bf16 v[20:23], v[164:167], v[206:209], v[20:23]
	v_mfma_f32_16x16x32_bf16 v[16:19], v[172:175], v[206:209], v[16:19]
	v_mfma_f32_16x16x32_bf16 v[4:7], v[164:167], v[214:217], v[4:7]
	v_mfma_f32_16x16x32_bf16 v[0:3], v[172:175], v[214:217], v[0:3]
	s_setprio 0
	s_barrier
	s_add_i32 s78, 0, 0x18000
	s_add_i32 s79, 0, 0x1c000
	v_add_u32_e32 v140, s78, v181
	v_add_u32_e32 v172, s79, v181
	ds_read_b128 v[128:131], v140
	ds_read_b128 v[132:135], v140 offset:1024
	ds_read_b128 v[136:139], v140 offset:2048
	ds_read_b128 v[140:143], v140 offset:3072
	ds_read_b128 v[160:163], v172
	ds_read_b128 v[164:167], v172 offset:1024
	ds_read_b128 v[168:171], v172 offset:2048
	ds_read_b128 v[172:175], v172 offset:3072
	s_add_u32 s38, s38, 0xb0000
	s_addc_u32 s39, s39, 0
	s_mov_b32 m0, s53
	v_lshl_add_u64 v[226:227], s[38:39], 0, v[144:145]
	ds_read_b128 v[186:189], v184 offset:32768
	ds_read_b128 v[190:193], v184 offset:33792
	ds_read_b128 v[194:197], v184 offset:34816
	ds_read_b128 v[198:201], v184 offset:35840
	ds_read_b128 v[202:205], v184 offset:36864
	ds_read_b128 v[206:209], v184 offset:37888
	ds_read_b128 v[210:213], v184 offset:38912
	ds_read_b128 v[214:217], v184 offset:39936
	global_load_lds_dwordx4 v[226:227], off
	v_lshl_add_u64 v[226:227], s[38:39], 0, v[148:149]
	s_mov_b32 m0, s54
	s_nop 0
	global_load_lds_dwordx4 v[226:227], off
	s_waitcnt vmcnt(8)
	s_waitcnt lgkmcnt(0)
	s_barrier
	s_setprio 1
	s_waitcnt lgkmcnt(0)
	v_mfma_f32_16x16x32_bf16 v[124:127], v[128:131], v[186:189], v[124:127]
	v_mfma_f32_16x16x32_bf16 v[120:123], v[136:139], v[186:189], v[120:123]
	v_mfma_f32_16x16x32_bf16 v[108:111], v[128:131], v[194:197], v[108:111]
	v_mfma_f32_16x16x32_bf16 v[104:107], v[136:139], v[194:197], v[104:107]
	v_mfma_f32_16x16x32_bf16 v[92:95], v[128:131], v[202:205], v[92:95]
	v_mfma_f32_16x16x32_bf16 v[88:91], v[136:139], v[202:205], v[88:91]
	v_mfma_f32_16x16x32_bf16 v[76:79], v[128:131], v[210:213], v[76:79]
	v_mfma_f32_16x16x32_bf16 v[72:75], v[136:139], v[210:213], v[72:75]
	v_mfma_f32_16x16x32_bf16 v[124:127], v[132:135], v[190:193], v[124:127]
	v_mfma_f32_16x16x32_bf16 v[120:123], v[140:143], v[190:193], v[120:123]
	v_mfma_f32_16x16x32_bf16 v[108:111], v[132:135], v[198:201], v[108:111]
	v_mfma_f32_16x16x32_bf16 v[104:107], v[140:143], v[198:201], v[104:107]
	v_mfma_f32_16x16x32_bf16 v[92:95], v[132:135], v[206:209], v[92:95]
	v_mfma_f32_16x16x32_bf16 v[88:91], v[140:143], v[206:209], v[88:91]
	v_mfma_f32_16x16x32_bf16 v[76:79], v[132:135], v[214:217], v[76:79]
	v_mfma_f32_16x16x32_bf16 v[72:75], v[140:143], v[214:217], v[72:75]
	s_setprio 0
	s_setprio 1
	v_mfma_f32_16x16x32_bf16 v[116:119], v[160:163], v[186:189], v[116:119]
	v_mfma_f32_16x16x32_bf16 v[112:115], v[168:171], v[186:189], v[112:115]
	v_mfma_f32_16x16x32_bf16 v[100:103], v[160:163], v[194:197], v[100:103]
	v_mfma_f32_16x16x32_bf16 v[96:99], v[168:171], v[194:197], v[96:99]
	v_mfma_f32_16x16x32_bf16 v[84:87], v[160:163], v[202:205], v[84:87]
	v_mfma_f32_16x16x32_bf16 v[80:83], v[168:171], v[202:205], v[80:83]
	v_mfma_f32_16x16x32_bf16 v[68:71], v[160:163], v[210:213], v[68:71]
	v_mfma_f32_16x16x32_bf16 v[64:67], v[168:171], v[210:213], v[64:67]
	v_mfma_f32_16x16x32_bf16 v[116:119], v[164:167], v[190:193], v[116:119]
	v_mfma_f32_16x16x32_bf16 v[112:115], v[172:175], v[190:193], v[112:115]
	v_mfma_f32_16x16x32_bf16 v[100:103], v[164:167], v[198:201], v[100:103]
	v_mfma_f32_16x16x32_bf16 v[96:99], v[172:175], v[198:201], v[96:99]
	v_mfma_f32_16x16x32_bf16 v[84:87], v[164:167], v[206:209], v[84:87]
	v_mfma_f32_16x16x32_bf16 v[80:83], v[172:175], v[206:209], v[80:83]
	v_mfma_f32_16x16x32_bf16 v[68:71], v[164:167], v[214:217], v[68:71]
	v_mfma_f32_16x16x32_bf16 v[64:67], v[172:175], v[214:217], v[64:67]
	s_setprio 0
	s_barrier
; #define PG8_STAGE(bufoff, gbase, voff) do { _Pragma("unroll") for (int _i = 0; _i < 2; ++_i) \
;         __builtin_amdgcn_global_load_lds((const unsigned*)((const char*)(gbase) + (voff)[_i]), (LAS unsigned*)(lds + (bufoff) + ldsw + _i * 8192), 16, 0, 0); } while (0)
; #define PG8_LDA(dst, b, h) do { _Pragma("unroll") for (int m = 0; m < 4; ++m) _Pragma("unroll") for (int k = 0; k < 2; ++k) dst[m][k] = *(const LAS bf16x8*)(lds + PG8_SA(b, h) + aoff + m * 2048 + k * 1024); } while (0)
; #define PG8_LDB(dst, b, h) do { _Pragma("unroll") for (int n = 0; n < 2; ++n) _Pragma("unroll") for (int k = 0; k < 2; ++k) dst[n][k] = *(const LAS bf16x8*)(lds + PG8_SB(b, h) + boff + n * 2048 + k * 1024); } while (0)
; #define PG8_WAIT_V(n) asm volatile("s_waitcnt vmcnt(" #n ")" ::: "memory")
; #define PG8_WAIT_L(n) asm volatile("s_waitcnt lgkmcnt(" #n ")" ::: "memory")
; template <class Epi>
; __device__ __forceinline__ void gemm_phase(LAS unsigned char* lds, const Gemm g, const StaticOrder& S, const Epi& E) {
;     ...
;         for (int t = 0; t < nt; t += 2) {
;             const bool last = (t == nt - 2);
;             const char* a1 = cA + (size_t)(t + 1) * kstep;
;             const char* a2 = last ? nA : cA + (size_t)(t + 2) * kstep; const char* b2 = last ? nB : cB + (size_t)(t + 2) * kstep;
;             const char* a3 = a2 + kstep; const char* b3 = b2 + kstep;
;             PG8_LDB(B0, 0, 0); PG8_LDB(B1, 0, 1); PG8_SCHED; PG8_LDA(At, 0, 0); PG8_STAGE(PG8_SA(1, 1), a1 + hstepA, voffA);
;             PG8_WAIT_V(8); PG8_WAIT_L(0); PG8_BAR; PG8_MMA(0, 0, At, B0); PG8_MMA(0, 1, At, B1); PG8_BAR; PG8_SCHED;
;             PG8_LDA(At, 0, 1); PG8_STAGE(PG8_SB(0, 0), b2, voffB); PG8_STAGE(PG8_SB(0, 1), b2 + hstepB, voffB); PG8_STAGE(PG8_SA(0, 0), a2, voffA);
;             PG8_WAIT_V(8); PG8_WAIT_L(0); PG8_BAR; PG8_MMA(1, 0, At, B0); PG8_MMA(1, 1, At, B1); PG8_BAR; PG8_SCHED;
;             PG8_LDB(B0, 1, 0); PG8_LDB(B1, 1, 1); PG8_SCHED; PG8_LDA(At, 1, 0); PG8_STAGE(PG8_SA(0, 1), a2 + hstepA, voffA);
;             PG8_WAIT_V(8); PG8_WAIT_L(0); PG8_BAR; PG8_MMA(0, 0, At, B0); PG8_MMA(0, 1, At, B1); PG8_BAR; PG8_SCHED;
;             PG8_LDA(At, 1, 1); PG8_STAGE(PG8_SB(1, 0), b3, voffB); PG8_STAGE(PG8_SB(1, 1), b3 + hstepB, voffB); PG8_STAGE(PG8_SA(1, 0), a3, voffA);
;             PG8_WAIT_V(8); PG8_WAIT_L(0); PG8_BAR; PG8_MMA(1, 0, At, B0); PG8_MMA(1, 1, At, B1); PG8_BAR; PG8_SCHED;
	s_add_i32 s38, s78, s42
	v_lshl_add_u64 v[178:179], v[178:179], 0, s[16:17]
	s_mov_b32 m0, s38
	ds_read_b128 v[186:189], v184 offset:49152
	ds_read_b128 v[190:193], v184 offset:50176
	ds_read_b128 v[194:197], v184 offset:51200
	ds_read_b128 v[198:201], v184 offset:52224
	ds_read_b128 v[202:205], v184 offset:53248
	ds_read_b128 v[206:209], v184 offset:54272
	ds_read_b128 v[210:213], v184 offset:55296
	ds_read_b128 v[214:217], v184 offset:56320
	global_load_lds_dwordx4 v[178:179], off
	s_add_i32 m0, s38, 0x2000
	s_add_u32 s34, s34, 0xb0080
	v_lshl_add_u64 v[178:179], v[218:219], 0, s[16:17]
	s_addc_u32 s35, s35, 0
	s_add_i32 s38, s79, s42
	global_load_lds_dwordx4 v[178:179], off
	v_lshl_add_u64 v[178:179], s[34:35], 0, v[146:147]
	s_mov_b32 m0, s38
	s_nop 0
	global_load_lds_dwordx4 v[178:179], off
	v_lshl_add_u64 v[178:179], s[34:35], 0, v[150:151]
	s_add_i32 m0, s38, 0x2000
	s_nop 0
	global_load_lds_dwordx4 v[178:179], off
	v_lshl_add_u64 v[178:179], v[220:221], 0, s[16:17]
	s_mov_b32 m0, s62
	s_nop 0
	global_load_lds_dwordx4 v[178:179], off
	v_lshl_add_u64 v[178:179], v[222:223], 0, s[16:17]
	s_mov_b32 m0, s63
	s_nop 0
	global_load_lds_dwordx4 v[178:179], off
	s_waitcnt vmcnt(8)
	s_waitcnt lgkmcnt(0)
	s_barrier
	s_setprio 1
	s_waitcnt lgkmcnt(0)
	v_mfma_f32_16x16x32_bf16 v[60:63], v[128:131], v[186:189], v[60:63]
	v_mfma_f32_16x16x32_bf16 v[56:59], v[136:139], v[186:189], v[56:59]
	v_mfma_f32_16x16x32_bf16 v[44:47], v[128:131], v[194:197], v[44:47]
	v_mfma_f32_16x16x32_bf16 v[40:43], v[136:139], v[194:197], v[40:43]
	v_mfma_f32_16x16x32_bf16 v[28:31], v[128:131], v[202:205], v[28:31]
	v_mfma_f32_16x16x32_bf16 v[24:27], v[136:139], v[202:205], v[24:27]
	v_mfma_f32_16x16x32_bf16 v[12:15], v[128:131], v[210:213], v[12:15]
	v_mfma_f32_16x16x32_bf16 v[8:11], v[136:139], v[210:213], v[8:11]
	v_mfma_f32_16x16x32_bf16 v[60:63], v[132:135], v[190:193], v[60:63]
	v_mfma_f32_16x16x32_bf16 v[56:59], v[140:143], v[190:193], v[56:59]
	v_mfma_f32_16x16x32_bf16 v[44:47], v[132:135], v[198:201], v[44:47]
	v_mfma_f32_16x16x32_bf16 v[40:43], v[140:143], v[198:201], v[40:43]
	v_mfma_f32_16x16x32_bf16 v[28:31], v[132:135], v[206:209], v[28:31]
	v_mfma_f32_16x16x32_bf16 v[24:27], v[140:143], v[206:209], v[24:27]
	v_mfma_f32_16x16x32_bf16 v[12:15], v[132:135], v[214:217], v[12:15]
	v_mfma_f32_16x16x32_bf16 v[8:11], v[140:143], v[214:217], v[8:11]
	s_setprio 0
	s_setprio 1
	v_mfma_f32_16x16x32_bf16 v[52:55], v[160:163], v[186:189], v[52:55]
	v_mfma_f32_16x16x32_bf16 v[48:51], v[168:171], v[186:189], v[48:51]
	v_mfma_f32_16x16x32_bf16 v[36:39], v[160:163], v[194:197], v[36:39]
	v_mfma_f32_16x16x32_bf16 v[32:35], v[168:171], v[194:197], v[32:35]
	v_mfma_f32_16x16x32_bf16 v[20:23], v[160:163], v[202:205], v[20:23]
	v_mfma_f32_16x16x32_bf16 v[16:19], v[168:171], v[202:205], v[16:19]
	v_mfma_f32_16x16x32_bf16 v[4:7], v[160:163], v[210:213], v[4:7]
	v_mfma_f32_16x16x32_bf16 v[0:3], v[168:171], v[210:213], v[0:3]
	v_mfma_f32_16x16x32_bf16 v[52:55], v[164:167], v[190:193], v[52:55]
	v_mfma_f32_16x16x32_bf16 v[48:51], v[172:175], v[190:193], v[48:51]
	v_mfma_f32_16x16x32_bf16 v[36:39], v[164:167], v[198:201], v[36:39]
	v_mfma_f32_16x16x32_bf16 v[32:35], v[172:175], v[198:201], v[32:35]
	v_mfma_f32_16x16x32_bf16 v[20:23], v[164:167], v[206:209], v[20:23]
	v_mfma_f32_16x16x32_bf16 v[16:19], v[172:175], v[206:209], v[16:19]
	v_mfma_f32_16x16x32_bf16 v[4:7], v[164:167], v[214:217], v[4:7]
	v_mfma_f32_16x16x32_bf16 v[0:3], v[172:175], v[214:217], v[0:3]
	s_setprio 0
	s_barrier
	s_add_i32 s77, s77, 2
	s_add_u32 s0, s0, 0x100
	s_addc_u32 s1, s1, 0
	s_add_u32 s75, s75, 0x100
	s_addc_u32 s76, s76, 0
	s_cmp_gt_u32 s77, 41

; #define PG8_STAGE(bufoff, gbase, voff) do { _Pragma("unroll") for (int _i = 0; _i < 2; ++_i) \
;         __builtin_amdgcn_global_load_lds((const unsigned*)((const char*)(gbase) + (voff)[_i]), (LAS unsigned*)(lds + (bufoff) + ldsw + _i * 8192), 16, 0, 0); } while (0)
; #define PG8_LDA(dst, b, h) do { _Pragma("unroll") for (int m = 0; m < 4; ++m) _Pragma("unroll") for (int k = 0; k < 2; ++k) dst[m][k] = *(const LAS bf16x8*)(lds + PG8_SA(b, h) + aoff + m * 2048 + k * 1024); } while (0)
; #define PG8_LDB(dst, b, h) do { _Pragma("unroll") for (int n = 0; n < 2; ++n) _Pragma("unroll") for (int k = 0; k < 2; ++k) dst[n][k] = *(const LAS bf16x8*)(lds + PG8_SB(b, h) + boff + n * 2048 + k * 1024); } while (0)
; #define PG8_MMA(ai, bj, At, Bt) do { __builtin_amdgcn_s_setprio(1); _Pragma("unroll") for (int m = 0; m < 4; ++m) _Pragma("unroll") for (int n = 0; n < 2; ++n) _Pragma("unroll") for (int k = 0; k < 2; ++k) \
;         acc[ai][bj][m][n] = __builtin_amdgcn_mfma_f32_16x16x32_bf16(Bt[n][k], At[m][k], acc[ai][bj][m][n], 0, 0, 0); __builtin_amdgcn_s_setprio(0); } while (0)
; #define PG8_WAIT_V(n) asm volatile("s_waitcnt vmcnt(" #n ")" ::: "memory")
; template <class Epi>
; __device__ __forceinline__ void gemm_phase(LAS unsigned char* lds, const Gemm g, const StaticOrder& S, const Epi& E) {
;     ...
;         const char* nA = has_next ? (const char*)g.A + (size_t)nxt.pm * tstepA : cA; const char* nB = has_next ? (const char*)g.Bt + (size_t)nxt.pn * tstepB : cB;
; #pragma nounroll
;         for (int t = 0; t < nt; t += 2) {
;             const bool last = (t == nt - 2);
;             const char* a1 = cA + (size_t)(t + 1) * kstep;
;             const char* a2 = last ? nA : cA + (size_t)(t + 2) * kstep; const char* b2 = last ? nB : cB + (size_t)(t + 2) * kstep;
;             const char* a3 = a2 + kstep; const char* b3 = b2 + kstep;
;             PG8_LDB(B0, 0, 0); PG8_LDB(B1, 0, 1); PG8_SCHED; PG8_LDA(At, 0, 0); PG8_STAGE(PG8_SA(1, 1), a1 + hstepA, voffA);
;             PG8_WAIT_V(8); PG8_WAIT_L(0); PG8_BAR; PG8_MMA(0, 0, At, B0); PG8_MMA(0, 1, At, B1); PG8_BAR; PG8_SCHED;
;             PG8_LDA(At, 0, 1); PG8_STAGE(PG8_SB(0, 0), b2, voffB); PG8_STAGE(PG8_SB(0, 1), b2 + hstepB, voffB); PG8_STAGE(PG8_SA(0, 0), a2, voffA);
;             PG8_WAIT_V(8); PG8_WAIT_L(0); PG8_BAR; PG8_MMA(1, 0, At, B0); PG8_MMA(1, 1, At, B1); PG8_BAR; PG8_SCHED;
.LBB0_888:
	s_ashr_i32 s43, s42, 31
	s_lshl_b64 s[52:53], s[42:43], 19
	s_add_u32 s52, s30, s52
	s_addc_u32 s53, s31, s53
	s_and_b64 s[54:55], s[4:5], exec
	s_cselect_b32 s7, s53, s57
	s_cselect_b32 s9, s52, s56
	s_ashr_i32 s39, s38, 31
	s_lshl_b64 s[54:55], s[38:39], 19
	s_add_u32 s54, s3, s54
	s_addc_u32 s55, s33, s55
	s_and_b64 s[64:65], s[4:5], exec
	s_cselect_b32 s39, s55, s63
	s_cselect_b32 s43, s54, s62
	s_add_u32 s56, s56, 0x40080
	s_addc_u32 s57, s57, 0
	s_add_u32 s83, s62, 0x100
	s_addc_u32 s84, s63, 0
	s_mov_b32 s85, -2
	s_waitcnt lgkmcnt(0)
	s_waitcnt vmcnt(0)
	ds_read_b128 v[40:43], v208
	ds_read_b128 v[44:47], v208 offset:1024
	ds_read_b128 v[56:59], v208 offset:2048
	ds_read_b128 v[60:63], v208 offset:3072
	ds_read_b128 v[144:147], v209
	ds_read_b128 v[148:151], v209 offset:1024
	ds_read_b128 v[152:155], v209 offset:2048
	ds_read_b128 v[156:159], v209 offset:3072
	s_add_u32 s62, s56, 0xfffc0080
	s_addc_u32 s63, s57, -1
	s_cmp_eq_u32 s85, 12
	s_cselect_b32 s65, s7, s63
	s_cselect_b32 s64, s9, s62
	s_cselect_b32 s63, s39, s84
	s_cselect_b32 s62, s43, s83
	v_lshl_add_u64 v[218:219], s[56:57], 0, v[178:179]
	s_add_i32 m0, s69, 0xc000
	ds_read_b128 v[160:163], v210
	ds_read_b128 v[164:167], v210 offset:1024
	ds_read_b128 v[186:189], v210 offset:2048
	ds_read_b128 v[190:193], v210 offset:3072
	ds_read_b128 v[194:197], v210 offset:4096
	ds_read_b128 v[198:201], v210 offset:5120
	ds_read_b128 v[202:205], v210 offset:6144
	ds_read_b128 v[214:217], v210 offset:7168
	global_load_lds_dwordx4 v[218:219], off
	v_lshl_add_u64 v[218:219], s[56:57], 0, v[180:181]
	s_add_i32 m0, s69, 0xe000
	s_nop 0
	global_load_lds_dwordx4 v[218:219], off
	s_waitcnt vmcnt(8)
	s_waitcnt lgkmcnt(0)
	s_barrier
	s_setprio 1
	s_waitcnt lgkmcnt(0)
	v_mfma_f32_16x16x32_bf16 v[140:143], v[40:43], v[160:163], 0
	v_mfma_f32_16x16x32_bf16 v[136:139], v[56:59], v[160:163], 0
	v_mfma_f32_16x16x32_bf16 v[124:127], v[40:43], v[186:189], 0
	v_mfma_f32_16x16x32_bf16 v[120:123], v[56:59], v[186:189], 0
	v_mfma_f32_16x16x32_bf16 v[108:111], v[40:43], v[194:197], 0
	v_mfma_f32_16x16x32_bf16 v[104:107], v[56:59], v[194:197], 0
	v_mfma_f32_16x16x32_bf16 v[92:95], v[40:43], v[202:205], 0
	v_mfma_f32_16x16x32_bf16 v[88:91], v[56:59], v[202:205], 0
	v_mfma_f32_16x16x32_bf16 v[140:143], v[44:47], v[164:167], v[140:143]
	v_mfma_f32_16x16x32_bf16 v[136:139], v[60:63], v[164:167], v[136:139]
	v_mfma_f32_16x16x32_bf16 v[124:127], v[44:47], v[190:193], v[124:127]
	v_mfma_f32_16x16x32_bf16 v[120:123], v[60:63], v[190:193], v[120:123]
	v_mfma_f32_16x16x32_bf16 v[108:111], v[44:47], v[198:201], v[108:111]
	v_mfma_f32_16x16x32_bf16 v[104:107], v[60:63], v[198:201], v[104:107]
	v_mfma_f32_16x16x32_bf16 v[92:95], v[44:47], v[214:217], v[92:95]
	v_mfma_f32_16x16x32_bf16 v[88:91], v[60:63], v[214:217], v[88:91]
	s_setprio 0
	s_setprio 1
	v_mfma_f32_16x16x32_bf16 v[132:135], v[144:147], v[160:163], 0
	v_mfma_f32_16x16x32_bf16 v[128:131], v[152:155], v[160:163], 0
	v_mfma_f32_16x16x32_bf16 v[116:119], v[144:147], v[186:189], 0
	v_mfma_f32_16x16x32_bf16 v[112:115], v[152:155], v[186:189], 0
	v_mfma_f32_16x16x32_bf16 v[100:103], v[144:147], v[194:197], 0
	v_mfma_f32_16x16x32_bf16 v[96:99], v[152:155], v[194:197], 0
	v_mfma_f32_16x16x32_bf16 v[84:87], v[144:147], v[202:205], 0
	v_mfma_f32_16x16x32_bf16 v[80:83], v[152:155], v[202:205], 0
	v_mfma_f32_16x16x32_bf16 v[132:135], v[148:151], v[164:167], v[132:135]
	v_mfma_f32_16x16x32_bf16 v[128:131], v[156:159], v[164:167], v[128:131]
	v_mfma_f32_16x16x32_bf16 v[116:119], v[148:151], v[190:193], v[116:119]
	v_mfma_f32_16x16x32_bf16 v[112:115], v[156:159], v[190:193], v[112:115]
	v_mfma_f32_16x16x32_bf16 v[100:103], v[148:151], v[198:201], v[100:103]
	v_mfma_f32_16x16x32_bf16 v[96:99], v[156:159], v[198:201], v[96:99]
	v_mfma_f32_16x16x32_bf16 v[84:87], v[148:151], v[214:217], v[84:87]
	v_mfma_f32_16x16x32_bf16 v[80:83], v[156:159], v[214:217], v[80:83]
	s_setprio 0
	s_barrier
	s_add_i32 s86, s81, s68
	v_lshl_add_u64 v[218:219], s[62:63], 0, v[170:171]
	s_mov_b32 m0, s86
	ds_read_b128 v[160:163], v210 offset:16384
	ds_read_b128 v[164:167], v210 offset:17408
	ds_read_b128 v[186:189], v210 offset:18432
	ds_read_b128 v[190:193], v210 offset:19456
	ds_read_b128 v[194:197], v210 offset:20480
	ds_read_b128 v[198:201], v210 offset:21504
	ds_read_b128 v[202:205], v210 offset:22528
	ds_read_b128 v[214:217], v210 offset:23552
	global_load_lds_dwordx4 v[218:219], off
	s_add_i32 m0, s86, 0x2000
	s_add_u32 s86, s62, 0x40000
	v_lshl_add_u64 v[220:221], s[62:63], 0, v[174:175]
	s_addc_u32 s87, s63, 0
	s_add_i32 s88, s82, s68
	global_load_lds_dwordx4 v[220:221], off
	v_lshl_add_u64 v[222:223], s[86:87], 0, v[170:171]
	s_mov_b32 m0, s88
	v_lshl_add_u64 v[226:227], s[64:65], 0, v[172:173]
	global_load_lds_dwordx4 v[222:223], off
	v_lshl_add_u64 v[222:223], s[86:87], 0, v[174:175]
	s_add_i32 m0, s88, 0x2000
	s_nop 0
	global_load_lds_dwordx4 v[222:223], off
	v_lshl_add_u64 v[222:223], s[64:65], 0, v[168:169]
	s_mov_b32 m0, s69
	s_nop 0
	global_load_lds_dwordx4 v[222:223], off
	s_mov_b32 m0, s70
	s_nop 0
	global_load_lds_dwordx4 v[226:227], off
	s_waitcnt vmcnt(8)
	s_waitcnt lgkmcnt(0)
	s_barrier
; #define PG8_STAGE(bufoff, gbase, voff) do { _Pragma("unroll") for (int _i = 0; _i < 2; ++_i) \
;         __builtin_amdgcn_global_load_lds((const unsigned*)((const char*)(gbase) + (voff)[_i]), (LAS unsigned*)(lds + (bufoff) + ldsw + _i * 8192), 16, 0, 0); } while (0)
; #define PG8_LDA(dst, b, h) do { _Pragma("unroll") for (int m = 0; m < 4; ++m) _Pragma("unroll") for (int k = 0; k < 2; ++k) dst[m][k] = *(const LAS bf16x8*)(lds + PG8_SA(b, h) + aoff + m * 2048 + k * 1024); } while (0)
; #define PG8_LDB(dst, b, h) do { _Pragma("unroll") for (int n = 0; n < 2; ++n) _Pragma("unroll") for (int k = 0; k < 2; ++k) dst[n][k] = *(const LAS bf16x8*)(lds + PG8_SB(b, h) + boff + n * 2048 + k * 1024); } while (0)
; #define PG8_MMA(ai, bj, At, Bt) do { __builtin_amdgcn_s_setprio(1); _Pragma("unroll") for (int m = 0; m < 4; ++m) _Pragma("unroll") for (int n = 0; n < 2; ++n) _Pragma("unroll") for (int k = 0; k < 2; ++k) \
;         acc[ai][bj][m][n] = __builtin_amdgcn_mfma_f32_16x16x32_bf16(Bt[n][k], At[m][k], acc[ai][bj][m][n], 0, 0, 0); __builtin_amdgcn_s_setprio(0); } while (0)
; #define PG8_WAIT_V(n) asm volatile("s_waitcnt vmcnt(" #n ")" ::: "memory")
; #define PG8_WAIT_L(n) asm volatile("s_waitcnt lgkmcnt(" #n ")" ::: "memory")
; #define PG8_BAR __builtin_amdgcn_s_barrier()
; #define PG8_SCHED __builtin_amdgcn_sched_barrier(0)
; template <class Epi>
; __device__ __forceinline__ void gemm_phase(LAS unsigned char* lds, const Gemm g, const StaticOrder& S, const Epi& E) {
;     ...
;             PG8_WAIT_V(8); PG8_WAIT_L(0); PG8_BAR; PG8_MMA(1, 0, At, B0); PG8_MMA(1, 1, At, B1); PG8_BAR; PG8_SCHED;
;             PG8_LDB(B0, 1, 0); PG8_LDB(B1, 1, 1); PG8_SCHED; PG8_LDA(At, 1, 0); PG8_STAGE(PG8_SA(0, 1), a2 + hstepA, voffA);
;             PG8_WAIT_V(8); PG8_WAIT_L(0); PG8_BAR; PG8_MMA(0, 0, At, B0); PG8_MMA(0, 1, At, B1); PG8_BAR; PG8_SCHED;
;             PG8_LDA(At, 1, 1); PG8_STAGE(PG8_SB(1, 0), b3, voffB); PG8_STAGE(PG8_SB(1, 1), b3 + hstepB, voffB); PG8_STAGE(PG8_SA(1, 0), a3, voffA);
	s_setprio 1
	s_waitcnt lgkmcnt(0)
	v_mfma_f32_16x16x32_bf16 v[76:79], v[40:43], v[160:163], 0
	v_mfma_f32_16x16x32_bf16 v[72:75], v[56:59], v[160:163], 0
	v_mfma_f32_16x16x32_bf16 v[52:55], v[40:43], v[186:189], 0
	v_mfma_f32_16x16x32_bf16 v[48:51], v[56:59], v[186:189], 0
	v_mfma_f32_16x16x32_bf16 v[28:31], v[40:43], v[194:197], 0
	v_mfma_f32_16x16x32_bf16 v[24:27], v[56:59], v[194:197], 0
	v_mfma_f32_16x16x32_bf16 v[12:15], v[40:43], v[202:205], 0
	v_mfma_f32_16x16x32_bf16 v[8:11], v[56:59], v[202:205], 0
	v_mfma_f32_16x16x32_bf16 v[76:79], v[44:47], v[164:167], v[76:79]
	v_mfma_f32_16x16x32_bf16 v[72:75], v[60:63], v[164:167], v[72:75]
	v_mfma_f32_16x16x32_bf16 v[52:55], v[44:47], v[190:193], v[52:55]
	v_mfma_f32_16x16x32_bf16 v[48:51], v[60:63], v[190:193], v[48:51]
	v_mfma_f32_16x16x32_bf16 v[28:31], v[44:47], v[198:201], v[28:31]
	v_mfma_f32_16x16x32_bf16 v[24:27], v[60:63], v[198:201], v[24:27]
	v_mfma_f32_16x16x32_bf16 v[12:15], v[44:47], v[214:217], v[12:15]
	v_mfma_f32_16x16x32_bf16 v[8:11], v[60:63], v[214:217], v[8:11]
	s_setprio 0
	s_setprio 1
	v_mfma_f32_16x16x32_bf16 v[36:39], v[144:147], v[186:189], 0
	v_mfma_f32_16x16x32_bf16 v[32:35], v[152:155], v[186:189], 0
	v_mfma_f32_16x16x32_bf16 v[20:23], v[144:147], v[194:197], 0
	v_mfma_f32_16x16x32_bf16 v[16:19], v[152:155], v[194:197], 0
	v_mfma_f32_16x16x32_bf16 v[4:7], v[144:147], v[202:205], 0
	v_mfma_f32_16x16x32_bf16 v[0:3], v[152:155], v[202:205], 0
	v_mfma_f32_16x16x32_bf16 v[40:43], v[144:147], v[160:163], 0
	v_mfma_f32_16x16x32_bf16 v[44:47], v[152:155], v[160:163], 0
	v_mfma_f32_16x16x32_bf16 v[36:39], v[148:151], v[190:193], v[36:39]
	v_mfma_f32_16x16x32_bf16 v[32:35], v[156:159], v[190:193], v[32:35]
	v_mfma_f32_16x16x32_bf16 v[20:23], v[148:151], v[198:201], v[20:23]
	v_mfma_f32_16x16x32_bf16 v[16:19], v[156:159], v[198:201], v[16:19]
	v_mfma_f32_16x16x32_bf16 v[4:7], v[148:151], v[214:217], v[4:7]
	v_mfma_f32_16x16x32_bf16 v[0:3], v[156:159], v[214:217], v[0:3]
	v_mfma_f32_16x16x32_bf16 v[40:43], v[148:151], v[164:167], v[40:43]
	v_mfma_f32_16x16x32_bf16 v[44:47], v[156:159], v[164:167], v[44:47]
	s_setprio 0
	s_barrier
	s_add_i32 s86, 0, 0x18000
	s_add_i32 s87, 0, 0x1c000
	v_add_u32_e32 v68, s86, v207
	v_add_u32_e32 v156, s87, v207
	ds_read_b128 v[56:59], v68
	ds_read_b128 v[60:63], v68 offset:1024
	ds_read_b128 v[64:67], v68 offset:2048
	ds_read_b128 v[68:71], v68 offset:3072
	ds_read_b128 v[144:147], v156
	ds_read_b128 v[148:151], v156 offset:1024
	ds_read_b128 v[152:155], v156 offset:2048
	ds_read_b128 v[156:159], v156 offset:3072
	s_add_u32 s64, s64, 0x40000
	s_addc_u32 s65, s65, 0
	s_mov_b32 m0, s71
	v_lshl_add_u64 v[228:229], s[64:65], 0, v[168:169]
	ds_read_b128 v[160:163], v210 offset:32768
	ds_read_b128 v[164:167], v210 offset:33792
	ds_read_b128 v[186:189], v210 offset:34816
	ds_read_b128 v[190:193], v210 offset:35840
	ds_read_b128 v[194:197], v210 offset:36864
	ds_read_b128 v[198:201], v210 offset:37888
	ds_read_b128 v[202:205], v210 offset:38912
	ds_read_b128 v[214:217], v210 offset:39936
	global_load_lds_dwordx4 v[228:229], off
	v_lshl_add_u64 v[228:229], s[64:65], 0, v[172:173]
	s_mov_b32 m0, s72
	s_nop 0
	global_load_lds_dwordx4 v[228:229], off
	s_waitcnt vmcnt(8)
	s_waitcnt lgkmcnt(0)
	s_barrier
	s_setprio 1
	s_waitcnt lgkmcnt(0)
	v_mfma_f32_16x16x32_bf16 v[140:143], v[56:59], v[160:163], v[140:143]
	v_mfma_f32_16x16x32_bf16 v[136:139], v[64:67], v[160:163], v[136:139]
	v_mfma_f32_16x16x32_bf16 v[124:127], v[56:59], v[186:189], v[124:127]
	v_mfma_f32_16x16x32_bf16 v[120:123], v[64:67], v[186:189], v[120:123]
	v_mfma_f32_16x16x32_bf16 v[108:111], v[56:59], v[194:197], v[108:111]
	v_mfma_f32_16x16x32_bf16 v[104:107], v[64:67], v[194:197], v[104:107]
	v_mfma_f32_16x16x32_bf16 v[92:95], v[56:59], v[202:205], v[92:95]
	v_mfma_f32_16x16x32_bf16 v[88:91], v[64:67], v[202:205], v[88:91]
	v_mfma_f32_16x16x32_bf16 v[140:143], v[60:63], v[164:167], v[140:143]
	v_mfma_f32_16x16x32_bf16 v[136:139], v[68:71], v[164:167], v[136:139]
	v_mfma_f32_16x16x32_bf16 v[124:127], v[60:63], v[190:193], v[124:127]
	v_mfma_f32_16x16x32_bf16 v[120:123], v[68:71], v[190:193], v[120:123]
	v_mfma_f32_16x16x32_bf16 v[108:111], v[60:63], v[198:201], v[108:111]
	v_mfma_f32_16x16x32_bf16 v[104:107], v[68:71], v[198:201], v[104:107]
	v_mfma_f32_16x16x32_bf16 v[92:95], v[60:63], v[214:217], v[92:95]
	v_mfma_f32_16x16x32_bf16 v[88:91], v[68:71], v[214:217], v[88:91]
	s_setprio 0
	s_setprio 1
	v_mfma_f32_16x16x32_bf16 v[132:135], v[144:147], v[160:163], v[132:135]
	v_mfma_f32_16x16x32_bf16 v[128:131], v[152:155], v[160:163], v[128:131]
	v_mfma_f32_16x16x32_bf16 v[116:119], v[144:147], v[186:189], v[116:119]
	v_mfma_f32_16x16x32_bf16 v[112:115], v[152:155], v[186:189], v[112:115]
	v_mfma_f32_16x16x32_bf16 v[100:103], v[144:147], v[194:197], v[100:103]
	v_mfma_f32_16x16x32_bf16 v[96:99], v[152:155], v[194:197], v[96:99]
	v_mfma_f32_16x16x32_bf16 v[84:87], v[144:147], v[202:205], v[84:87]
	v_mfma_f32_16x16x32_bf16 v[80:83], v[152:155], v[202:205], v[80:83]
	v_mfma_f32_16x16x32_bf16 v[132:135], v[148:151], v[164:167], v[132:135]
	v_mfma_f32_16x16x32_bf16 v[128:131], v[156:159], v[164:167], v[128:131]
	v_mfma_f32_16x16x32_bf16 v[116:119], v[148:151], v[190:193], v[116:119]
	v_mfma_f32_16x16x32_bf16 v[112:115], v[156:159], v[190:193], v[112:115]
	v_mfma_f32_16x16x32_bf16 v[100:103], v[148:151], v[198:201], v[100:103]
	v_mfma_f32_16x16x32_bf16 v[96:99], v[156:159], v[198:201], v[96:99]
	v_mfma_f32_16x16x32_bf16 v[84:87], v[148:151], v[214:217], v[84:87]
	v_mfma_f32_16x16x32_bf16 v[80:83], v[156:159], v[214:217], v[80:83]
	s_setprio 0
	s_barrier
; #define PG8_STAGE(bufoff, gbase, voff) do { _Pragma("unroll") for (int _i = 0; _i < 2; ++_i) \
;         __builtin_amdgcn_global_load_lds((const unsigned*)((const char*)(gbase) + (voff)[_i]), (LAS unsigned*)(lds + (bufoff) + ldsw + _i * 8192), 16, 0, 0); } while (0)
; #define PG8_LDA(dst, b, h) do { _Pragma("unroll") for (int m = 0; m < 4; ++m) _Pragma("unroll") for (int k = 0; k < 2; ++k) dst[m][k] = *(const LAS bf16x8*)(lds + PG8_SA(b, h) + aoff + m * 2048 + k * 1024); } while (0)
; #define PG8_LDB(dst, b, h) do { _Pragma("unroll") for (int n = 0; n < 2; ++n) _Pragma("unroll") for (int k = 0; k < 2; ++k) dst[n][k] = *(const LAS bf16x8*)(lds + PG8_SB(b, h) + boff + n * 2048 + k * 1024); } while (0)
; #define PG8_WAIT_V(n) asm volatile("s_waitcnt vmcnt(" #n ")" ::: "memory")
; #define PG8_WAIT_L(n) asm volatile("s_waitcnt lgkmcnt(" #n ")" ::: "memory")
; template <class Epi>
; __device__ __forceinline__ void gemm_phase(LAS unsigned char* lds, const Gemm g, const StaticOrder& S, const Epi& E) {
;     ...
;         for (int t = 0; t < nt; t += 2) {
;             const bool last = (t == nt - 2);
;             const char* a1 = cA + (size_t)(t + 1) * kstep;
;             const char* a2 = last ? nA : cA + (size_t)(t + 2) * kstep; const char* b2 = last ? nB : cB + (size_t)(t + 2) * kstep;
;             const char* a3 = a2 + kstep; const char* b3 = b2 + kstep;
;             PG8_LDB(B0, 0, 0); PG8_LDB(B1, 0, 1); PG8_SCHED; PG8_LDA(At, 0, 0); PG8_STAGE(PG8_SA(1, 1), a1 + hstepA, voffA);
;             PG8_WAIT_V(8); PG8_WAIT_L(0); PG8_BAR; PG8_MMA(0, 0, At, B0); PG8_MMA(0, 1, At, B1); PG8_BAR; PG8_SCHED;
;             PG8_LDA(At, 0, 1); PG8_STAGE(PG8_SB(0, 0), b2, voffB); PG8_STAGE(PG8_SB(0, 1), b2 + hstepB, voffB); PG8_STAGE(PG8_SA(0, 0), a2, voffA);
;             PG8_WAIT_V(8); PG8_WAIT_L(0); PG8_BAR; PG8_MMA(1, 0, At, B0); PG8_MMA(1, 1, At, B1); PG8_BAR; PG8_SCHED;
;             PG8_LDB(B0, 1, 0); PG8_LDB(B1, 1, 1); PG8_SCHED; PG8_LDA(At, 1, 0); PG8_STAGE(PG8_SA(0, 1), a2 + hstepA, voffA);
;             PG8_WAIT_V(8); PG8_WAIT_L(0); PG8_BAR; PG8_MMA(0, 0, At, B0); PG8_MMA(0, 1, At, B1); PG8_BAR; PG8_SCHED;
;             PG8_LDA(At, 1, 1); PG8_STAGE(PG8_SB(1, 0), b3, voffB); PG8_STAGE(PG8_SB(1, 1), b3 + hstepB, voffB); PG8_STAGE(PG8_SA(1, 0), a3, voffA);
;             PG8_WAIT_V(8); PG8_WAIT_L(0); PG8_BAR; PG8_MMA(1, 0, At, B0); PG8_MMA(1, 1, At, B1); PG8_BAR; PG8_SCHED;
	s_add_i32 s64, s86, s68
	v_lshl_add_u64 v[218:219], v[218:219], 0, s[18:19]
	s_mov_b32 m0, s64
	ds_read_b128 v[160:163], v210 offset:49152
	ds_read_b128 v[164:167], v210 offset:50176
	ds_read_b128 v[186:189], v210 offset:51200
	ds_read_b128 v[190:193], v210 offset:52224
	ds_read_b128 v[194:197], v210 offset:53248
	ds_read_b128 v[198:201], v210 offset:54272
	ds_read_b128 v[202:205], v210 offset:55296
	ds_read_b128 v[214:217], v210 offset:56320
	global_load_lds_dwordx4 v[218:219], off
	s_add_i32 m0, s64, 0x2000
	s_add_u32 s62, s62, 0x40080
	v_lshl_add_u64 v[218:219], v[220:221], 0, s[18:19]
	s_addc_u32 s63, s63, 0
	s_add_i32 s64, s87, s68
	global_load_lds_dwordx4 v[218:219], off
	v_lshl_add_u64 v[218:219], s[62:63], 0, v[170:171]
	s_mov_b32 m0, s64
	s_nop 0
	global_load_lds_dwordx4 v[218:219], off
	v_lshl_add_u64 v[218:219], s[62:63], 0, v[174:175]
	s_add_i32 m0, s64, 0x2000
	s_nop 0
	global_load_lds_dwordx4 v[218:219], off
	v_lshl_add_u64 v[218:219], v[222:223], 0, s[18:19]
	s_mov_b32 m0, s76
	s_nop 0
	global_load_lds_dwordx4 v[218:219], off
	v_lshl_add_u64 v[218:219], v[226:227], 0, s[18:19]
	s_mov_b32 m0, s77
	s_nop 0
	global_load_lds_dwordx4 v[218:219], off
	s_waitcnt vmcnt(8)
	s_waitcnt lgkmcnt(0)
	s_barrier
	s_setprio 1
	s_waitcnt lgkmcnt(0)
	v_mfma_f32_16x16x32_bf16 v[76:79], v[56:59], v[160:163], v[76:79]
	v_mfma_f32_16x16x32_bf16 v[72:75], v[64:67], v[160:163], v[72:75]
	v_mfma_f32_16x16x32_bf16 v[52:55], v[56:59], v[186:189], v[52:55]
	v_mfma_f32_16x16x32_bf16 v[48:51], v[64:67], v[186:189], v[48:51]
	v_mfma_f32_16x16x32_bf16 v[28:31], v[56:59], v[194:197], v[28:31]
	v_mfma_f32_16x16x32_bf16 v[24:27], v[64:67], v[194:197], v[24:27]
	v_mfma_f32_16x16x32_bf16 v[12:15], v[56:59], v[202:205], v[12:15]
	v_mfma_f32_16x16x32_bf16 v[8:11], v[64:67], v[202:205], v[8:11]
	v_mfma_f32_16x16x32_bf16 v[76:79], v[60:63], v[164:167], v[76:79]
	v_mfma_f32_16x16x32_bf16 v[72:75], v[68:71], v[164:167], v[72:75]
	v_mfma_f32_16x16x32_bf16 v[52:55], v[60:63], v[190:193], v[52:55]
	v_mfma_f32_16x16x32_bf16 v[48:51], v[68:71], v[190:193], v[48:51]
	v_mfma_f32_16x16x32_bf16 v[28:31], v[60:63], v[198:201], v[28:31]
	v_mfma_f32_16x16x32_bf16 v[24:27], v[68:71], v[198:201], v[24:27]
	v_mfma_f32_16x16x32_bf16 v[12:15], v[60:63], v[214:217], v[12:15]
	v_mfma_f32_16x16x32_bf16 v[8:11], v[68:71], v[214:217], v[8:11]
	s_setprio 0
	s_setprio 1
	v_mfma_f32_16x16x32_bf16 v[40:43], v[144:147], v[160:163], v[40:43]
	v_mfma_f32_16x16x32_bf16 v[68:71], v[148:151], v[164:167], v[40:43]
	v_mfma_f32_16x16x32_bf16 v[40:43], v[152:155], v[160:163], v[44:47]
	v_mfma_f32_16x16x32_bf16 v[36:39], v[144:147], v[186:189], v[36:39]
	v_mfma_f32_16x16x32_bf16 v[32:35], v[152:155], v[186:189], v[32:35]
	v_mfma_f32_16x16x32_bf16 v[20:23], v[144:147], v[194:197], v[20:23]
	v_mfma_f32_16x16x32_bf16 v[16:19], v[152:155], v[194:197], v[16:19]
	v_mfma_f32_16x16x32_bf16 v[4:7], v[144:147], v[202:205], v[4:7]
	v_mfma_f32_16x16x32_bf16 v[0:3], v[152:155], v[202:205], v[0:3]
	v_mfma_f32_16x16x32_bf16 v[64:67], v[156:159], v[164:167], v[40:43]
	v_mfma_f32_16x16x32_bf16 v[36:39], v[148:151], v[190:193], v[36:39]
	v_mfma_f32_16x16x32_bf16 v[32:35], v[156:159], v[190:193], v[32:35]
	v_mfma_f32_16x16x32_bf16 v[20:23], v[148:151], v[198:201], v[20:23]
	v_mfma_f32_16x16x32_bf16 v[16:19], v[156:159], v[198:201], v[16:19]
	v_mfma_f32_16x16x32_bf16 v[4:7], v[148:151], v[214:217], v[4:7]
	v_mfma_f32_16x16x32_bf16 v[0:3], v[156:159], v[214:217], v[0:3]
	s_setprio 0
	s_barrier
	s_add_i32 s85, s85, 2
	s_add_u32 s56, s56, 0x100
	s_addc_u32 s57, s57, 0
	s_add_u32 s83, s83, 0x100
	s_addc_u32 s84, s84, 0
	s_cmp_gt_u32 s85, 13

; #define PG8_STAGE(bufoff, gbase, voff) do { _Pragma("unroll") for (int _i = 0; _i < 2; ++_i) \
;         __builtin_amdgcn_global_load_lds((const unsigned*)((const char*)(gbase) + (voff)[_i]), (LAS unsigned*)(lds + (bufoff) + ldsw + _i * 8192), 16, 0, 0); } while (0)
; #define PG8_LDA(dst, b, h) do { _Pragma("unroll") for (int m = 0; m < 4; ++m) _Pragma("unroll") for (int k = 0; k < 2; ++k) dst[m][k] = *(const LAS bf16x8*)(lds + PG8_SA(b, h) + aoff + m * 2048 + k * 1024); } while (0)
; #define PG8_LDB(dst, b, h) do { _Pragma("unroll") for (int n = 0; n < 2; ++n) _Pragma("unroll") for (int k = 0; k < 2; ++k) dst[n][k] = *(const LAS bf16x8*)(lds + PG8_SB(b, h) + boff + n * 2048 + k * 1024); } while (0)
; #define PG8_MMA(ai, bj, At, Bt) do { __builtin_amdgcn_s_setprio(1); _Pragma("unroll") for (int m = 0; m < 4; ++m) _Pragma("unroll") for (int n = 0; n < 2; ++n) _Pragma("unroll") for (int k = 0; k < 2; ++k) \
;         acc[ai][bj][m][n] = __builtin_amdgcn_mfma_f32_16x16x32_bf16(Bt[n][k], At[m][k], acc[ai][bj][m][n], 0, 0, 0); __builtin_amdgcn_s_setprio(0); } while (0)
; #define PG8_WAIT_V(n) asm volatile("s_waitcnt vmcnt(" #n ")" ::: "memory")
; template <class Epi>
; __device__ __forceinline__ void gemm_phase(LAS unsigned char* lds, const Gemm g, const StaticOrder& S, const Epi& E) {
;     ...
;         const char* nA = has_next ? (const char*)g.A + (size_t)nxt.pm * tstepA : cA; const char* nB = has_next ? (const char*)g.Bt + (size_t)nxt.pn * tstepB : cB;
; #pragma nounroll
;         for (int t = 0; t < nt; t += 2) {
;             const bool last = (t == nt - 2);
;             const char* a1 = cA + (size_t)(t + 1) * kstep;
;             const char* a2 = last ? nA : cA + (size_t)(t + 2) * kstep; const char* b2 = last ? nB : cB + (size_t)(t + 2) * kstep;
;             const char* a3 = a2 + kstep; const char* b3 = b2 + kstep;
;             PG8_LDB(B0, 0, 0); PG8_LDB(B1, 0, 1); PG8_SCHED; PG8_LDA(At, 0, 0); PG8_STAGE(PG8_SA(1, 1), a1 + hstepA, voffA);
;             PG8_WAIT_V(8); PG8_WAIT_L(0); PG8_BAR; PG8_MMA(0, 0, At, B0); PG8_MMA(0, 1, At, B1); PG8_BAR; PG8_SCHED;
;             PG8_LDA(At, 0, 1); PG8_STAGE(PG8_SB(0, 0), b2, voffB); PG8_STAGE(PG8_SB(0, 1), b2 + hstepB, voffB); PG8_STAGE(PG8_SA(0, 0), a2, voffA);
;             PG8_WAIT_V(8); PG8_WAIT_L(0); PG8_BAR; PG8_MMA(1, 0, At, B0); PG8_MMA(1, 1, At, B1); PG8_BAR; PG8_SCHED;
.LBB0_1017:
	s_ashr_i32 s35, s34, 31
	s_lshl_b64 s[38:39], s[34:35], 19
	s_add_u32 s38, s24, s38
	s_addc_u32 s39, s25, s39
	s_and_b64 s[42:43], s[4:5], exec
	s_cselect_b32 s7, s39, s55
	s_cselect_b32 s35, s38, s54
	s_ashr_i32 s23, s22, 31
	s_lshl_b64 s[42:43], s[22:23], 19
	s_add_u32 s42, s33, s42
	s_addc_u32 s43, s64, s43
	s_and_b64 s[62:63], s[4:5], exec
	s_cselect_b32 s23, s43, s57
	s_cselect_b32 s53, s42, s56
	s_add_u32 s54, s54, 0x40080
	s_addc_u32 s55, s55, 0
	s_add_u32 s83, s56, 0x100
	s_waitcnt vmcnt(0)
	s_addc_u32 s84, s57, 0
	s_mov_b32 s85, -2
	ds_read_b128 v[0:3], v230
	ds_read_b128 v[4:7], v230 offset:1024
	ds_read_b128 v[8:11], v230 offset:2048
	ds_read_b128 v[12:15], v230 offset:3072
	ds_read_b128 v[144:147], v231
	ds_read_b128 v[148:151], v231 offset:1024
	ds_read_b128 v[152:155], v231 offset:2048
	ds_read_b128 v[156:159], v231 offset:3072
	s_add_u32 s56, s54, 0xfffc0080
	s_addc_u32 s57, s55, -1
	s_cmp_eq_u32 s85, 12
	s_cselect_b32 s63, s7, s57
	s_cselect_b32 s62, s35, s56
	s_cselect_b32 s57, s23, s84
	s_cselect_b32 s56, s53, s83
	v_lshl_add_u64 v[212:213], s[54:55], 0, v[188:189]
	s_add_i32 m0, s68, 0xc000
	ds_read_b128 v[160:163], v232
	ds_read_b128 v[164:167], v232 offset:1024
	ds_read_b128 v[168:171], v232 offset:2048
	ds_read_b128 v[172:175], v232 offset:3072
	ds_read_b128 v[196:199], v232 offset:4096
	ds_read_b128 v[200:203], v232 offset:5120
	ds_read_b128 v[204:207], v232 offset:6144
	ds_read_b128 v[208:211], v232 offset:7168
	global_load_lds_dwordx4 v[212:213], off
	v_lshl_add_u64 v[212:213], s[54:55], 0, v[190:191]
	s_add_i32 m0, s68, 0xe000
	s_nop 0
	global_load_lds_dwordx4 v[212:213], off
	s_waitcnt vmcnt(8)
	s_waitcnt lgkmcnt(0)
	s_barrier
	s_setprio 1
	s_waitcnt lgkmcnt(0)
	v_mfma_f32_16x16x32_bf16 v[140:143], v[0:3], v[160:163], 0
	v_mfma_f32_16x16x32_bf16 v[132:135], v[8:11], v[160:163], 0
	v_mfma_f32_16x16x32_bf16 v[124:127], v[0:3], v[168:171], 0
	v_mfma_f32_16x16x32_bf16 v[120:123], v[8:11], v[168:171], 0
	v_mfma_f32_16x16x32_bf16 v[108:111], v[0:3], v[196:199], 0
	v_mfma_f32_16x16x32_bf16 v[104:107], v[8:11], v[196:199], 0
	v_mfma_f32_16x16x32_bf16 v[92:95], v[0:3], v[204:207], 0
	v_mfma_f32_16x16x32_bf16 v[88:91], v[8:11], v[204:207], 0
	v_mfma_f32_16x16x32_bf16 v[140:143], v[4:7], v[164:167], v[140:143]
	v_mfma_f32_16x16x32_bf16 v[132:135], v[12:15], v[164:167], v[132:135]
	v_mfma_f32_16x16x32_bf16 v[124:127], v[4:7], v[172:175], v[124:127]
	v_mfma_f32_16x16x32_bf16 v[120:123], v[12:15], v[172:175], v[120:123]
	v_mfma_f32_16x16x32_bf16 v[108:111], v[4:7], v[200:203], v[108:111]
	v_mfma_f32_16x16x32_bf16 v[104:107], v[12:15], v[200:203], v[104:107]
	v_mfma_f32_16x16x32_bf16 v[92:95], v[4:7], v[208:211], v[92:95]
	v_mfma_f32_16x16x32_bf16 v[88:91], v[12:15], v[208:211], v[88:91]
	s_setprio 0
	s_setprio 1
	v_mfma_f32_16x16x32_bf16 v[136:139], v[144:147], v[160:163], 0
	v_mfma_f32_16x16x32_bf16 v[128:131], v[152:155], v[160:163], 0
	v_mfma_f32_16x16x32_bf16 v[116:119], v[144:147], v[168:171], 0
	v_mfma_f32_16x16x32_bf16 v[112:115], v[152:155], v[168:171], 0
	v_mfma_f32_16x16x32_bf16 v[100:103], v[144:147], v[196:199], 0
	v_mfma_f32_16x16x32_bf16 v[96:99], v[152:155], v[196:199], 0
	v_mfma_f32_16x16x32_bf16 v[84:87], v[144:147], v[204:207], 0
	v_mfma_f32_16x16x32_bf16 v[80:83], v[152:155], v[204:207], 0
	v_mfma_f32_16x16x32_bf16 v[136:139], v[148:151], v[164:167], v[136:139]
	v_mfma_f32_16x16x32_bf16 v[128:131], v[156:159], v[164:167], v[128:131]
	v_mfma_f32_16x16x32_bf16 v[116:119], v[148:151], v[172:175], v[116:119]
	v_mfma_f32_16x16x32_bf16 v[112:115], v[156:159], v[172:175], v[112:115]
	v_mfma_f32_16x16x32_bf16 v[100:103], v[148:151], v[200:203], v[100:103]
	v_mfma_f32_16x16x32_bf16 v[96:99], v[156:159], v[200:203], v[96:99]
	v_mfma_f32_16x16x32_bf16 v[84:87], v[148:151], v[208:211], v[84:87]
	v_mfma_f32_16x16x32_bf16 v[80:83], v[156:159], v[208:211], v[80:83]
	s_setprio 0
	s_barrier
	s_add_i32 s86, s81, s65
	v_lshl_add_u64 v[212:213], s[56:57], 0, v[180:181]
	s_mov_b32 m0, s86
	ds_read_b128 v[160:163], v232 offset:16384
	ds_read_b128 v[164:167], v232 offset:17408
	ds_read_b128 v[168:171], v232 offset:18432
	ds_read_b128 v[172:175], v232 offset:19456
	ds_read_b128 v[196:199], v232 offset:20480
	ds_read_b128 v[200:203], v232 offset:21504
	ds_read_b128 v[204:207], v232 offset:22528
	ds_read_b128 v[208:211], v232 offset:23552
	global_load_lds_dwordx4 v[212:213], off
	s_add_i32 m0, s86, 0x2000
	s_add_u32 s86, s56, 0x40000
	v_lshl_add_u64 v[214:215], s[56:57], 0, v[184:185]
	s_addc_u32 s87, s57, 0
	s_add_i32 s88, s82, s65
	global_load_lds_dwordx4 v[214:215], off
	v_lshl_add_u64 v[216:217], s[86:87], 0, v[180:181]
	s_mov_b32 m0, s88
	v_lshl_add_u64 v[218:219], s[62:63], 0, v[182:183]
	global_load_lds_dwordx4 v[216:217], off
	v_lshl_add_u64 v[216:217], s[86:87], 0, v[184:185]
	s_add_i32 m0, s88, 0x2000
	s_nop 0
	global_load_lds_dwordx4 v[216:217], off
	v_lshl_add_u64 v[216:217], s[62:63], 0, v[178:179]
	s_mov_b32 m0, s68
	s_nop 0
	global_load_lds_dwordx4 v[216:217], off
	s_mov_b32 m0, s69
	s_nop 0
	global_load_lds_dwordx4 v[218:219], off
	s_waitcnt vmcnt(8)
	s_waitcnt lgkmcnt(0)
	s_barrier
; #define PG8_STAGE(bufoff, gbase, voff) do { _Pragma("unroll") for (int _i = 0; _i < 2; ++_i) \
;         __builtin_amdgcn_global_load_lds((const unsigned*)((const char*)(gbase) + (voff)[_i]), (LAS unsigned*)(lds + (bufoff) + ldsw + _i * 8192), 16, 0, 0); } while (0)
; #define PG8_LDA(dst, b, h) do { _Pragma("unroll") for (int m = 0; m < 4; ++m) _Pragma("unroll") for (int k = 0; k < 2; ++k) dst[m][k] = *(const LAS bf16x8*)(lds + PG8_SA(b, h) + aoff + m * 2048 + k * 1024); } while (0)
; #define PG8_LDB(dst, b, h) do { _Pragma("unroll") for (int n = 0; n < 2; ++n) _Pragma("unroll") for (int k = 0; k < 2; ++k) dst[n][k] = *(const LAS bf16x8*)(lds + PG8_SB(b, h) + boff + n * 2048 + k * 1024); } while (0)
; #define PG8_MMA(ai, bj, At, Bt) do { __builtin_amdgcn_s_setprio(1); _Pragma("unroll") for (int m = 0; m < 4; ++m) _Pragma("unroll") for (int n = 0; n < 2; ++n) _Pragma("unroll") for (int k = 0; k < 2; ++k) \
;         acc[ai][bj][m][n] = __builtin_amdgcn_mfma_f32_16x16x32_bf16(Bt[n][k], At[m][k], acc[ai][bj][m][n], 0, 0, 0); __builtin_amdgcn_s_setprio(0); } while (0)
; #define PG8_WAIT_V(n) asm volatile("s_waitcnt vmcnt(" #n ")" ::: "memory")
; #define PG8_WAIT_L(n) asm volatile("s_waitcnt lgkmcnt(" #n ")" ::: "memory")
; #define PG8_BAR __builtin_amdgcn_s_barrier()
; #define PG8_SCHED __builtin_amdgcn_sched_barrier(0)
; template <class Epi>
; __device__ __forceinline__ void gemm_phase(LAS unsigned char* lds, const Gemm g, const StaticOrder& S, const Epi& E) {
;     ...
;             PG8_WAIT_V(8); PG8_WAIT_L(0); PG8_BAR; PG8_MMA(1, 0, At, B0); PG8_MMA(1, 1, At, B1); PG8_BAR; PG8_SCHED;
;             PG8_LDB(B0, 1, 0); PG8_LDB(B1, 1, 1); PG8_SCHED; PG8_LDA(At, 1, 0); PG8_STAGE(PG8_SA(0, 1), a2 + hstepA, voffA);
;             PG8_WAIT_V(8); PG8_WAIT_L(0); PG8_BAR; PG8_MMA(0, 0, At, B0); PG8_MMA(0, 1, At, B1); PG8_BAR; PG8_SCHED;
;             PG8_LDA(At, 1, 1); PG8_STAGE(PG8_SB(1, 0), b3, voffB); PG8_STAGE(PG8_SB(1, 1), b3 + hstepB, voffB); PG8_STAGE(PG8_SA(1, 0), a3, voffA);
	s_setprio 1
	s_waitcnt lgkmcnt(0)
	v_mfma_f32_16x16x32_bf16 v[76:79], v[0:3], v[160:163], 0
	v_mfma_f32_16x16x32_bf16 v[72:75], v[8:11], v[160:163], 0
	v_mfma_f32_16x16x32_bf16 v[60:63], v[0:3], v[168:171], 0
	v_mfma_f32_16x16x32_bf16 v[56:59], v[8:11], v[168:171], 0
	v_mfma_f32_16x16x32_bf16 v[44:47], v[0:3], v[196:199], 0
	v_mfma_f32_16x16x32_bf16 v[40:43], v[8:11], v[196:199], 0
	v_mfma_f32_16x16x32_bf16 v[0:3], v[0:3], v[204:207], 0
	v_mfma_f32_16x16x32_bf16 v[76:79], v[4:7], v[164:167], v[76:79]
	v_mfma_f32_16x16x32_bf16 v[72:75], v[12:15], v[164:167], v[72:75]
	v_mfma_f32_16x16x32_bf16 v[60:63], v[4:7], v[172:175], v[60:63]
	v_mfma_f32_16x16x32_bf16 v[56:59], v[12:15], v[172:175], v[56:59]
	v_mfma_f32_16x16x32_bf16 v[44:47], v[4:7], v[200:203], v[44:47]
	v_mfma_f32_16x16x32_bf16 v[40:43], v[12:15], v[200:203], v[40:43]
	v_mfma_f32_16x16x32_bf16 v[0:3], v[4:7], v[208:211], v[0:3]
	v_mfma_f32_16x16x32_bf16 v[4:7], v[8:11], v[204:207], 0
	v_mfma_f32_16x16x32_bf16 v[4:7], v[12:15], v[208:211], v[4:7]
	s_setprio 0
	s_setprio 1
	v_mfma_f32_16x16x32_bf16 v[20:23], v[144:147], v[168:171], 0
	v_mfma_f32_16x16x32_bf16 v[52:55], v[148:151], v[172:175], v[20:23]
	v_mfma_f32_16x16x32_bf16 v[20:23], v[152:155], v[168:171], 0
	v_mfma_f32_16x16x32_bf16 v[48:51], v[156:159], v[172:175], v[20:23]
	v_mfma_f32_16x16x32_bf16 v[20:23], v[144:147], v[196:199], 0
	v_mfma_f32_16x16x32_bf16 v[36:39], v[148:151], v[200:203], v[20:23]
	v_mfma_f32_16x16x32_bf16 v[20:23], v[152:155], v[196:199], 0
	v_mfma_f32_16x16x32_bf16 v[32:35], v[156:159], v[200:203], v[20:23]
	v_mfma_f32_16x16x32_bf16 v[20:23], v[144:147], v[204:207], 0
	v_mfma_f32_16x16x32_bf16 v[16:19], v[152:155], v[204:207], 0
	v_mfma_f32_16x16x32_bf16 v[8:11], v[144:147], v[160:163], 0
	v_mfma_f32_16x16x32_bf16 v[12:15], v[152:155], v[160:163], 0
	v_mfma_f32_16x16x32_bf16 v[24:27], v[148:151], v[208:211], v[20:23]
	v_mfma_f32_16x16x32_bf16 v[16:19], v[156:159], v[208:211], v[16:19]
	v_mfma_f32_16x16x32_bf16 v[8:11], v[148:151], v[164:167], v[8:11]
	v_mfma_f32_16x16x32_bf16 v[12:15], v[156:159], v[164:167], v[12:15]
	s_setprio 0
	s_barrier
	s_add_i32 s86, 0, 0x18000
	s_add_i32 s87, 0, 0x1c000
	v_add_u32_e32 v68, s86, v229
	v_add_u32_e32 v156, s87, v229
	ds_read_b128 v[20:23], v68
	ds_read_b128 v[28:31], v68 offset:1024
	ds_read_b128 v[64:67], v68 offset:2048
	ds_read_b128 v[68:71], v68 offset:3072
	ds_read_b128 v[144:147], v156
	ds_read_b128 v[148:151], v156 offset:1024
	ds_read_b128 v[152:155], v156 offset:2048
	ds_read_b128 v[156:159], v156 offset:3072
	s_add_u32 s62, s62, 0x40000
	s_addc_u32 s63, s63, 0
	s_mov_b32 m0, s70
	v_lshl_add_u64 v[220:221], s[62:63], 0, v[178:179]
	ds_read_b128 v[160:163], v232 offset:32768
	ds_read_b128 v[164:167], v232 offset:33792
	ds_read_b128 v[168:171], v232 offset:34816
	ds_read_b128 v[172:175], v232 offset:35840
	ds_read_b128 v[196:199], v232 offset:36864
	ds_read_b128 v[200:203], v232 offset:37888
	ds_read_b128 v[204:207], v232 offset:38912
	ds_read_b128 v[208:211], v232 offset:39936
	global_load_lds_dwordx4 v[220:221], off
	v_lshl_add_u64 v[220:221], s[62:63], 0, v[182:183]
	s_mov_b32 m0, s71
	s_nop 0
	global_load_lds_dwordx4 v[220:221], off
	s_waitcnt vmcnt(8)
	s_waitcnt lgkmcnt(0)
	s_barrier
	s_setprio 1
	s_waitcnt lgkmcnt(0)
	v_mfma_f32_16x16x32_bf16 v[140:143], v[20:23], v[160:163], v[140:143]
	v_mfma_f32_16x16x32_bf16 v[132:135], v[64:67], v[160:163], v[132:135]
	v_mfma_f32_16x16x32_bf16 v[124:127], v[20:23], v[168:171], v[124:127]
	v_mfma_f32_16x16x32_bf16 v[120:123], v[64:67], v[168:171], v[120:123]
	v_mfma_f32_16x16x32_bf16 v[108:111], v[20:23], v[196:199], v[108:111]
	v_mfma_f32_16x16x32_bf16 v[104:107], v[64:67], v[196:199], v[104:107]
	v_mfma_f32_16x16x32_bf16 v[92:95], v[20:23], v[204:207], v[92:95]
	v_mfma_f32_16x16x32_bf16 v[88:91], v[64:67], v[204:207], v[88:91]
	v_mfma_f32_16x16x32_bf16 v[140:143], v[28:31], v[164:167], v[140:143]
	v_mfma_f32_16x16x32_bf16 v[132:135], v[68:71], v[164:167], v[132:135]
	v_mfma_f32_16x16x32_bf16 v[124:127], v[28:31], v[172:175], v[124:127]
	v_mfma_f32_16x16x32_bf16 v[120:123], v[68:71], v[172:175], v[120:123]
	v_mfma_f32_16x16x32_bf16 v[108:111], v[28:31], v[200:203], v[108:111]
	v_mfma_f32_16x16x32_bf16 v[104:107], v[68:71], v[200:203], v[104:107]
	v_mfma_f32_16x16x32_bf16 v[92:95], v[28:31], v[208:211], v[92:95]
	v_mfma_f32_16x16x32_bf16 v[88:91], v[68:71], v[208:211], v[88:91]
	s_setprio 0
	s_setprio 1
	v_mfma_f32_16x16x32_bf16 v[136:139], v[144:147], v[160:163], v[136:139]
	v_mfma_f32_16x16x32_bf16 v[128:131], v[152:155], v[160:163], v[128:131]
	v_mfma_f32_16x16x32_bf16 v[116:119], v[144:147], v[168:171], v[116:119]
	v_mfma_f32_16x16x32_bf16 v[112:115], v[152:155], v[168:171], v[112:115]
	v_mfma_f32_16x16x32_bf16 v[100:103], v[144:147], v[196:199], v[100:103]
	v_mfma_f32_16x16x32_bf16 v[96:99], v[152:155], v[196:199], v[96:99]
	v_mfma_f32_16x16x32_bf16 v[84:87], v[144:147], v[204:207], v[84:87]
	v_mfma_f32_16x16x32_bf16 v[80:83], v[152:155], v[204:207], v[80:83]
	v_mfma_f32_16x16x32_bf16 v[136:139], v[148:151], v[164:167], v[136:139]
	v_mfma_f32_16x16x32_bf16 v[128:131], v[156:159], v[164:167], v[128:131]
	v_mfma_f32_16x16x32_bf16 v[116:119], v[148:151], v[172:175], v[116:119]
	v_mfma_f32_16x16x32_bf16 v[112:115], v[156:159], v[172:175], v[112:115]
	v_mfma_f32_16x16x32_bf16 v[100:103], v[148:151], v[200:203], v[100:103]
	v_mfma_f32_16x16x32_bf16 v[96:99], v[156:159], v[200:203], v[96:99]
	v_mfma_f32_16x16x32_bf16 v[84:87], v[148:151], v[208:211], v[84:87]
	v_mfma_f32_16x16x32_bf16 v[80:83], v[156:159], v[208:211], v[80:83]
	s_setprio 0
	s_barrier
; #define PG8_STAGE(bufoff, gbase, voff) do { _Pragma("unroll") for (int _i = 0; _i < 2; ++_i) \
;         __builtin_amdgcn_global_load_lds((const unsigned*)((const char*)(gbase) + (voff)[_i]), (LAS unsigned*)(lds + (bufoff) + ldsw + _i * 8192), 16, 0, 0); } while (0)
; #define PG8_LDA(dst, b, h) do { _Pragma("unroll") for (int m = 0; m < 4; ++m) _Pragma("unroll") for (int k = 0; k < 2; ++k) dst[m][k] = *(const LAS bf16x8*)(lds + PG8_SA(b, h) + aoff + m * 2048 + k * 1024); } while (0)
; #define PG8_LDB(dst, b, h) do { _Pragma("unroll") for (int n = 0; n < 2; ++n) _Pragma("unroll") for (int k = 0; k < 2; ++k) dst[n][k] = *(const LAS bf16x8*)(lds + PG8_SB(b, h) + boff + n * 2048 + k * 1024); } while (0)
; #define PG8_WAIT_V(n) asm volatile("s_waitcnt vmcnt(" #n ")" ::: "memory")
; #define PG8_WAIT_L(n) asm volatile("s_waitcnt lgkmcnt(" #n ")" ::: "memory")
; template <class Epi>
; __device__ __forceinline__ void gemm_phase(LAS unsigned char* lds, const Gemm g, const StaticOrder& S, const Epi& E) {
;     ...
;         for (int t = 0; t < nt; t += 2) {
;             const bool last = (t == nt - 2);
;             const char* a1 = cA + (size_t)(t + 1) * kstep;
;             const char* a2 = last ? nA : cA + (size_t)(t + 2) * kstep; const char* b2 = last ? nB : cB + (size_t)(t + 2) * kstep;
;             const char* a3 = a2 + kstep; const char* b3 = b2 + kstep;
;             PG8_LDB(B0, 0, 0); PG8_LDB(B1, 0, 1); PG8_SCHED; PG8_LDA(At, 0, 0); PG8_STAGE(PG8_SA(1, 1), a1 + hstepA, voffA);
;             PG8_WAIT_V(8); PG8_WAIT_L(0); PG8_BAR; PG8_MMA(0, 0, At, B0); PG8_MMA(0, 1, At, B1); PG8_BAR; PG8_SCHED;
;             PG8_LDA(At, 0, 1); PG8_STAGE(PG8_SB(0, 0), b2, voffB); PG8_STAGE(PG8_SB(0, 1), b2 + hstepB, voffB); PG8_STAGE(PG8_SA(0, 0), a2, voffA);
;             PG8_WAIT_V(8); PG8_WAIT_L(0); PG8_BAR; PG8_MMA(1, 0, At, B0); PG8_MMA(1, 1, At, B1); PG8_BAR; PG8_SCHED;
;             PG8_LDB(B0, 1, 0); PG8_LDB(B1, 1, 1); PG8_SCHED; PG8_LDA(At, 1, 0); PG8_STAGE(PG8_SA(0, 1), a2 + hstepA, voffA);
;             PG8_WAIT_V(8); PG8_WAIT_L(0); PG8_BAR; PG8_MMA(0, 0, At, B0); PG8_MMA(0, 1, At, B1); PG8_BAR; PG8_SCHED;
;             PG8_LDA(At, 1, 1); PG8_STAGE(PG8_SB(1, 0), b3, voffB); PG8_STAGE(PG8_SB(1, 1), b3 + hstepB, voffB); PG8_STAGE(PG8_SA(1, 0), a3, voffA);
;             PG8_WAIT_V(8); PG8_WAIT_L(0); PG8_BAR; PG8_MMA(1, 0, At, B0); PG8_MMA(1, 1, At, B1); PG8_BAR; PG8_SCHED;
	s_add_i32 s62, s86, s65
	v_lshl_add_u64 v[212:213], v[212:213], 0, s[16:17]
	s_mov_b32 m0, s62
	ds_read_b128 v[160:163], v232 offset:49152
	ds_read_b128 v[164:167], v232 offset:50176
	ds_read_b128 v[168:171], v232 offset:51200
	ds_read_b128 v[172:175], v232 offset:52224
	ds_read_b128 v[196:199], v232 offset:53248
	ds_read_b128 v[200:203], v232 offset:54272
	ds_read_b128 v[204:207], v232 offset:55296
	ds_read_b128 v[208:211], v232 offset:56320
	global_load_lds_dwordx4 v[212:213], off
	s_add_i32 m0, s62, 0x2000
	s_add_u32 s56, s56, 0x40080
	v_lshl_add_u64 v[212:213], v[214:215], 0, s[16:17]
	s_addc_u32 s57, s57, 0
	s_add_i32 s62, s87, s65
	global_load_lds_dwordx4 v[212:213], off
	v_lshl_add_u64 v[212:213], s[56:57], 0, v[180:181]
	s_mov_b32 m0, s62
	s_nop 0
	global_load_lds_dwordx4 v[212:213], off
	v_lshl_add_u64 v[212:213], s[56:57], 0, v[184:185]
	s_add_i32 m0, s62, 0x2000
	s_nop 0
	global_load_lds_dwordx4 v[212:213], off
	v_lshl_add_u64 v[212:213], v[216:217], 0, s[16:17]
	s_mov_b32 m0, s76
	s_nop 0
	global_load_lds_dwordx4 v[212:213], off
	v_lshl_add_u64 v[212:213], v[218:219], 0, s[16:17]
	s_mov_b32 m0, s77
	s_nop 0
	global_load_lds_dwordx4 v[212:213], off
	s_waitcnt vmcnt(8)
	s_waitcnt lgkmcnt(0)
	s_barrier
	s_setprio 1
	s_waitcnt lgkmcnt(0)
	v_mfma_f32_16x16x32_bf16 v[76:79], v[20:23], v[160:163], v[76:79]
	v_mfma_f32_16x16x32_bf16 v[60:63], v[20:23], v[168:171], v[60:63]
	v_mfma_f32_16x16x32_bf16 v[44:47], v[20:23], v[196:199], v[44:47]
	v_mfma_f32_16x16x32_bf16 v[0:3], v[20:23], v[204:207], v[0:3]
	v_mfma_f32_16x16x32_bf16 v[76:79], v[28:31], v[164:167], v[76:79]
	v_mfma_f32_16x16x32_bf16 v[72:75], v[64:67], v[160:163], v[72:75]
	v_mfma_f32_16x16x32_bf16 v[60:63], v[28:31], v[172:175], v[60:63]
	v_mfma_f32_16x16x32_bf16 v[56:59], v[64:67], v[168:171], v[56:59]
	v_mfma_f32_16x16x32_bf16 v[44:47], v[28:31], v[200:203], v[44:47]
	v_mfma_f32_16x16x32_bf16 v[40:43], v[64:67], v[196:199], v[40:43]
	v_mfma_f32_16x16x32_bf16 v[28:31], v[28:31], v[208:211], v[0:3]
	v_mfma_f32_16x16x32_bf16 v[0:3], v[64:67], v[204:207], v[4:7]
	v_mfma_f32_16x16x32_bf16 v[72:75], v[68:71], v[164:167], v[72:75]
	v_mfma_f32_16x16x32_bf16 v[56:59], v[68:71], v[172:175], v[56:59]
	v_mfma_f32_16x16x32_bf16 v[40:43], v[68:71], v[200:203], v[40:43]
	v_mfma_f32_16x16x32_bf16 v[20:23], v[68:71], v[208:211], v[0:3]
	s_setprio 0
	s_setprio 1
	v_mfma_f32_16x16x32_bf16 v[0:3], v[144:147], v[160:163], v[8:11]
	v_mfma_f32_16x16x32_bf16 v[68:71], v[148:151], v[164:167], v[0:3]
	v_mfma_f32_16x16x32_bf16 v[0:3], v[152:155], v[160:163], v[12:15]
	v_mfma_f32_16x16x32_bf16 v[64:67], v[156:159], v[164:167], v[0:3]
	v_mfma_f32_16x16x32_bf16 v[0:3], v[144:147], v[168:171], v[52:55]
	v_mfma_f32_16x16x32_bf16 v[52:55], v[148:151], v[172:175], v[0:3]
	v_mfma_f32_16x16x32_bf16 v[0:3], v[152:155], v[168:171], v[48:51]
	v_mfma_f32_16x16x32_bf16 v[48:51], v[156:159], v[172:175], v[0:3]
	v_mfma_f32_16x16x32_bf16 v[0:3], v[144:147], v[196:199], v[36:39]
	v_mfma_f32_16x16x32_bf16 v[36:39], v[148:151], v[200:203], v[0:3]
	v_mfma_f32_16x16x32_bf16 v[0:3], v[152:155], v[196:199], v[32:35]
	v_mfma_f32_16x16x32_bf16 v[32:35], v[156:159], v[200:203], v[0:3]
	v_mfma_f32_16x16x32_bf16 v[0:3], v[144:147], v[204:207], v[24:27]
	v_mfma_f32_16x16x32_bf16 v[24:27], v[148:151], v[208:211], v[0:3]
	v_mfma_f32_16x16x32_bf16 v[0:3], v[152:155], v[204:207], v[16:19]
	v_mfma_f32_16x16x32_bf16 v[16:19], v[156:159], v[208:211], v[0:3]
	s_setprio 0
	s_barrier
	s_add_i32 s85, s85, 2
	s_add_u32 s54, s54, 0x100
	s_addc_u32 s55, s55, 0
	s_add_u32 s83, s83, 0x100
	s_addc_u32 s84, s84, 0
	s_cmp_gt_u32 s85, 13

; #define PG8_STAGE(bufoff, gbase, voff) do { _Pragma("unroll") for (int _i = 0; _i < 2; ++_i) \
;         __builtin_amdgcn_global_load_lds((const unsigned*)((const char*)(gbase) + (voff)[_i]), (LAS unsigned*)(lds + (bufoff) + ldsw + _i * 8192), 16, 0, 0); } while (0)
; #define PG8_LDA(dst, b, h) do { _Pragma("unroll") for (int m = 0; m < 4; ++m) _Pragma("unroll") for (int k = 0; k < 2; ++k) dst[m][k] = *(const LAS bf16x8*)(lds + PG8_SA(b, h) + aoff + m * 2048 + k * 1024); } while (0)
; #define PG8_LDB(dst, b, h) do { _Pragma("unroll") for (int n = 0; n < 2; ++n) _Pragma("unroll") for (int k = 0; k < 2; ++k) dst[n][k] = *(const LAS bf16x8*)(lds + PG8_SB(b, h) + boff + n * 2048 + k * 1024); } while (0)
; #define PG8_MMA(ai, bj, At, Bt) do { __builtin_amdgcn_s_setprio(1); _Pragma("unroll") for (int m = 0; m < 4; ++m) _Pragma("unroll") for (int n = 0; n < 2; ++n) _Pragma("unroll") for (int k = 0; k < 2; ++k) \
;         acc[ai][bj][m][n] = __builtin_amdgcn_mfma_f32_16x16x32_bf16(Bt[n][k], At[m][k], acc[ai][bj][m][n], 0, 0, 0); __builtin_amdgcn_s_setprio(0); } while (0)
; #define PG8_WAIT_V(n) asm volatile("s_waitcnt vmcnt(" #n ")" ::: "memory")
; template <class Epi>
; __device__ __forceinline__ void gemm_phase(LAS unsigned char* lds, const Gemm g, const StaticOrder& S, const Epi& E) {
;     ...
;         const char* nA = has_next ? (const char*)g.A + (size_t)nxt.pm * tstepA : cA; const char* nB = has_next ? (const char*)g.Bt + (size_t)nxt.pn * tstepB : cB;
; #pragma nounroll
;         for (int t = 0; t < nt; t += 2) {
;             const bool last = (t == nt - 2);
;             const char* a1 = cA + (size_t)(t + 1) * kstep;
;             const char* a2 = last ? nA : cA + (size_t)(t + 2) * kstep; const char* b2 = last ? nB : cB + (size_t)(t + 2) * kstep;
;             const char* a3 = a2 + kstep; const char* b3 = b2 + kstep;
;             PG8_LDB(B0, 0, 0); PG8_LDB(B1, 0, 1); PG8_SCHED; PG8_LDA(At, 0, 0); PG8_STAGE(PG8_SA(1, 1), a1 + hstepA, voffA);
;             PG8_WAIT_V(8); PG8_WAIT_L(0); PG8_BAR; PG8_MMA(0, 0, At, B0); PG8_MMA(0, 1, At, B1); PG8_BAR; PG8_SCHED;
;             PG8_LDA(At, 0, 1); PG8_STAGE(PG8_SB(0, 0), b2, voffB); PG8_STAGE(PG8_SB(0, 1), b2 + hstepB, voffB); PG8_STAGE(PG8_SA(0, 0), a2, voffA);
;             PG8_WAIT_V(8); PG8_WAIT_L(0); PG8_BAR; PG8_MMA(1, 0, At, B0); PG8_MMA(1, 1, At, B1); PG8_BAR; PG8_SCHED;
.LBB0_1232:
	s_ashr_i32 s23, s22, 31
	s_lshl_b64 s[34:35], s[22:23], 19
	s_add_u32 s34, s24, s34
	s_addc_u32 s35, s25, s35
	s_and_b64 s[38:39], s[4:5], exec
	s_cselect_b32 s23, s35, s53
	s_cselect_b32 s76, s34, s52
	s_ashr_i32 s21, s20, 31
	s_lshl_b64 s[38:39], s[20:21], 19
	s_add_u32 s38, s19, s38
	s_addc_u32 s39, s33, s39
	s_and_b64 s[56:57], s[4:5], exec
	s_cselect_b32 s21, s39, s55
	s_cselect_b32 s77, s38, s54
	s_add_u32 s52, s52, 0x40080
	s_addc_u32 s53, s53, 0
	s_add_u32 s78, s54, 0x100
	s_addc_u32 s79, s55, 0
	s_mov_b32 s80, -2
	ds_read_b128 v[56:59], v189
	ds_read_b128 v[60:63], v189 offset:1024
	ds_read_b128 v[72:75], v189 offset:2048
	ds_read_b128 v[76:79], v189 offset:3072
	ds_read_b128 v[144:147], v195
	ds_read_b128 v[148:151], v195 offset:1024
	ds_read_b128 v[168:171], v195 offset:2048
	ds_read_b128 v[178:181], v195 offset:3072
	s_add_u32 s54, s52, 0xfffc0080
	s_addc_u32 s55, s53, -1
	s_cmp_eq_u32 s80, 12
	s_cselect_b32 s57, s23, s55
	s_cselect_b32 s56, s76, s54
	s_cselect_b32 s55, s21, s79
	s_cselect_b32 s54, s77, s78
	v_lshl_add_u64 v[174:175], s[52:53], 0, v[160:161]
	s_add_i32 m0, s43, 0xc000
	ds_read_b128 v[184:187], v201
	ds_read_b128 v[190:193], v201 offset:1024
	ds_read_b128 v[196:199], v201 offset:2048
	ds_read_b128 v[202:205], v201 offset:3072
	ds_read_b128 v[208:211], v201 offset:4096
	ds_read_b128 v[212:215], v201 offset:5120
	ds_read_b128 v[216:219], v201 offset:6144
	ds_read_b128 v[220:223], v201 offset:7168
	global_load_lds_dwordx4 v[174:175], off
	v_lshl_add_u64 v[174:175], s[52:53], 0, v[162:163]
	s_add_i32 m0, s43, 0xe000
	s_nop 0
	global_load_lds_dwordx4 v[174:175], off
	s_waitcnt vmcnt(8)
	s_waitcnt lgkmcnt(0)
	s_barrier
	s_setprio 1
	s_waitcnt lgkmcnt(0)
	v_mfma_f32_16x16x32_bf16 v[140:143], v[56:59], v[184:187], 0
	v_mfma_f32_16x16x32_bf16 v[136:139], v[72:75], v[184:187], 0
	v_mfma_f32_16x16x32_bf16 v[124:127], v[56:59], v[196:199], 0
	v_mfma_f32_16x16x32_bf16 v[120:123], v[72:75], v[196:199], 0
	v_mfma_f32_16x16x32_bf16 v[108:111], v[56:59], v[208:211], 0
	v_mfma_f32_16x16x32_bf16 v[104:107], v[72:75], v[208:211], 0
	v_mfma_f32_16x16x32_bf16 v[92:95], v[56:59], v[216:219], 0
	v_mfma_f32_16x16x32_bf16 v[88:91], v[72:75], v[216:219], 0
	v_mfma_f32_16x16x32_bf16 v[140:143], v[60:63], v[190:193], v[140:143]
	v_mfma_f32_16x16x32_bf16 v[136:139], v[76:79], v[190:193], v[136:139]
	v_mfma_f32_16x16x32_bf16 v[124:127], v[60:63], v[202:205], v[124:127]
	v_mfma_f32_16x16x32_bf16 v[120:123], v[76:79], v[202:205], v[120:123]
	v_mfma_f32_16x16x32_bf16 v[108:111], v[60:63], v[212:215], v[108:111]
	v_mfma_f32_16x16x32_bf16 v[104:107], v[76:79], v[212:215], v[104:107]
	v_mfma_f32_16x16x32_bf16 v[92:95], v[60:63], v[220:223], v[92:95]
	v_mfma_f32_16x16x32_bf16 v[88:91], v[76:79], v[220:223], v[88:91]
	s_setprio 0
	s_setprio 1
	v_mfma_f32_16x16x32_bf16 v[132:135], v[144:147], v[184:187], 0
	v_mfma_f32_16x16x32_bf16 v[128:131], v[168:171], v[184:187], 0
	v_mfma_f32_16x16x32_bf16 v[116:119], v[144:147], v[196:199], 0
	v_mfma_f32_16x16x32_bf16 v[112:115], v[168:171], v[196:199], 0
	v_mfma_f32_16x16x32_bf16 v[100:103], v[144:147], v[208:211], 0
	v_mfma_f32_16x16x32_bf16 v[96:99], v[168:171], v[208:211], 0
	v_mfma_f32_16x16x32_bf16 v[84:87], v[144:147], v[216:219], 0
	v_mfma_f32_16x16x32_bf16 v[80:83], v[168:171], v[216:219], 0
	v_mfma_f32_16x16x32_bf16 v[132:135], v[148:151], v[190:193], v[132:135]
	v_mfma_f32_16x16x32_bf16 v[128:131], v[178:181], v[190:193], v[128:131]
	v_mfma_f32_16x16x32_bf16 v[116:119], v[148:151], v[202:205], v[116:119]
	v_mfma_f32_16x16x32_bf16 v[112:115], v[178:181], v[202:205], v[112:115]
	v_mfma_f32_16x16x32_bf16 v[100:103], v[148:151], v[212:215], v[100:103]
	v_mfma_f32_16x16x32_bf16 v[96:99], v[178:181], v[212:215], v[96:99]
	v_mfma_f32_16x16x32_bf16 v[84:87], v[148:151], v[220:223], v[84:87]
	v_mfma_f32_16x16x32_bf16 v[80:83], v[178:181], v[220:223], v[80:83]
	s_setprio 0
	s_barrier
	s_add_i32 s81, s73, s58
	v_lshl_add_u64 v[174:175], s[54:55], 0, v[154:155]
	s_mov_b32 m0, s81
	ds_read_b128 v[184:187], v201 offset:16384
	ds_read_b128 v[190:193], v201 offset:17408
	ds_read_b128 v[196:199], v201 offset:18432
	ds_read_b128 v[202:205], v201 offset:19456
	ds_read_b128 v[208:211], v201 offset:20480
	ds_read_b128 v[212:215], v201 offset:21504
	ds_read_b128 v[216:219], v201 offset:22528
	ds_read_b128 v[220:223], v201 offset:23552
	global_load_lds_dwordx4 v[174:175], off
	s_add_i32 m0, s81, 0x2000
	s_add_u32 s82, s54, 0x40000
	v_lshl_add_u64 v[224:225], s[54:55], 0, v[158:159]
	s_addc_u32 s83, s55, 0
	s_add_i32 s81, s74, s58
	global_load_lds_dwordx4 v[224:225], off
	v_lshl_add_u64 v[226:227], s[82:83], 0, v[154:155]
	s_mov_b32 m0, s81
	v_lshl_add_u64 v[228:229], s[56:57], 0, v[156:157]
	global_load_lds_dwordx4 v[226:227], off
	v_lshl_add_u64 v[226:227], s[82:83], 0, v[158:159]
	s_add_i32 m0, s81, 0x2000
	s_nop 0
	global_load_lds_dwordx4 v[226:227], off
	v_lshl_add_u64 v[226:227], s[56:57], 0, v[152:153]
	s_mov_b32 m0, s43
	s_nop 0
	global_load_lds_dwordx4 v[226:227], off
	s_mov_b32 m0, s59
	s_nop 0
	global_load_lds_dwordx4 v[228:229], off
	s_waitcnt vmcnt(8)
	s_waitcnt lgkmcnt(0)
	s_barrier
; #define PG8_STAGE(bufoff, gbase, voff) do { _Pragma("unroll") for (int _i = 0; _i < 2; ++_i) \
;         __builtin_amdgcn_global_load_lds((const unsigned*)((const char*)(gbase) + (voff)[_i]), (LAS unsigned*)(lds + (bufoff) + ldsw + _i * 8192), 16, 0, 0); } while (0)
; #define PG8_LDA(dst, b, h) do { _Pragma("unroll") for (int m = 0; m < 4; ++m) _Pragma("unroll") for (int k = 0; k < 2; ++k) dst[m][k] = *(const LAS bf16x8*)(lds + PG8_SA(b, h) + aoff + m * 2048 + k * 1024); } while (0)
; #define PG8_LDB(dst, b, h) do { _Pragma("unroll") for (int n = 0; n < 2; ++n) _Pragma("unroll") for (int k = 0; k < 2; ++k) dst[n][k] = *(const LAS bf16x8*)(lds + PG8_SB(b, h) + boff + n * 2048 + k * 1024); } while (0)
; #define PG8_MMA(ai, bj, At, Bt) do { __builtin_amdgcn_s_setprio(1); _Pragma("unroll") for (int m = 0; m < 4; ++m) _Pragma("unroll") for (int n = 0; n < 2; ++n) _Pragma("unroll") for (int k = 0; k < 2; ++k) \
;         acc[ai][bj][m][n] = __builtin_amdgcn_mfma_f32_16x16x32_bf16(Bt[n][k], At[m][k], acc[ai][bj][m][n], 0, 0, 0); __builtin_amdgcn_s_setprio(0); } while (0)
; #define PG8_WAIT_V(n) asm volatile("s_waitcnt vmcnt(" #n ")" ::: "memory")
; #define PG8_WAIT_L(n) asm volatile("s_waitcnt lgkmcnt(" #n ")" ::: "memory")
; #define PG8_BAR __builtin_amdgcn_s_barrier()
; #define PG8_SCHED __builtin_amdgcn_sched_barrier(0)
; template <class Epi>
; __device__ __forceinline__ void gemm_phase(LAS unsigned char* lds, const Gemm g, const StaticOrder& S, const Epi& E) {
;     ...
;             PG8_WAIT_V(8); PG8_WAIT_L(0); PG8_BAR; PG8_MMA(1, 0, At, B0); PG8_MMA(1, 1, At, B1); PG8_BAR; PG8_SCHED;
;             PG8_LDB(B0, 1, 0); PG8_LDB(B1, 1, 1); PG8_SCHED; PG8_LDA(At, 1, 0); PG8_STAGE(PG8_SA(0, 1), a2 + hstepA, voffA);
;             PG8_WAIT_V(8); PG8_WAIT_L(0); PG8_BAR; PG8_MMA(0, 0, At, B0); PG8_MMA(0, 1, At, B1); PG8_BAR; PG8_SCHED;
;             PG8_LDA(At, 1, 1); PG8_STAGE(PG8_SB(1, 0), b3, voffB); PG8_STAGE(PG8_SB(1, 1), b3 + hstepB, voffB); PG8_STAGE(PG8_SA(1, 0), a3, voffA);
	s_setprio 1
	s_waitcnt lgkmcnt(0)
	v_mfma_f32_16x16x32_bf16 v[68:71], v[56:59], v[184:187], 0
	v_mfma_f32_16x16x32_bf16 v[64:67], v[72:75], v[184:187], 0
	v_mfma_f32_16x16x32_bf16 v[44:47], v[56:59], v[196:199], 0
	v_mfma_f32_16x16x32_bf16 v[40:43], v[72:75], v[196:199], 0
	v_mfma_f32_16x16x32_bf16 v[28:31], v[56:59], v[208:211], 0
	v_mfma_f32_16x16x32_bf16 v[24:27], v[72:75], v[208:211], 0
	v_mfma_f32_16x16x32_bf16 v[12:15], v[56:59], v[216:219], 0
	v_mfma_f32_16x16x32_bf16 v[8:11], v[72:75], v[216:219], 0
	v_mfma_f32_16x16x32_bf16 v[68:71], v[60:63], v[190:193], v[68:71]
	v_mfma_f32_16x16x32_bf16 v[64:67], v[76:79], v[190:193], v[64:67]
	v_mfma_f32_16x16x32_bf16 v[44:47], v[60:63], v[202:205], v[44:47]
	v_mfma_f32_16x16x32_bf16 v[40:43], v[76:79], v[202:205], v[40:43]
	v_mfma_f32_16x16x32_bf16 v[28:31], v[60:63], v[212:215], v[28:31]
	v_mfma_f32_16x16x32_bf16 v[24:27], v[76:79], v[212:215], v[24:27]
	v_mfma_f32_16x16x32_bf16 v[12:15], v[60:63], v[220:223], v[12:15]
	v_mfma_f32_16x16x32_bf16 v[8:11], v[76:79], v[220:223], v[8:11]
	s_setprio 0
	s_setprio 1
	v_mfma_f32_16x16x32_bf16 v[52:55], v[144:147], v[184:187], 0
	v_mfma_f32_16x16x32_bf16 v[48:51], v[168:171], v[184:187], 0
	v_mfma_f32_16x16x32_bf16 v[36:39], v[144:147], v[196:199], 0
	v_mfma_f32_16x16x32_bf16 v[32:35], v[168:171], v[196:199], 0
	v_mfma_f32_16x16x32_bf16 v[20:23], v[144:147], v[208:211], 0
	v_mfma_f32_16x16x32_bf16 v[16:19], v[168:171], v[208:211], 0
	v_mfma_f32_16x16x32_bf16 v[4:7], v[144:147], v[216:219], 0
	v_mfma_f32_16x16x32_bf16 v[0:3], v[168:171], v[216:219], 0
	v_mfma_f32_16x16x32_bf16 v[52:55], v[148:151], v[190:193], v[52:55]
	v_mfma_f32_16x16x32_bf16 v[48:51], v[178:181], v[190:193], v[48:51]
	v_mfma_f32_16x16x32_bf16 v[36:39], v[148:151], v[202:205], v[36:39]
	v_mfma_f32_16x16x32_bf16 v[32:35], v[178:181], v[202:205], v[32:35]
	v_mfma_f32_16x16x32_bf16 v[20:23], v[148:151], v[212:215], v[20:23]
	v_mfma_f32_16x16x32_bf16 v[16:19], v[178:181], v[212:215], v[16:19]
	v_mfma_f32_16x16x32_bf16 v[4:7], v[148:151], v[220:223], v[4:7]
	v_mfma_f32_16x16x32_bf16 v[0:3], v[178:181], v[220:223], v[0:3]
	s_setprio 0
	s_barrier
	s_add_i32 s81, 0, 0x18000
	s_add_i32 s82, 0, 0x1c000
	v_add_u32_e32 v76, s81, v183
	v_add_u32_e32 v172, s82, v183
	ds_read_b128 v[56:59], v76
	ds_read_b128 v[60:63], v76 offset:1024
	ds_read_b128 v[72:75], v76 offset:2048
	ds_read_b128 v[76:79], v76 offset:3072
	ds_read_b128 v[144:147], v172
	ds_read_b128 v[148:151], v172 offset:1024
	ds_read_b128 v[168:171], v172 offset:2048
	ds_read_b128 v[178:181], v172 offset:3072
	s_add_u32 s56, s56, 0x40000
	s_addc_u32 s57, s57, 0
	s_mov_b32 m0, s62
	v_lshl_add_u64 v[230:231], s[56:57], 0, v[152:153]
	ds_read_b128 v[184:187], v201 offset:32768
	ds_read_b128 v[190:193], v201 offset:33792
	ds_read_b128 v[196:199], v201 offset:34816
	ds_read_b128 v[202:205], v201 offset:35840
	ds_read_b128 v[208:211], v201 offset:36864
	ds_read_b128 v[212:215], v201 offset:37888
	ds_read_b128 v[216:219], v201 offset:38912
	ds_read_b128 v[220:223], v201 offset:39936
	global_load_lds_dwordx4 v[230:231], off
	v_lshl_add_u64 v[230:231], s[56:57], 0, v[156:157]
	s_mov_b32 m0, s63
	s_nop 0
	global_load_lds_dwordx4 v[230:231], off
	s_waitcnt vmcnt(8)
	s_waitcnt lgkmcnt(0)
	s_barrier
	s_setprio 1
	s_waitcnt lgkmcnt(0)
	v_mfma_f32_16x16x32_bf16 v[140:143], v[56:59], v[184:187], v[140:143]
	v_mfma_f32_16x16x32_bf16 v[136:139], v[72:75], v[184:187], v[136:139]
	v_mfma_f32_16x16x32_bf16 v[124:127], v[56:59], v[196:199], v[124:127]
	v_mfma_f32_16x16x32_bf16 v[120:123], v[72:75], v[196:199], v[120:123]
	v_mfma_f32_16x16x32_bf16 v[108:111], v[56:59], v[208:211], v[108:111]
	v_mfma_f32_16x16x32_bf16 v[104:107], v[72:75], v[208:211], v[104:107]
	v_mfma_f32_16x16x32_bf16 v[92:95], v[56:59], v[216:219], v[92:95]
	v_mfma_f32_16x16x32_bf16 v[88:91], v[72:75], v[216:219], v[88:91]
	v_mfma_f32_16x16x32_bf16 v[140:143], v[60:63], v[190:193], v[140:143]
	v_mfma_f32_16x16x32_bf16 v[136:139], v[76:79], v[190:193], v[136:139]
	v_mfma_f32_16x16x32_bf16 v[124:127], v[60:63], v[202:205], v[124:127]
	v_mfma_f32_16x16x32_bf16 v[120:123], v[76:79], v[202:205], v[120:123]
	v_mfma_f32_16x16x32_bf16 v[108:111], v[60:63], v[212:215], v[108:111]
	v_mfma_f32_16x16x32_bf16 v[104:107], v[76:79], v[212:215], v[104:107]
	v_mfma_f32_16x16x32_bf16 v[92:95], v[60:63], v[220:223], v[92:95]
	v_mfma_f32_16x16x32_bf16 v[88:91], v[76:79], v[220:223], v[88:91]
	s_setprio 0
	s_setprio 1
	v_mfma_f32_16x16x32_bf16 v[132:135], v[144:147], v[184:187], v[132:135]
	v_mfma_f32_16x16x32_bf16 v[128:131], v[168:171], v[184:187], v[128:131]
	v_mfma_f32_16x16x32_bf16 v[116:119], v[144:147], v[196:199], v[116:119]
	v_mfma_f32_16x16x32_bf16 v[112:115], v[168:171], v[196:199], v[112:115]
	v_mfma_f32_16x16x32_bf16 v[100:103], v[144:147], v[208:211], v[100:103]
	v_mfma_f32_16x16x32_bf16 v[96:99], v[168:171], v[208:211], v[96:99]
	v_mfma_f32_16x16x32_bf16 v[84:87], v[144:147], v[216:219], v[84:87]
	v_mfma_f32_16x16x32_bf16 v[80:83], v[168:171], v[216:219], v[80:83]
	v_mfma_f32_16x16x32_bf16 v[132:135], v[148:151], v[190:193], v[132:135]
	v_mfma_f32_16x16x32_bf16 v[128:131], v[178:181], v[190:193], v[128:131]
	v_mfma_f32_16x16x32_bf16 v[116:119], v[148:151], v[202:205], v[116:119]
	v_mfma_f32_16x16x32_bf16 v[112:115], v[178:181], v[202:205], v[112:115]
	v_mfma_f32_16x16x32_bf16 v[100:103], v[148:151], v[212:215], v[100:103]
	v_mfma_f32_16x16x32_bf16 v[96:99], v[178:181], v[212:215], v[96:99]
	v_mfma_f32_16x16x32_bf16 v[84:87], v[148:151], v[220:223], v[84:87]
	v_mfma_f32_16x16x32_bf16 v[80:83], v[178:181], v[220:223], v[80:83]
	s_setprio 0
	s_barrier
; #define PG8_STAGE(bufoff, gbase, voff) do { _Pragma("unroll") for (int _i = 0; _i < 2; ++_i) \
;         __builtin_amdgcn_global_load_lds((const unsigned*)((const char*)(gbase) + (voff)[_i]), (LAS unsigned*)(lds + (bufoff) + ldsw + _i * 8192), 16, 0, 0); } while (0)
; #define PG8_LDA(dst, b, h) do { _Pragma("unroll") for (int m = 0; m < 4; ++m) _Pragma("unroll") for (int k = 0; k < 2; ++k) dst[m][k] = *(const LAS bf16x8*)(lds + PG8_SA(b, h) + aoff + m * 2048 + k * 1024); } while (0)
; #define PG8_LDB(dst, b, h) do { _Pragma("unroll") for (int n = 0; n < 2; ++n) _Pragma("unroll") for (int k = 0; k < 2; ++k) dst[n][k] = *(const LAS bf16x8*)(lds + PG8_SB(b, h) + boff + n * 2048 + k * 1024); } while (0)
; #define PG8_WAIT_V(n) asm volatile("s_waitcnt vmcnt(" #n ")" ::: "memory")
; #define PG8_WAIT_L(n) asm volatile("s_waitcnt lgkmcnt(" #n ")" ::: "memory")
; template <class Epi>
; __device__ __forceinline__ void gemm_phase(LAS unsigned char* lds, const Gemm g, const StaticOrder& S, const Epi& E) {
;     ...
;         for (int t = 0; t < nt; t += 2) {
;             const bool last = (t == nt - 2);
;             const char* a1 = cA + (size_t)(t + 1) * kstep;
;             const char* a2 = last ? nA : cA + (size_t)(t + 2) * kstep; const char* b2 = last ? nB : cB + (size_t)(t + 2) * kstep;
;             const char* a3 = a2 + kstep; const char* b3 = b2 + kstep;
;             PG8_LDB(B0, 0, 0); PG8_LDB(B1, 0, 1); PG8_SCHED; PG8_LDA(At, 0, 0); PG8_STAGE(PG8_SA(1, 1), a1 + hstepA, voffA);
;             PG8_WAIT_V(8); PG8_WAIT_L(0); PG8_BAR; PG8_MMA(0, 0, At, B0); PG8_MMA(0, 1, At, B1); PG8_BAR; PG8_SCHED;
;             PG8_LDA(At, 0, 1); PG8_STAGE(PG8_SB(0, 0), b2, voffB); PG8_STAGE(PG8_SB(0, 1), b2 + hstepB, voffB); PG8_STAGE(PG8_SA(0, 0), a2, voffA);
;             PG8_WAIT_V(8); PG8_WAIT_L(0); PG8_BAR; PG8_MMA(1, 0, At, B0); PG8_MMA(1, 1, At, B1); PG8_BAR; PG8_SCHED;
;             PG8_LDB(B0, 1, 0); PG8_LDB(B1, 1, 1); PG8_SCHED; PG8_LDA(At, 1, 0); PG8_STAGE(PG8_SA(0, 1), a2 + hstepA, voffA);
;             PG8_WAIT_V(8); PG8_WAIT_L(0); PG8_BAR; PG8_MMA(0, 0, At, B0); PG8_MMA(0, 1, At, B1); PG8_BAR; PG8_SCHED;
;             PG8_LDA(At, 1, 1); PG8_STAGE(PG8_SB(1, 0), b3, voffB); PG8_STAGE(PG8_SB(1, 1), b3 + hstepB, voffB); PG8_STAGE(PG8_SA(1, 0), a3, voffA);
;             PG8_WAIT_V(8); PG8_WAIT_L(0); PG8_BAR; PG8_MMA(1, 0, At, B0); PG8_MMA(1, 1, At, B1); PG8_BAR; PG8_SCHED;
	s_add_i32 s56, s81, s58
	v_lshl_add_u64 v[174:175], v[174:175], 0, s[12:13]
	s_mov_b32 m0, s56
	ds_read_b128 v[184:187], v201 offset:49152
	ds_read_b128 v[190:193], v201 offset:50176
	ds_read_b128 v[196:199], v201 offset:51200
	ds_read_b128 v[202:205], v201 offset:52224
	ds_read_b128 v[208:211], v201 offset:53248
	ds_read_b128 v[212:215], v201 offset:54272
	ds_read_b128 v[216:219], v201 offset:55296
	ds_read_b128 v[220:223], v201 offset:56320
	global_load_lds_dwordx4 v[174:175], off
	s_add_i32 m0, s56, 0x2000
	s_add_u32 s54, s54, 0x40080
	v_lshl_add_u64 v[174:175], v[224:225], 0, s[12:13]
	s_addc_u32 s55, s55, 0
	s_add_i32 s56, s82, s58
	global_load_lds_dwordx4 v[174:175], off
	v_lshl_add_u64 v[174:175], s[54:55], 0, v[154:155]
	s_mov_b32 m0, s56
	s_nop 0
	global_load_lds_dwordx4 v[174:175], off
	v_lshl_add_u64 v[174:175], s[54:55], 0, v[158:159]
	s_add_i32 m0, s56, 0x2000
	s_nop 0
	global_load_lds_dwordx4 v[174:175], off
	v_lshl_add_u64 v[174:175], v[226:227], 0, s[12:13]
	s_mov_b32 m0, s69
	s_nop 0
	global_load_lds_dwordx4 v[174:175], off
	v_lshl_add_u64 v[174:175], v[228:229], 0, s[12:13]
	s_mov_b32 m0, s70
	s_nop 0
	global_load_lds_dwordx4 v[174:175], off
	s_waitcnt vmcnt(8)
	s_waitcnt lgkmcnt(0)
	s_barrier
	s_setprio 1
	s_waitcnt lgkmcnt(0)
	v_mfma_f32_16x16x32_bf16 v[68:71], v[56:59], v[184:187], v[68:71]
	v_mfma_f32_16x16x32_bf16 v[64:67], v[72:75], v[184:187], v[64:67]
	v_mfma_f32_16x16x32_bf16 v[44:47], v[56:59], v[196:199], v[44:47]
	v_mfma_f32_16x16x32_bf16 v[40:43], v[72:75], v[196:199], v[40:43]
	v_mfma_f32_16x16x32_bf16 v[28:31], v[56:59], v[208:211], v[28:31]
	v_mfma_f32_16x16x32_bf16 v[24:27], v[72:75], v[208:211], v[24:27]
	v_mfma_f32_16x16x32_bf16 v[12:15], v[56:59], v[216:219], v[12:15]
	v_mfma_f32_16x16x32_bf16 v[8:11], v[72:75], v[216:219], v[8:11]
	v_mfma_f32_16x16x32_bf16 v[68:71], v[60:63], v[190:193], v[68:71]
	v_mfma_f32_16x16x32_bf16 v[64:67], v[76:79], v[190:193], v[64:67]
	v_mfma_f32_16x16x32_bf16 v[44:47], v[60:63], v[202:205], v[44:47]
	v_mfma_f32_16x16x32_bf16 v[40:43], v[76:79], v[202:205], v[40:43]
	v_mfma_f32_16x16x32_bf16 v[28:31], v[60:63], v[212:215], v[28:31]
	v_mfma_f32_16x16x32_bf16 v[24:27], v[76:79], v[212:215], v[24:27]
	v_mfma_f32_16x16x32_bf16 v[12:15], v[60:63], v[220:223], v[12:15]
	v_mfma_f32_16x16x32_bf16 v[8:11], v[76:79], v[220:223], v[8:11]
	s_setprio 0
	s_setprio 1
	v_mfma_f32_16x16x32_bf16 v[52:55], v[144:147], v[184:187], v[52:55]
	v_mfma_f32_16x16x32_bf16 v[48:51], v[168:171], v[184:187], v[48:51]
	v_mfma_f32_16x16x32_bf16 v[36:39], v[144:147], v[196:199], v[36:39]
	v_mfma_f32_16x16x32_bf16 v[32:35], v[168:171], v[196:199], v[32:35]
	v_mfma_f32_16x16x32_bf16 v[20:23], v[144:147], v[208:211], v[20:23]
	v_mfma_f32_16x16x32_bf16 v[16:19], v[168:171], v[208:211], v[16:19]
	v_mfma_f32_16x16x32_bf16 v[4:7], v[144:147], v[216:219], v[4:7]
	v_mfma_f32_16x16x32_bf16 v[0:3], v[168:171], v[216:219], v[0:3]
	v_mfma_f32_16x16x32_bf16 v[52:55], v[148:151], v[190:193], v[52:55]
	v_mfma_f32_16x16x32_bf16 v[48:51], v[178:181], v[190:193], v[48:51]
	v_mfma_f32_16x16x32_bf16 v[36:39], v[148:151], v[202:205], v[36:39]
	v_mfma_f32_16x16x32_bf16 v[32:35], v[178:181], v[202:205], v[32:35]
	v_mfma_f32_16x16x32_bf16 v[20:23], v[148:151], v[212:215], v[20:23]
	v_mfma_f32_16x16x32_bf16 v[16:19], v[178:181], v[212:215], v[16:19]
	v_mfma_f32_16x16x32_bf16 v[4:7], v[148:151], v[220:223], v[4:7]
	v_mfma_f32_16x16x32_bf16 v[0:3], v[178:181], v[220:223], v[0:3]
	s_setprio 0
	s_barrier
	s_add_i32 s80, s80, 2
	s_add_u32 s52, s52, 0x100
	s_addc_u32 s53, s53, 0
	s_add_u32 s78, s78, 0x100
	s_addc_u32 s79, s79, 0
	s_cmp_gt_u32 s80, 13

; #define PG8_STAGE(bufoff, gbase, voff) do { _Pragma("unroll") for (int _i = 0; _i < 2; ++_i) \
;         __builtin_amdgcn_global_load_lds((const unsigned*)((const char*)(gbase) + (voff)[_i]), (LAS unsigned*)(lds + (bufoff) + ldsw + _i * 8192), 16, 0, 0); } while (0)
; #define PG8_LDA(dst, b, h) do { _Pragma("unroll") for (int m = 0; m < 4; ++m) _Pragma("unroll") for (int k = 0; k < 2; ++k) dst[m][k] = *(const LAS bf16x8*)(lds + PG8_SA(b, h) + aoff + m * 2048 + k * 1024); } while (0)
; #define PG8_LDB(dst, b, h) do { _Pragma("unroll") for (int n = 0; n < 2; ++n) _Pragma("unroll") for (int k = 0; k < 2; ++k) dst[n][k] = *(const LAS bf16x8*)(lds + PG8_SB(b, h) + boff + n * 2048 + k * 1024); } while (0)
; #define PG8_MMA(ai, bj, At, Bt) do { __builtin_amdgcn_s_setprio(1); _Pragma("unroll") for (int m = 0; m < 4; ++m) _Pragma("unroll") for (int n = 0; n < 2; ++n) _Pragma("unroll") for (int k = 0; k < 2; ++k) \
;         acc[ai][bj][m][n] = __builtin_amdgcn_mfma_f32_16x16x32_bf16(Bt[n][k], At[m][k], acc[ai][bj][m][n], 0, 0, 0); __builtin_amdgcn_s_setprio(0); } while (0)
; #define PG8_WAIT_V(n) asm volatile("s_waitcnt vmcnt(" #n ")" ::: "memory")
; template <class Epi>
; __device__ __forceinline__ void gemm_phase(LAS unsigned char* lds, const Gemm g, const StaticOrder& S, const Epi& E) {
;     ...
;         const char* nA = has_next ? (const char*)g.A + (size_t)nxt.pm * tstepA : cA; const char* nB = has_next ? (const char*)g.Bt + (size_t)nxt.pn * tstepB : cB;
; #pragma nounroll
;         for (int t = 0; t < nt; t += 2) {
;             const bool last = (t == nt - 2);
;             const char* a1 = cA + (size_t)(t + 1) * kstep;
;             const char* a2 = last ? nA : cA + (size_t)(t + 2) * kstep; const char* b2 = last ? nB : cB + (size_t)(t + 2) * kstep;
;             const char* a3 = a2 + kstep; const char* b3 = b2 + kstep;
;             PG8_LDB(B0, 0, 0); PG8_LDB(B1, 0, 1); PG8_SCHED; PG8_LDA(At, 0, 0); PG8_STAGE(PG8_SA(1, 1), a1 + hstepA, voffA);
;             PG8_WAIT_V(8); PG8_WAIT_L(0); PG8_BAR; PG8_MMA(0, 0, At, B0); PG8_MMA(0, 1, At, B1); PG8_BAR; PG8_SCHED;
;             PG8_LDA(At, 0, 1); PG8_STAGE(PG8_SB(0, 0), b2, voffB); PG8_STAGE(PG8_SB(0, 1), b2 + hstepB, voffB); PG8_STAGE(PG8_SA(0, 0), a2, voffA);
;             PG8_WAIT_V(8); PG8_WAIT_L(0); PG8_BAR; PG8_MMA(1, 0, At, B0); PG8_MMA(1, 1, At, B1); PG8_BAR; PG8_SCHED;
.LBB0_1313:
	s_ashr_i32 s19, s18, 31
	s_lshl_b64 s[20:21], s[18:19], 21
	s_add_u32 s20, s26, s20
	s_addc_u32 s21, s27, s21
	s_and_b64 s[22:23], s[4:5], exec
	s_cselect_b32 s1, s21, s39
	s_cselect_b32 s19, s20, s38
	s_ashr_i32 s17, s16, 31
	s_lshl_b64 s[22:23], s[16:17], 20
	s_add_u32 s22, s3, s22
	s_addc_u32 s23, s33, s23
	s_and_b64 s[52:53], s[4:5], exec
	s_cselect_b32 s17, s23, s43
	s_cselect_b32 s70, s22, s42
	s_add_u32 s38, s38, 0x100080
	s_addc_u32 s39, s39, 0
	s_add_u32 s71, s42, 0x100
	s_addc_u32 s72, s43, 0
	s_mov_b32 s73, -2
	s_waitcnt lgkmcnt(0)
	ds_read_b128 v[128:131], v182
	ds_read_b128 v[132:135], v182 offset:1024
	ds_read_b128 v[136:139], v182 offset:2048
	ds_read_b128 v[140:143], v182 offset:3072
	ds_read_b128 v[160:163], v183
	ds_read_b128 v[164:167], v183 offset:1024
	ds_read_b128 v[168:171], v183 offset:2048
	ds_read_b128 v[172:175], v183 offset:3072
	s_add_u32 s42, s38, 0xfff00080
	s_addc_u32 s43, s39, -1
	s_cmp_eq_u32 s73, 28
	s_cselect_b32 s53, s1, s43
	s_cselect_b32 s52, s19, s42
	s_cselect_b32 s43, s17, s72
	s_cselect_b32 s42, s70, s71
	v_lshl_add_u64 v[178:179], s[38:39], 0, v[152:153]
	s_add_i32 m0, s35, 0xc000
	ds_read_b128 v[186:189], v184
	ds_read_b128 v[190:193], v184 offset:1024
	ds_read_b128 v[194:197], v184 offset:2048
	ds_read_b128 v[198:201], v184 offset:3072
	ds_read_b128 v[202:205], v184 offset:4096
	ds_read_b128 v[206:209], v184 offset:5120
	ds_read_b128 v[210:213], v184 offset:6144
	ds_read_b128 v[214:217], v184 offset:7168
	global_load_lds_dwordx4 v[178:179], off
	v_lshl_add_u64 v[178:179], s[38:39], 0, v[154:155]
	s_add_i32 m0, s35, 0xe000
	s_nop 0
	global_load_lds_dwordx4 v[178:179], off
	s_waitcnt vmcnt(8)
	s_waitcnt lgkmcnt(0)
	s_barrier
	s_setprio 1
	s_waitcnt lgkmcnt(0)
	v_mfma_f32_16x16x32_bf16 v[124:127], v[128:131], v[186:189], 0
	v_mfma_f32_16x16x32_bf16 v[120:123], v[136:139], v[186:189], 0
	v_mfma_f32_16x16x32_bf16 v[108:111], v[128:131], v[194:197], 0
	v_mfma_f32_16x16x32_bf16 v[104:107], v[136:139], v[194:197], 0
	v_mfma_f32_16x16x32_bf16 v[92:95], v[128:131], v[202:205], 0
	v_mfma_f32_16x16x32_bf16 v[88:91], v[136:139], v[202:205], 0
	v_mfma_f32_16x16x32_bf16 v[76:79], v[128:131], v[210:213], 0
	v_mfma_f32_16x16x32_bf16 v[72:75], v[136:139], v[210:213], 0
	v_mfma_f32_16x16x32_bf16 v[124:127], v[132:135], v[190:193], v[124:127]
	v_mfma_f32_16x16x32_bf16 v[120:123], v[140:143], v[190:193], v[120:123]
	v_mfma_f32_16x16x32_bf16 v[108:111], v[132:135], v[198:201], v[108:111]
	v_mfma_f32_16x16x32_bf16 v[104:107], v[140:143], v[198:201], v[104:107]
	v_mfma_f32_16x16x32_bf16 v[92:95], v[132:135], v[206:209], v[92:95]
	v_mfma_f32_16x16x32_bf16 v[88:91], v[140:143], v[206:209], v[88:91]
	v_mfma_f32_16x16x32_bf16 v[76:79], v[132:135], v[214:217], v[76:79]
	v_mfma_f32_16x16x32_bf16 v[72:75], v[140:143], v[214:217], v[72:75]
	s_setprio 0
	s_setprio 1
	v_mfma_f32_16x16x32_bf16 v[116:119], v[160:163], v[186:189], 0
	v_mfma_f32_16x16x32_bf16 v[112:115], v[168:171], v[186:189], 0
	v_mfma_f32_16x16x32_bf16 v[100:103], v[160:163], v[194:197], 0
	v_mfma_f32_16x16x32_bf16 v[96:99], v[168:171], v[194:197], 0
	v_mfma_f32_16x16x32_bf16 v[84:87], v[160:163], v[202:205], 0
	v_mfma_f32_16x16x32_bf16 v[80:83], v[168:171], v[202:205], 0
	v_mfma_f32_16x16x32_bf16 v[68:71], v[160:163], v[210:213], 0
	v_mfma_f32_16x16x32_bf16 v[64:67], v[168:171], v[210:213], 0
	v_mfma_f32_16x16x32_bf16 v[116:119], v[164:167], v[190:193], v[116:119]
	v_mfma_f32_16x16x32_bf16 v[112:115], v[172:175], v[190:193], v[112:115]
	v_mfma_f32_16x16x32_bf16 v[100:103], v[164:167], v[198:201], v[100:103]
	v_mfma_f32_16x16x32_bf16 v[96:99], v[172:175], v[198:201], v[96:99]
	v_mfma_f32_16x16x32_bf16 v[84:87], v[164:167], v[206:209], v[84:87]
	v_mfma_f32_16x16x32_bf16 v[80:83], v[172:175], v[206:209], v[80:83]
	v_mfma_f32_16x16x32_bf16 v[68:71], v[164:167], v[214:217], v[68:71]
	v_mfma_f32_16x16x32_bf16 v[64:67], v[172:175], v[214:217], v[64:67]
	s_setprio 0
	s_barrier
	s_add_i32 s74, s68, s54
	v_lshl_add_u64 v[178:179], s[42:43], 0, v[146:147]
	s_mov_b32 m0, s74
	ds_read_b128 v[186:189], v184 offset:16384
	ds_read_b128 v[190:193], v184 offset:17408
	ds_read_b128 v[194:197], v184 offset:18432
	ds_read_b128 v[198:201], v184 offset:19456
	ds_read_b128 v[202:205], v184 offset:20480
	ds_read_b128 v[206:209], v184 offset:21504
	ds_read_b128 v[210:213], v184 offset:22528
	ds_read_b128 v[214:217], v184 offset:23552
	global_load_lds_dwordx4 v[178:179], off
	s_add_i32 m0, s74, 0x2000
	s_add_u32 s74, s42, 0x80000
	v_lshl_add_u64 v[218:219], s[42:43], 0, v[150:151]
	s_addc_u32 s75, s43, 0
	s_add_i32 s76, s69, s54
	global_load_lds_dwordx4 v[218:219], off
	v_lshl_add_u64 v[220:221], s[74:75], 0, v[146:147]
	s_mov_b32 m0, s76
	v_lshl_add_u64 v[222:223], s[52:53], 0, v[148:149]
	global_load_lds_dwordx4 v[220:221], off
	v_lshl_add_u64 v[220:221], s[74:75], 0, v[150:151]
	s_add_i32 m0, s76, 0x2000
	s_nop 0
	global_load_lds_dwordx4 v[220:221], off
	v_lshl_add_u64 v[220:221], s[52:53], 0, v[144:145]
	s_mov_b32 m0, s35
	s_nop 0
	global_load_lds_dwordx4 v[220:221], off
	s_mov_b32 m0, s55
	s_nop 0
	global_load_lds_dwordx4 v[222:223], off
	s_waitcnt vmcnt(8)
	s_waitcnt lgkmcnt(0)
	s_barrier
; #define PG8_STAGE(bufoff, gbase, voff) do { _Pragma("unroll") for (int _i = 0; _i < 2; ++_i) \
;         __builtin_amdgcn_global_load_lds((const unsigned*)((const char*)(gbase) + (voff)[_i]), (LAS unsigned*)(lds + (bufoff) + ldsw + _i * 8192), 16, 0, 0); } while (0)
; #define PG8_LDA(dst, b, h) do { _Pragma("unroll") for (int m = 0; m < 4; ++m) _Pragma("unroll") for (int k = 0; k < 2; ++k) dst[m][k] = *(const LAS bf16x8*)(lds + PG8_SA(b, h) + aoff + m * 2048 + k * 1024); } while (0)
; #define PG8_LDB(dst, b, h) do { _Pragma("unroll") for (int n = 0; n < 2; ++n) _Pragma("unroll") for (int k = 0; k < 2; ++k) dst[n][k] = *(const LAS bf16x8*)(lds + PG8_SB(b, h) + boff + n * 2048 + k * 1024); } while (0)
; #define PG8_MMA(ai, bj, At, Bt) do { __builtin_amdgcn_s_setprio(1); _Pragma("unroll") for (int m = 0; m < 4; ++m) _Pragma("unroll") for (int n = 0; n < 2; ++n) _Pragma("unroll") for (int k = 0; k < 2; ++k) \
;         acc[ai][bj][m][n] = __builtin_amdgcn_mfma_f32_16x16x32_bf16(Bt[n][k], At[m][k], acc[ai][bj][m][n], 0, 0, 0); __builtin_amdgcn_s_setprio(0); } while (0)
; #define PG8_WAIT_V(n) asm volatile("s_waitcnt vmcnt(" #n ")" ::: "memory")
; #define PG8_WAIT_L(n) asm volatile("s_waitcnt lgkmcnt(" #n ")" ::: "memory")
; #define PG8_BAR __builtin_amdgcn_s_barrier()
; #define PG8_SCHED __builtin_amdgcn_sched_barrier(0)
; template <class Epi>
; __device__ __forceinline__ void gemm_phase(LAS unsigned char* lds, const Gemm g, const StaticOrder& S, const Epi& E) {
;     ...
;             PG8_WAIT_V(8); PG8_WAIT_L(0); PG8_BAR; PG8_MMA(1, 0, At, B0); PG8_MMA(1, 1, At, B1); PG8_BAR; PG8_SCHED;
;             PG8_LDB(B0, 1, 0); PG8_LDB(B1, 1, 1); PG8_SCHED; PG8_LDA(At, 1, 0); PG8_STAGE(PG8_SA(0, 1), a2 + hstepA, voffA);
;             PG8_WAIT_V(8); PG8_WAIT_L(0); PG8_BAR; PG8_MMA(0, 0, At, B0); PG8_MMA(0, 1, At, B1); PG8_BAR; PG8_SCHED;
;             PG8_LDA(At, 1, 1); PG8_STAGE(PG8_SB(1, 0), b3, voffB); PG8_STAGE(PG8_SB(1, 1), b3 + hstepB, voffB); PG8_STAGE(PG8_SA(1, 0), a3, voffA);
	s_setprio 1
	s_waitcnt lgkmcnt(0)
	v_mfma_f32_16x16x32_bf16 v[60:63], v[128:131], v[186:189], 0
	v_mfma_f32_16x16x32_bf16 v[56:59], v[136:139], v[186:189], 0
	v_mfma_f32_16x16x32_bf16 v[44:47], v[128:131], v[194:197], 0
	v_mfma_f32_16x16x32_bf16 v[40:43], v[136:139], v[194:197], 0
	v_mfma_f32_16x16x32_bf16 v[28:31], v[128:131], v[202:205], 0
	v_mfma_f32_16x16x32_bf16 v[24:27], v[136:139], v[202:205], 0
	v_mfma_f32_16x16x32_bf16 v[12:15], v[128:131], v[210:213], 0
	v_mfma_f32_16x16x32_bf16 v[8:11], v[136:139], v[210:213], 0
	v_mfma_f32_16x16x32_bf16 v[60:63], v[132:135], v[190:193], v[60:63]
	v_mfma_f32_16x16x32_bf16 v[56:59], v[140:143], v[190:193], v[56:59]
	v_mfma_f32_16x16x32_bf16 v[44:47], v[132:135], v[198:201], v[44:47]
	v_mfma_f32_16x16x32_bf16 v[40:43], v[140:143], v[198:201], v[40:43]
	v_mfma_f32_16x16x32_bf16 v[28:31], v[132:135], v[206:209], v[28:31]
	v_mfma_f32_16x16x32_bf16 v[24:27], v[140:143], v[206:209], v[24:27]
	v_mfma_f32_16x16x32_bf16 v[12:15], v[132:135], v[214:217], v[12:15]
	v_mfma_f32_16x16x32_bf16 v[8:11], v[140:143], v[214:217], v[8:11]
	s_setprio 0
	s_setprio 1
	v_mfma_f32_16x16x32_bf16 v[52:55], v[160:163], v[186:189], 0
	v_mfma_f32_16x16x32_bf16 v[48:51], v[168:171], v[186:189], 0
	v_mfma_f32_16x16x32_bf16 v[36:39], v[160:163], v[194:197], 0
	v_mfma_f32_16x16x32_bf16 v[32:35], v[168:171], v[194:197], 0
	v_mfma_f32_16x16x32_bf16 v[20:23], v[160:163], v[202:205], 0
	v_mfma_f32_16x16x32_bf16 v[16:19], v[168:171], v[202:205], 0
	v_mfma_f32_16x16x32_bf16 v[4:7], v[160:163], v[210:213], 0
	v_mfma_f32_16x16x32_bf16 v[0:3], v[168:171], v[210:213], 0
	v_mfma_f32_16x16x32_bf16 v[52:55], v[164:167], v[190:193], v[52:55]
	v_mfma_f32_16x16x32_bf16 v[48:51], v[172:175], v[190:193], v[48:51]
	v_mfma_f32_16x16x32_bf16 v[36:39], v[164:167], v[198:201], v[36:39]
	v_mfma_f32_16x16x32_bf16 v[32:35], v[172:175], v[198:201], v[32:35]
	v_mfma_f32_16x16x32_bf16 v[20:23], v[164:167], v[206:209], v[20:23]
	v_mfma_f32_16x16x32_bf16 v[16:19], v[172:175], v[206:209], v[16:19]
	v_mfma_f32_16x16x32_bf16 v[4:7], v[164:167], v[214:217], v[4:7]
	v_mfma_f32_16x16x32_bf16 v[0:3], v[172:175], v[214:217], v[0:3]
	s_setprio 0
	s_barrier
	s_add_i32 s74, 0, 0x18000
	s_add_i32 s75, 0, 0x1c000
	v_add_u32_e32 v140, s74, v181
	v_add_u32_e32 v172, s75, v181
	ds_read_b128 v[128:131], v140
	ds_read_b128 v[132:135], v140 offset:1024
	ds_read_b128 v[136:139], v140 offset:2048
	ds_read_b128 v[140:143], v140 offset:3072
	ds_read_b128 v[160:163], v172
	ds_read_b128 v[164:167], v172 offset:1024
	ds_read_b128 v[168:171], v172 offset:2048
	ds_read_b128 v[172:175], v172 offset:3072
	s_add_u32 s52, s52, 0x100000
	s_addc_u32 s53, s53, 0
	s_mov_b32 m0, s56
	v_lshl_add_u64 v[224:225], s[52:53], 0, v[144:145]
	ds_read_b128 v[186:189], v184 offset:32768
	ds_read_b128 v[190:193], v184 offset:33792
	ds_read_b128 v[194:197], v184 offset:34816
	ds_read_b128 v[198:201], v184 offset:35840
	ds_read_b128 v[202:205], v184 offset:36864
	ds_read_b128 v[206:209], v184 offset:37888
	ds_read_b128 v[210:213], v184 offset:38912
	ds_read_b128 v[214:217], v184 offset:39936
	global_load_lds_dwordx4 v[224:225], off
	v_lshl_add_u64 v[224:225], s[52:53], 0, v[148:149]
	s_mov_b32 m0, s57
	s_nop 0
	global_load_lds_dwordx4 v[224:225], off
	s_waitcnt vmcnt(8)
	s_waitcnt lgkmcnt(0)
	s_barrier
	s_setprio 1
	s_waitcnt lgkmcnt(0)
	v_mfma_f32_16x16x32_bf16 v[124:127], v[128:131], v[186:189], v[124:127]
	v_mfma_f32_16x16x32_bf16 v[120:123], v[136:139], v[186:189], v[120:123]
	v_mfma_f32_16x16x32_bf16 v[108:111], v[128:131], v[194:197], v[108:111]
	v_mfma_f32_16x16x32_bf16 v[104:107], v[136:139], v[194:197], v[104:107]
	v_mfma_f32_16x16x32_bf16 v[92:95], v[128:131], v[202:205], v[92:95]
	v_mfma_f32_16x16x32_bf16 v[88:91], v[136:139], v[202:205], v[88:91]
	v_mfma_f32_16x16x32_bf16 v[76:79], v[128:131], v[210:213], v[76:79]
	v_mfma_f32_16x16x32_bf16 v[72:75], v[136:139], v[210:213], v[72:75]
	v_mfma_f32_16x16x32_bf16 v[124:127], v[132:135], v[190:193], v[124:127]
	v_mfma_f32_16x16x32_bf16 v[120:123], v[140:143], v[190:193], v[120:123]
	v_mfma_f32_16x16x32_bf16 v[108:111], v[132:135], v[198:201], v[108:111]
	v_mfma_f32_16x16x32_bf16 v[104:107], v[140:143], v[198:201], v[104:107]
	v_mfma_f32_16x16x32_bf16 v[92:95], v[132:135], v[206:209], v[92:95]
	v_mfma_f32_16x16x32_bf16 v[88:91], v[140:143], v[206:209], v[88:91]
	v_mfma_f32_16x16x32_bf16 v[76:79], v[132:135], v[214:217], v[76:79]
	v_mfma_f32_16x16x32_bf16 v[72:75], v[140:143], v[214:217], v[72:75]
	s_setprio 0
	s_setprio 1
	v_mfma_f32_16x16x32_bf16 v[116:119], v[160:163], v[186:189], v[116:119]
	v_mfma_f32_16x16x32_bf16 v[112:115], v[168:171], v[186:189], v[112:115]
	v_mfma_f32_16x16x32_bf16 v[100:103], v[160:163], v[194:197], v[100:103]
	v_mfma_f32_16x16x32_bf16 v[96:99], v[168:171], v[194:197], v[96:99]
	v_mfma_f32_16x16x32_bf16 v[84:87], v[160:163], v[202:205], v[84:87]
	v_mfma_f32_16x16x32_bf16 v[80:83], v[168:171], v[202:205], v[80:83]
	v_mfma_f32_16x16x32_bf16 v[68:71], v[160:163], v[210:213], v[68:71]
	v_mfma_f32_16x16x32_bf16 v[64:67], v[168:171], v[210:213], v[64:67]
	v_mfma_f32_16x16x32_bf16 v[116:119], v[164:167], v[190:193], v[116:119]
	v_mfma_f32_16x16x32_bf16 v[112:115], v[172:175], v[190:193], v[112:115]
	v_mfma_f32_16x16x32_bf16 v[100:103], v[164:167], v[198:201], v[100:103]
	v_mfma_f32_16x16x32_bf16 v[96:99], v[172:175], v[198:201], v[96:99]
	v_mfma_f32_16x16x32_bf16 v[84:87], v[164:167], v[206:209], v[84:87]
	v_mfma_f32_16x16x32_bf16 v[80:83], v[172:175], v[206:209], v[80:83]
	v_mfma_f32_16x16x32_bf16 v[68:71], v[164:167], v[214:217], v[68:71]
	v_mfma_f32_16x16x32_bf16 v[64:67], v[172:175], v[214:217], v[64:67]
	s_setprio 0
	s_barrier
; #define PG8_STAGE(bufoff, gbase, voff) do { _Pragma("unroll") for (int _i = 0; _i < 2; ++_i) \
;         __builtin_amdgcn_global_load_lds((const unsigned*)((const char*)(gbase) + (voff)[_i]), (LAS unsigned*)(lds + (bufoff) + ldsw + _i * 8192), 16, 0, 0); } while (0)
; #define PG8_LDA(dst, b, h) do { _Pragma("unroll") for (int m = 0; m < 4; ++m) _Pragma("unroll") for (int k = 0; k < 2; ++k) dst[m][k] = *(const LAS bf16x8*)(lds + PG8_SA(b, h) + aoff + m * 2048 + k * 1024); } while (0)
; #define PG8_LDB(dst, b, h) do { _Pragma("unroll") for (int n = 0; n < 2; ++n) _Pragma("unroll") for (int k = 0; k < 2; ++k) dst[n][k] = *(const LAS bf16x8*)(lds + PG8_SB(b, h) + boff + n * 2048 + k * 1024); } while (0)
; #define PG8_WAIT_V(n) asm volatile("s_waitcnt vmcnt(" #n ")" ::: "memory")
; #define PG8_WAIT_L(n) asm volatile("s_waitcnt lgkmcnt(" #n ")" ::: "memory")
; template <class Epi>
; __device__ __forceinline__ void gemm_phase(LAS unsigned char* lds, const Gemm g, const StaticOrder& S, const Epi& E) {
;     ...
;         for (int t = 0; t < nt; t += 2) {
;             const bool last = (t == nt - 2);
;             const char* a1 = cA + (size_t)(t + 1) * kstep;
;             const char* a2 = last ? nA : cA + (size_t)(t + 2) * kstep; const char* b2 = last ? nB : cB + (size_t)(t + 2) * kstep;
;             const char* a3 = a2 + kstep; const char* b3 = b2 + kstep;
;             PG8_LDB(B0, 0, 0); PG8_LDB(B1, 0, 1); PG8_SCHED; PG8_LDA(At, 0, 0); PG8_STAGE(PG8_SA(1, 1), a1 + hstepA, voffA);
;             PG8_WAIT_V(8); PG8_WAIT_L(0); PG8_BAR; PG8_MMA(0, 0, At, B0); PG8_MMA(0, 1, At, B1); PG8_BAR; PG8_SCHED;
;             PG8_LDA(At, 0, 1); PG8_STAGE(PG8_SB(0, 0), b2, voffB); PG8_STAGE(PG8_SB(0, 1), b2 + hstepB, voffB); PG8_STAGE(PG8_SA(0, 0), a2, voffA);
;             PG8_WAIT_V(8); PG8_WAIT_L(0); PG8_BAR; PG8_MMA(1, 0, At, B0); PG8_MMA(1, 1, At, B1); PG8_BAR; PG8_SCHED;
;             PG8_LDB(B0, 1, 0); PG8_LDB(B1, 1, 1); PG8_SCHED; PG8_LDA(At, 1, 0); PG8_STAGE(PG8_SA(0, 1), a2 + hstepA, voffA);
;             PG8_WAIT_V(8); PG8_WAIT_L(0); PG8_BAR; PG8_MMA(0, 0, At, B0); PG8_MMA(0, 1, At, B1); PG8_BAR; PG8_SCHED;
;             PG8_LDA(At, 1, 1); PG8_STAGE(PG8_SB(1, 0), b3, voffB); PG8_STAGE(PG8_SB(1, 1), b3 + hstepB, voffB); PG8_STAGE(PG8_SA(1, 0), a3, voffA);
;             PG8_WAIT_V(8); PG8_WAIT_L(0); PG8_BAR; PG8_MMA(1, 0, At, B0); PG8_MMA(1, 1, At, B1); PG8_BAR; PG8_SCHED;
	s_add_i32 s52, s74, s54
	v_lshl_add_u64 v[178:179], v[178:179], 0, s[12:13]
	s_mov_b32 m0, s52
	ds_read_b128 v[186:189], v184 offset:49152
	ds_read_b128 v[190:193], v184 offset:50176
	ds_read_b128 v[194:197], v184 offset:51200
	ds_read_b128 v[198:201], v184 offset:52224
	ds_read_b128 v[202:205], v184 offset:53248
	ds_read_b128 v[206:209], v184 offset:54272
	ds_read_b128 v[210:213], v184 offset:55296
	ds_read_b128 v[214:217], v184 offset:56320
	global_load_lds_dwordx4 v[178:179], off
	s_add_i32 m0, s52, 0x2000
	s_add_u32 s42, s42, 0x80080
	v_lshl_add_u64 v[178:179], v[218:219], 0, s[12:13]
	s_addc_u32 s43, s43, 0
	s_add_i32 s52, s75, s54
	global_load_lds_dwordx4 v[178:179], off
	v_lshl_add_u64 v[178:179], s[42:43], 0, v[146:147]
	s_mov_b32 m0, s52
	s_nop 0
	global_load_lds_dwordx4 v[178:179], off
	v_lshl_add_u64 v[178:179], s[42:43], 0, v[150:151]
	s_add_i32 m0, s52, 0x2000
	s_nop 0
	global_load_lds_dwordx4 v[178:179], off
	v_lshl_add_u64 v[178:179], v[220:221], 0, s[12:13]
	s_mov_b32 m0, s61
	s_nop 0
	global_load_lds_dwordx4 v[178:179], off
	v_lshl_add_u64 v[178:179], v[222:223], 0, s[12:13]
	s_mov_b32 m0, s62
	s_nop 0
	global_load_lds_dwordx4 v[178:179], off
	s_waitcnt vmcnt(8)
	s_waitcnt lgkmcnt(0)
	s_barrier
	s_setprio 1
	s_waitcnt lgkmcnt(0)
	v_mfma_f32_16x16x32_bf16 v[60:63], v[128:131], v[186:189], v[60:63]
	v_mfma_f32_16x16x32_bf16 v[56:59], v[136:139], v[186:189], v[56:59]
	v_mfma_f32_16x16x32_bf16 v[44:47], v[128:131], v[194:197], v[44:47]
	v_mfma_f32_16x16x32_bf16 v[40:43], v[136:139], v[194:197], v[40:43]
	v_mfma_f32_16x16x32_bf16 v[28:31], v[128:131], v[202:205], v[28:31]
	v_mfma_f32_16x16x32_bf16 v[24:27], v[136:139], v[202:205], v[24:27]
	v_mfma_f32_16x16x32_bf16 v[12:15], v[128:131], v[210:213], v[12:15]
	v_mfma_f32_16x16x32_bf16 v[8:11], v[136:139], v[210:213], v[8:11]
	v_mfma_f32_16x16x32_bf16 v[60:63], v[132:135], v[190:193], v[60:63]
	v_mfma_f32_16x16x32_bf16 v[56:59], v[140:143], v[190:193], v[56:59]
	v_mfma_f32_16x16x32_bf16 v[44:47], v[132:135], v[198:201], v[44:47]
	v_mfma_f32_16x16x32_bf16 v[40:43], v[140:143], v[198:201], v[40:43]
	v_mfma_f32_16x16x32_bf16 v[28:31], v[132:135], v[206:209], v[28:31]
	v_mfma_f32_16x16x32_bf16 v[24:27], v[140:143], v[206:209], v[24:27]
	v_mfma_f32_16x16x32_bf16 v[12:15], v[132:135], v[214:217], v[12:15]
	v_mfma_f32_16x16x32_bf16 v[8:11], v[140:143], v[214:217], v[8:11]
	s_setprio 0
	s_setprio 1
	v_mfma_f32_16x16x32_bf16 v[52:55], v[160:163], v[186:189], v[52:55]
	v_mfma_f32_16x16x32_bf16 v[48:51], v[168:171], v[186:189], v[48:51]
	v_mfma_f32_16x16x32_bf16 v[36:39], v[160:163], v[194:197], v[36:39]
	v_mfma_f32_16x16x32_bf16 v[32:35], v[168:171], v[194:197], v[32:35]
	v_mfma_f32_16x16x32_bf16 v[20:23], v[160:163], v[202:205], v[20:23]
	v_mfma_f32_16x16x32_bf16 v[16:19], v[168:171], v[202:205], v[16:19]
	v_mfma_f32_16x16x32_bf16 v[4:7], v[160:163], v[210:213], v[4:7]
	v_mfma_f32_16x16x32_bf16 v[0:3], v[168:171], v[210:213], v[0:3]
	v_mfma_f32_16x16x32_bf16 v[52:55], v[164:167], v[190:193], v[52:55]
	v_mfma_f32_16x16x32_bf16 v[48:51], v[172:175], v[190:193], v[48:51]
	v_mfma_f32_16x16x32_bf16 v[36:39], v[164:167], v[198:201], v[36:39]
	v_mfma_f32_16x16x32_bf16 v[32:35], v[172:175], v[198:201], v[32:35]
	v_mfma_f32_16x16x32_bf16 v[20:23], v[164:167], v[206:209], v[20:23]
	v_mfma_f32_16x16x32_bf16 v[16:19], v[172:175], v[206:209], v[16:19]
	v_mfma_f32_16x16x32_bf16 v[4:7], v[164:167], v[214:217], v[4:7]
	v_mfma_f32_16x16x32_bf16 v[0:3], v[172:175], v[214:217], v[0:3]
	s_setprio 0
	s_barrier
	s_add_i32 s73, s73, 2
	s_add_u32 s38, s38, 0x100
	s_addc_u32 s39, s39, 0
	s_add_u32 s71, s71, 0x100
	s_addc_u32 s72, s72, 0
	s_cmp_gt_u32 s73, 29

; #define PG8_STAGE(bufoff, gbase, voff) do { _Pragma("unroll") for (int _i = 0; _i < 2; ++_i) \
;         __builtin_amdgcn_global_load_lds((const unsigned*)((const char*)(gbase) + (voff)[_i]), (LAS unsigned*)(lds + (bufoff) + ldsw + _i * 8192), 16, 0, 0); } while (0)
; #define PG8_LDA(dst, b, h) do { _Pragma("unroll") for (int m = 0; m < 4; ++m) _Pragma("unroll") for (int k = 0; k < 2; ++k) dst[m][k] = *(const LAS bf16x8*)(lds + PG8_SA(b, h) + aoff + m * 2048 + k * 1024); } while (0)
; #define PG8_LDB(dst, b, h) do { _Pragma("unroll") for (int n = 0; n < 2; ++n) _Pragma("unroll") for (int k = 0; k < 2; ++k) dst[n][k] = *(const LAS bf16x8*)(lds + PG8_SB(b, h) + boff + n * 2048 + k * 1024); } while (0)
; #define PG8_MMA(ai, bj, At, Bt) do { __builtin_amdgcn_s_setprio(1); _Pragma("unroll") for (int m = 0; m < 4; ++m) _Pragma("unroll") for (int n = 0; n < 2; ++n) _Pragma("unroll") for (int k = 0; k < 2; ++k) \
;         acc[ai][bj][m][n] = __builtin_amdgcn_mfma_f32_16x16x32_bf16(Bt[n][k], At[m][k], acc[ai][bj][m][n], 0, 0, 0); __builtin_amdgcn_s_setprio(0); } while (0)
; #define PG8_WAIT_V(n) asm volatile("s_waitcnt vmcnt(" #n ")" ::: "memory")
; template <class Epi>
; __device__ __forceinline__ void gemm_phase(LAS unsigned char* lds, const Gemm g, const StaticOrder& S, const Epi& E) {
;     ...
;         const char* nA = has_next ? (const char*)g.A + (size_t)nxt.pm * tstepA : cA; const char* nB = has_next ? (const char*)g.Bt + (size_t)nxt.pn * tstepB : cB;
; #pragma nounroll
;         for (int t = 0; t < nt; t += 2) {
;             const bool last = (t == nt - 2);
;             const char* a1 = cA + (size_t)(t + 1) * kstep;
;             const char* a2 = last ? nA : cA + (size_t)(t + 2) * kstep; const char* b2 = last ? nB : cB + (size_t)(t + 2) * kstep;
;             const char* a3 = a2 + kstep; const char* b3 = b2 + kstep;
;             PG8_LDB(B0, 0, 0); PG8_LDB(B1, 0, 1); PG8_SCHED; PG8_LDA(At, 0, 0); PG8_STAGE(PG8_SA(1, 1), a1 + hstepA, voffA);
;             PG8_WAIT_V(8); PG8_WAIT_L(0); PG8_BAR; PG8_MMA(0, 0, At, B0); PG8_MMA(0, 1, At, B1); PG8_BAR; PG8_SCHED;
;             PG8_LDA(At, 0, 1); PG8_STAGE(PG8_SB(0, 0), b2, voffB); PG8_STAGE(PG8_SB(0, 1), b2 + hstepB, voffB); PG8_STAGE(PG8_SA(0, 0), a2, voffA);
;             PG8_WAIT_V(8); PG8_WAIT_L(0); PG8_BAR; PG8_MMA(1, 0, At, B0); PG8_MMA(1, 1, At, B1); PG8_BAR; PG8_SCHED;
.LBB0_1402:
	s_ashr_i32 s69, s68, 31
	s_lshl_b64 s[12:13], s[68:69], 19
	s_add_u32 s70, s24, s12
	s_addc_u32 s71, s25, s13
	s_and_b64 s[12:13], s[4:5], exec
	s_cselect_b32 s1, s71, s9
	s_cselect_b32 s7, s70, s8
	s_ashr_i32 s65, s64, 31
	s_lshl_b64 s[12:13], s[64:65], 19
	s_add_u32 s72, s3, s12
	s_addc_u32 s73, s33, s13
	s_and_b64 s[12:13], s[4:5], exec
	s_cselect_b32 s65, s73, s11
	s_cselect_b32 s69, s72, s10
	s_add_u32 s8, s8, 0x40080
	s_addc_u32 s9, s9, 0
	s_add_u32 s74, s10, 0x100
	s_addc_u32 s75, s11, 0
	s_mov_b32 s87, -2
	ds_read_b128 v[146:149], v162
	ds_read_b128 v[166:169], v162 offset:1024
	ds_read_b128 v[170:173], v162 offset:2048
	ds_read_b128 v[178:181], v162 offset:3072
	ds_read_b128 v[182:185], v163
	ds_read_b128 v[186:189], v163 offset:1024
	ds_read_b128 v[190:193], v163 offset:2048
	ds_read_b128 v[194:197], v163 offset:3072
	s_add_u32 s10, s8, 0xfffc0080
	s_addc_u32 s11, s9, -1
	s_cmp_eq_u32 s87, 12
	s_cselect_b32 s13, s1, s11
	s_cselect_b32 s12, s7, s10
	s_cselect_b32 s11, s65, s75
	s_cselect_b32 s10, s69, s74
	v_lshl_add_u64 v[174:175], s[8:9], 0, v[138:139]
	s_add_i32 m0, s53, 0xc000
	ds_read_b128 v[198:201], v164
	ds_read_b128 v[202:205], v164 offset:1024
	ds_read_b128 v[206:209], v164 offset:2048
	ds_read_b128 v[210:213], v164 offset:3072
	ds_read_b128 v[214:217], v164 offset:4096
	ds_read_b128 v[218:221], v164 offset:5120
	ds_read_b128 v[222:225], v164 offset:6144
	ds_read_b128 v[226:229], v164 offset:7168
	global_load_lds_dwordx4 v[174:175], off
	v_lshl_add_u64 v[174:175], s[8:9], 0, v[140:141]
	s_add_i32 m0, s53, 0xe000
	s_nop 0
	global_load_lds_dwordx4 v[174:175], off
	s_waitcnt vmcnt(8)
	s_waitcnt lgkmcnt(0)
	s_barrier
	s_setprio 1
	s_waitcnt lgkmcnt(0)
	v_mfma_f32_16x16x32_bf16 v[124:127], v[146:149], v[198:201], 0
	v_mfma_f32_16x16x32_bf16 v[120:123], v[170:173], v[198:201], 0
	v_mfma_f32_16x16x32_bf16 v[112:115], v[146:149], v[206:209], 0
	v_mfma_f32_16x16x32_bf16 v[104:107], v[170:173], v[206:209], 0
	v_mfma_f32_16x16x32_bf16 v[100:103], v[146:149], v[214:217], 0
	v_mfma_f32_16x16x32_bf16 v[92:95], v[170:173], v[214:217], 0
	v_mfma_f32_16x16x32_bf16 v[84:87], v[146:149], v[222:225], 0
	v_mfma_f32_16x16x32_bf16 v[76:79], v[170:173], v[222:225], 0
	v_mfma_f32_16x16x32_bf16 v[124:127], v[166:169], v[202:205], v[124:127]
	v_mfma_f32_16x16x32_bf16 v[120:123], v[178:181], v[202:205], v[120:123]
	v_mfma_f32_16x16x32_bf16 v[112:115], v[166:169], v[210:213], v[112:115]
	v_mfma_f32_16x16x32_bf16 v[104:107], v[178:181], v[210:213], v[104:107]
	v_mfma_f32_16x16x32_bf16 v[100:103], v[166:169], v[218:221], v[100:103]
	v_mfma_f32_16x16x32_bf16 v[92:95], v[178:181], v[218:221], v[92:95]
	v_mfma_f32_16x16x32_bf16 v[84:87], v[166:169], v[226:229], v[84:87]
	v_mfma_f32_16x16x32_bf16 v[76:79], v[178:181], v[226:229], v[76:79]
	s_setprio 0
	s_setprio 1
	v_mfma_f32_16x16x32_bf16 v[116:119], v[182:185], v[198:201], 0
	v_mfma_f32_16x16x32_bf16 v[108:111], v[190:193], v[198:201], 0
	v_mfma_f32_16x16x32_bf16 v[96:99], v[182:185], v[206:209], 0
	v_mfma_f32_16x16x32_bf16 v[88:91], v[190:193], v[206:209], 0
	v_mfma_f32_16x16x32_bf16 v[80:83], v[182:185], v[214:217], 0
	v_mfma_f32_16x16x32_bf16 v[72:75], v[190:193], v[214:217], 0
	v_mfma_f32_16x16x32_bf16 v[68:71], v[182:185], v[222:225], 0
	v_mfma_f32_16x16x32_bf16 v[64:67], v[190:193], v[222:225], 0
	v_mfma_f32_16x16x32_bf16 v[116:119], v[186:189], v[202:205], v[116:119]
	v_mfma_f32_16x16x32_bf16 v[108:111], v[194:197], v[202:205], v[108:111]
	v_mfma_f32_16x16x32_bf16 v[96:99], v[186:189], v[210:213], v[96:99]
	v_mfma_f32_16x16x32_bf16 v[88:91], v[194:197], v[210:213], v[88:91]
	v_mfma_f32_16x16x32_bf16 v[80:83], v[186:189], v[218:221], v[80:83]
	v_mfma_f32_16x16x32_bf16 v[72:75], v[194:197], v[218:221], v[72:75]
	v_mfma_f32_16x16x32_bf16 v[68:71], v[186:189], v[226:229], v[68:71]
	v_mfma_f32_16x16x32_bf16 v[64:67], v[194:197], v[226:229], v[64:67]
	s_setprio 0
	s_barrier
	s_add_i32 s88, s83, s43
	v_lshl_add_u64 v[174:175], s[10:11], 0, v[130:131]
	s_mov_b32 m0, s88
	ds_read_b128 v[198:201], v164 offset:16384
	ds_read_b128 v[202:205], v164 offset:17408
	ds_read_b128 v[206:209], v164 offset:18432
	ds_read_b128 v[210:213], v164 offset:19456
	ds_read_b128 v[214:217], v164 offset:20480
	ds_read_b128 v[218:221], v164 offset:21504
	ds_read_b128 v[222:225], v164 offset:22528
	ds_read_b128 v[226:229], v164 offset:23552
	global_load_lds_dwordx4 v[174:175], off
	s_add_i32 m0, s88, 0x2000
	s_add_u32 s88, s10, 0x40000
	v_lshl_add_u64 v[230:231], s[10:11], 0, v[134:135]
	s_addc_u32 s89, s11, 0
	s_add_i32 s90, s84, s43
	global_load_lds_dwordx4 v[230:231], off
	v_lshl_add_u64 v[232:233], s[88:89], 0, v[130:131]
	s_mov_b32 m0, s90
	v_lshl_add_u64 v[234:235], s[12:13], 0, v[132:133]
	global_load_lds_dwordx4 v[232:233], off
	v_lshl_add_u64 v[232:233], s[88:89], 0, v[134:135]
	s_add_i32 m0, s90, 0x2000
	s_nop 0
	global_load_lds_dwordx4 v[232:233], off
	v_lshl_add_u64 v[232:233], s[12:13], 0, v[128:129]
	s_mov_b32 m0, s53
	s_nop 0
	global_load_lds_dwordx4 v[232:233], off
	s_mov_b32 m0, s55
	s_nop 0
	global_load_lds_dwordx4 v[234:235], off
	s_waitcnt vmcnt(8)
	s_waitcnt lgkmcnt(0)
	s_barrier
; #define PG8_STAGE(bufoff, gbase, voff) do { _Pragma("unroll") for (int _i = 0; _i < 2; ++_i) \
;         __builtin_amdgcn_global_load_lds((const unsigned*)((const char*)(gbase) + (voff)[_i]), (LAS unsigned*)(lds + (bufoff) + ldsw + _i * 8192), 16, 0, 0); } while (0)
; #define PG8_LDA(dst, b, h) do { _Pragma("unroll") for (int m = 0; m < 4; ++m) _Pragma("unroll") for (int k = 0; k < 2; ++k) dst[m][k] = *(const LAS bf16x8*)(lds + PG8_SA(b, h) + aoff + m * 2048 + k * 1024); } while (0)
; #define PG8_LDB(dst, b, h) do { _Pragma("unroll") for (int n = 0; n < 2; ++n) _Pragma("unroll") for (int k = 0; k < 2; ++k) dst[n][k] = *(const LAS bf16x8*)(lds + PG8_SB(b, h) + boff + n * 2048 + k * 1024); } while (0)
; #define PG8_MMA(ai, bj, At, Bt) do { __builtin_amdgcn_s_setprio(1); _Pragma("unroll") for (int m = 0; m < 4; ++m) _Pragma("unroll") for (int n = 0; n < 2; ++n) _Pragma("unroll") for (int k = 0; k < 2; ++k) \
;         acc[ai][bj][m][n] = __builtin_amdgcn_mfma_f32_16x16x32_bf16(Bt[n][k], At[m][k], acc[ai][bj][m][n], 0, 0, 0); __builtin_amdgcn_s_setprio(0); } while (0)
; #define PG8_WAIT_V(n) asm volatile("s_waitcnt vmcnt(" #n ")" ::: "memory")
; #define PG8_WAIT_L(n) asm volatile("s_waitcnt lgkmcnt(" #n ")" ::: "memory")
; #define PG8_BAR __builtin_amdgcn_s_barrier()
; #define PG8_SCHED __builtin_amdgcn_sched_barrier(0)
; template <class Epi>
; __device__ __forceinline__ void gemm_phase(LAS unsigned char* lds, const Gemm g, const StaticOrder& S, const Epi& E) {
;     ...
;             PG8_WAIT_V(8); PG8_WAIT_L(0); PG8_BAR; PG8_MMA(1, 0, At, B0); PG8_MMA(1, 1, At, B1); PG8_BAR; PG8_SCHED;
;             PG8_LDB(B0, 1, 0); PG8_LDB(B1, 1, 1); PG8_SCHED; PG8_LDA(At, 1, 0); PG8_STAGE(PG8_SA(0, 1), a2 + hstepA, voffA);
;             PG8_WAIT_V(8); PG8_WAIT_L(0); PG8_BAR; PG8_MMA(0, 0, At, B0); PG8_MMA(0, 1, At, B1); PG8_BAR; PG8_SCHED;
;             PG8_LDA(At, 1, 1); PG8_STAGE(PG8_SB(1, 0), b3, voffB); PG8_STAGE(PG8_SB(1, 1), b3 + hstepB, voffB); PG8_STAGE(PG8_SA(1, 0), a3, voffA);
	s_setprio 1
	s_waitcnt lgkmcnt(0)
	v_mfma_f32_16x16x32_bf16 v[60:63], v[146:149], v[198:201], 0
	v_mfma_f32_16x16x32_bf16 v[56:59], v[170:173], v[198:201], 0
	v_mfma_f32_16x16x32_bf16 v[52:55], v[146:149], v[206:209], 0
	v_mfma_f32_16x16x32_bf16 v[44:47], v[170:173], v[206:209], 0
	v_mfma_f32_16x16x32_bf16 v[36:39], v[146:149], v[214:217], 0
	v_mfma_f32_16x16x32_bf16 v[28:31], v[170:173], v[214:217], 0
	v_mfma_f32_16x16x32_bf16 v[20:23], v[146:149], v[222:225], 0
	v_mfma_f32_16x16x32_bf16 v[12:15], v[170:173], v[222:225], 0
	v_mfma_f32_16x16x32_bf16 v[60:63], v[166:169], v[202:205], v[60:63]
	v_mfma_f32_16x16x32_bf16 v[56:59], v[178:181], v[202:205], v[56:59]
	v_mfma_f32_16x16x32_bf16 v[52:55], v[166:169], v[210:213], v[52:55]
	v_mfma_f32_16x16x32_bf16 v[44:47], v[178:181], v[210:213], v[44:47]
	v_mfma_f32_16x16x32_bf16 v[36:39], v[166:169], v[218:221], v[36:39]
	v_mfma_f32_16x16x32_bf16 v[28:31], v[178:181], v[218:221], v[28:31]
	v_mfma_f32_16x16x32_bf16 v[20:23], v[166:169], v[226:229], v[20:23]
	v_mfma_f32_16x16x32_bf16 v[12:15], v[178:181], v[226:229], v[12:15]
	s_setprio 0
	s_setprio 1
	v_mfma_f32_16x16x32_bf16 v[48:51], v[182:185], v[198:201], 0
	v_mfma_f32_16x16x32_bf16 v[40:43], v[190:193], v[198:201], 0
	v_mfma_f32_16x16x32_bf16 v[32:35], v[182:185], v[206:209], 0
	v_mfma_f32_16x16x32_bf16 v[24:27], v[190:193], v[206:209], 0
	v_mfma_f32_16x16x32_bf16 v[16:19], v[182:185], v[214:217], 0
	v_mfma_f32_16x16x32_bf16 v[8:11], v[190:193], v[214:217], 0
	v_mfma_f32_16x16x32_bf16 v[4:7], v[182:185], v[222:225], 0
	v_mfma_f32_16x16x32_bf16 v[0:3], v[190:193], v[222:225], 0
	v_mfma_f32_16x16x32_bf16 v[48:51], v[186:189], v[202:205], v[48:51]
	v_mfma_f32_16x16x32_bf16 v[40:43], v[194:197], v[202:205], v[40:43]
	v_mfma_f32_16x16x32_bf16 v[32:35], v[186:189], v[210:213], v[32:35]
	v_mfma_f32_16x16x32_bf16 v[24:27], v[194:197], v[210:213], v[24:27]
	v_mfma_f32_16x16x32_bf16 v[16:19], v[186:189], v[218:221], v[16:19]
	v_mfma_f32_16x16x32_bf16 v[8:11], v[194:197], v[218:221], v[8:11]
	v_mfma_f32_16x16x32_bf16 v[4:7], v[186:189], v[226:229], v[4:7]
	v_mfma_f32_16x16x32_bf16 v[0:3], v[194:197], v[226:229], v[0:3]
	s_setprio 0
	s_barrier
	s_add_i32 s88, 0, 0x18000
	v_add_u32_e32 v136, s88, v161
	s_add_i32 s89, 0, 0x1c000
	ds_read_b128 v[146:149], v136
	ds_read_b128 v[166:169], v136 offset:1024
	ds_read_b128 v[170:173], v136 offset:2048
	ds_read_b128 v[178:181], v136 offset:3072
	v_add_u32_e32 v136, s89, v161
	ds_read_b128 v[182:185], v136
	ds_read_b128 v[186:189], v136 offset:1024
	ds_read_b128 v[190:193], v136 offset:2048
	ds_read_b128 v[194:197], v136 offset:3072
	s_add_u32 s12, s12, 0x40000
	s_addc_u32 s13, s13, 0
	s_mov_b32 m0, s57
	v_lshl_add_u64 v[236:237], s[12:13], 0, v[128:129]
	ds_read_b128 v[198:201], v164 offset:32768
	ds_read_b128 v[202:205], v164 offset:33792
	ds_read_b128 v[206:209], v164 offset:34816
	ds_read_b128 v[210:213], v164 offset:35840
	ds_read_b128 v[214:217], v164 offset:36864
	ds_read_b128 v[218:221], v164 offset:37888
	ds_read_b128 v[222:225], v164 offset:38912
	ds_read_b128 v[226:229], v164 offset:39936
	global_load_lds_dwordx4 v[236:237], off
	v_lshl_add_u64 v[236:237], s[12:13], 0, v[132:133]
	s_mov_b32 m0, s59
	s_nop 0
	global_load_lds_dwordx4 v[236:237], off
	s_waitcnt vmcnt(8)
	s_waitcnt lgkmcnt(0)
	s_barrier
	s_setprio 1
	s_waitcnt lgkmcnt(0)
	v_mfma_f32_16x16x32_bf16 v[124:127], v[146:149], v[198:201], v[124:127]
	v_mfma_f32_16x16x32_bf16 v[120:123], v[170:173], v[198:201], v[120:123]
	v_mfma_f32_16x16x32_bf16 v[112:115], v[146:149], v[206:209], v[112:115]
	v_mfma_f32_16x16x32_bf16 v[104:107], v[170:173], v[206:209], v[104:107]
	v_mfma_f32_16x16x32_bf16 v[100:103], v[146:149], v[214:217], v[100:103]
	v_mfma_f32_16x16x32_bf16 v[92:95], v[170:173], v[214:217], v[92:95]
	v_mfma_f32_16x16x32_bf16 v[84:87], v[146:149], v[222:225], v[84:87]
	v_mfma_f32_16x16x32_bf16 v[76:79], v[170:173], v[222:225], v[76:79]
	v_mfma_f32_16x16x32_bf16 v[124:127], v[166:169], v[202:205], v[124:127]
	v_mfma_f32_16x16x32_bf16 v[120:123], v[178:181], v[202:205], v[120:123]
	v_mfma_f32_16x16x32_bf16 v[112:115], v[166:169], v[210:213], v[112:115]
	v_mfma_f32_16x16x32_bf16 v[104:107], v[178:181], v[210:213], v[104:107]
	v_mfma_f32_16x16x32_bf16 v[100:103], v[166:169], v[218:221], v[100:103]
	v_mfma_f32_16x16x32_bf16 v[92:95], v[178:181], v[218:221], v[92:95]
	v_mfma_f32_16x16x32_bf16 v[84:87], v[166:169], v[226:229], v[84:87]
	v_mfma_f32_16x16x32_bf16 v[76:79], v[178:181], v[226:229], v[76:79]
	s_setprio 0
	s_setprio 1
	v_mfma_f32_16x16x32_bf16 v[116:119], v[182:185], v[198:201], v[116:119]
	v_mfma_f32_16x16x32_bf16 v[108:111], v[190:193], v[198:201], v[108:111]
	v_mfma_f32_16x16x32_bf16 v[96:99], v[182:185], v[206:209], v[96:99]
	v_mfma_f32_16x16x32_bf16 v[88:91], v[190:193], v[206:209], v[88:91]
	v_mfma_f32_16x16x32_bf16 v[80:83], v[182:185], v[214:217], v[80:83]
	v_mfma_f32_16x16x32_bf16 v[72:75], v[190:193], v[214:217], v[72:75]
	v_mfma_f32_16x16x32_bf16 v[68:71], v[182:185], v[222:225], v[68:71]
	v_mfma_f32_16x16x32_bf16 v[64:67], v[190:193], v[222:225], v[64:67]
	v_mfma_f32_16x16x32_bf16 v[116:119], v[186:189], v[202:205], v[116:119]
	v_mfma_f32_16x16x32_bf16 v[108:111], v[194:197], v[202:205], v[108:111]
	v_mfma_f32_16x16x32_bf16 v[96:99], v[186:189], v[210:213], v[96:99]
	v_mfma_f32_16x16x32_bf16 v[88:91], v[194:197], v[210:213], v[88:91]
	v_mfma_f32_16x16x32_bf16 v[80:83], v[186:189], v[218:221], v[80:83]
	v_mfma_f32_16x16x32_bf16 v[72:75], v[194:197], v[218:221], v[72:75]
	v_mfma_f32_16x16x32_bf16 v[68:71], v[186:189], v[226:229], v[68:71]
	v_mfma_f32_16x16x32_bf16 v[64:67], v[194:197], v[226:229], v[64:67]
	s_setprio 0
	s_barrier
; #define PG8_STAGE(bufoff, gbase, voff) do { _Pragma("unroll") for (int _i = 0; _i < 2; ++_i) \
;         __builtin_amdgcn_global_load_lds((const unsigned*)((const char*)(gbase) + (voff)[_i]), (LAS unsigned*)(lds + (bufoff) + ldsw + _i * 8192), 16, 0, 0); } while (0)
; #define PG8_LDA(dst, b, h) do { _Pragma("unroll") for (int m = 0; m < 4; ++m) _Pragma("unroll") for (int k = 0; k < 2; ++k) dst[m][k] = *(const LAS bf16x8*)(lds + PG8_SA(b, h) + aoff + m * 2048 + k * 1024); } while (0)
; #define PG8_LDB(dst, b, h) do { _Pragma("unroll") for (int n = 0; n < 2; ++n) _Pragma("unroll") for (int k = 0; k < 2; ++k) dst[n][k] = *(const LAS bf16x8*)(lds + PG8_SB(b, h) + boff + n * 2048 + k * 1024); } while (0)
; #define PG8_WAIT_V(n) asm volatile("s_waitcnt vmcnt(" #n ")" ::: "memory")
; #define PG8_WAIT_L(n) asm volatile("s_waitcnt lgkmcnt(" #n ")" ::: "memory")
; template <class Epi>
; __device__ __forceinline__ void gemm_phase(LAS unsigned char* lds, const Gemm g, const StaticOrder& S, const Epi& E) {
;     ...
;         for (int t = 0; t < nt; t += 2) {
;             const bool last = (t == nt - 2);
;             const char* a1 = cA + (size_t)(t + 1) * kstep;
;             const char* a2 = last ? nA : cA + (size_t)(t + 2) * kstep; const char* b2 = last ? nB : cB + (size_t)(t + 2) * kstep;
;             const char* a3 = a2 + kstep; const char* b3 = b2 + kstep;
;             PG8_LDB(B0, 0, 0); PG8_LDB(B1, 0, 1); PG8_SCHED; PG8_LDA(At, 0, 0); PG8_STAGE(PG8_SA(1, 1), a1 + hstepA, voffA);
;             PG8_WAIT_V(8); PG8_WAIT_L(0); PG8_BAR; PG8_MMA(0, 0, At, B0); PG8_MMA(0, 1, At, B1); PG8_BAR; PG8_SCHED;
;             PG8_LDA(At, 0, 1); PG8_STAGE(PG8_SB(0, 0), b2, voffB); PG8_STAGE(PG8_SB(0, 1), b2 + hstepB, voffB); PG8_STAGE(PG8_SA(0, 0), a2, voffA);
;             PG8_WAIT_V(8); PG8_WAIT_L(0); PG8_BAR; PG8_MMA(1, 0, At, B0); PG8_MMA(1, 1, At, B1); PG8_BAR; PG8_SCHED;
;             PG8_LDB(B0, 1, 0); PG8_LDB(B1, 1, 1); PG8_SCHED; PG8_LDA(At, 1, 0); PG8_STAGE(PG8_SA(0, 1), a2 + hstepA, voffA);
;             PG8_WAIT_V(8); PG8_WAIT_L(0); PG8_BAR; PG8_MMA(0, 0, At, B0); PG8_MMA(0, 1, At, B1); PG8_BAR; PG8_SCHED;
;             PG8_LDA(At, 1, 1); PG8_STAGE(PG8_SB(1, 0), b3, voffB); PG8_STAGE(PG8_SB(1, 1), b3 + hstepB, voffB); PG8_STAGE(PG8_SA(1, 0), a3, voffA);
;             PG8_WAIT_V(8); PG8_WAIT_L(0); PG8_BAR; PG8_MMA(1, 0, At, B0); PG8_MMA(1, 1, At, B1); PG8_BAR; PG8_SCHED;
	s_add_i32 s12, s88, s43
	v_lshl_add_u64 v[174:175], v[174:175], 0, s[34:35]
	s_mov_b32 m0, s12
	ds_read_b128 v[198:201], v164 offset:49152
	ds_read_b128 v[202:205], v164 offset:50176
	ds_read_b128 v[206:209], v164 offset:51200
	ds_read_b128 v[210:213], v164 offset:52224
	ds_read_b128 v[214:217], v164 offset:53248
	ds_read_b128 v[218:221], v164 offset:54272
	ds_read_b128 v[222:225], v164 offset:55296
	ds_read_b128 v[226:229], v164 offset:56320
	global_load_lds_dwordx4 v[174:175], off
	s_add_i32 m0, s12, 0x2000
	s_add_u32 s10, s10, 0x40080
	v_lshl_add_u64 v[174:175], v[230:231], 0, s[34:35]
	s_addc_u32 s11, s11, 0
	s_add_i32 s12, s89, s43
	global_load_lds_dwordx4 v[174:175], off
	v_lshl_add_u64 v[174:175], s[10:11], 0, v[130:131]
	s_mov_b32 m0, s12
	s_nop 0
	global_load_lds_dwordx4 v[174:175], off
	v_lshl_add_u64 v[174:175], s[10:11], 0, v[134:135]
	s_add_i32 m0, s12, 0x2000
	s_nop 0
	global_load_lds_dwordx4 v[174:175], off
	v_lshl_add_u64 v[174:175], v[232:233], 0, s[34:35]
	s_mov_b32 m0, s77
	s_nop 0
	global_load_lds_dwordx4 v[174:175], off
	v_lshl_add_u64 v[174:175], v[234:235], 0, s[34:35]
	s_mov_b32 m0, s78
	s_nop 0
	global_load_lds_dwordx4 v[174:175], off
	s_waitcnt vmcnt(8)
	s_waitcnt lgkmcnt(0)
	s_barrier
	s_setprio 1
	s_waitcnt lgkmcnt(0)
	v_mfma_f32_16x16x32_bf16 v[60:63], v[146:149], v[198:201], v[60:63]
	v_mfma_f32_16x16x32_bf16 v[56:59], v[170:173], v[198:201], v[56:59]
	v_mfma_f32_16x16x32_bf16 v[52:55], v[146:149], v[206:209], v[52:55]
	v_mfma_f32_16x16x32_bf16 v[44:47], v[170:173], v[206:209], v[44:47]
	v_mfma_f32_16x16x32_bf16 v[36:39], v[146:149], v[214:217], v[36:39]
	v_mfma_f32_16x16x32_bf16 v[28:31], v[170:173], v[214:217], v[28:31]
	v_mfma_f32_16x16x32_bf16 v[20:23], v[146:149], v[222:225], v[20:23]
	v_mfma_f32_16x16x32_bf16 v[12:15], v[170:173], v[222:225], v[12:15]
	v_mfma_f32_16x16x32_bf16 v[60:63], v[166:169], v[202:205], v[60:63]
	v_mfma_f32_16x16x32_bf16 v[56:59], v[178:181], v[202:205], v[56:59]
	v_mfma_f32_16x16x32_bf16 v[52:55], v[166:169], v[210:213], v[52:55]
	v_mfma_f32_16x16x32_bf16 v[44:47], v[178:181], v[210:213], v[44:47]
	v_mfma_f32_16x16x32_bf16 v[36:39], v[166:169], v[218:221], v[36:39]
	v_mfma_f32_16x16x32_bf16 v[28:31], v[178:181], v[218:221], v[28:31]
	v_mfma_f32_16x16x32_bf16 v[20:23], v[166:169], v[226:229], v[20:23]
	v_mfma_f32_16x16x32_bf16 v[12:15], v[178:181], v[226:229], v[12:15]
	s_setprio 0
	s_setprio 1
	v_mfma_f32_16x16x32_bf16 v[48:51], v[182:185], v[198:201], v[48:51]
	v_mfma_f32_16x16x32_bf16 v[40:43], v[190:193], v[198:201], v[40:43]
	v_mfma_f32_16x16x32_bf16 v[32:35], v[182:185], v[206:209], v[32:35]
	v_mfma_f32_16x16x32_bf16 v[24:27], v[190:193], v[206:209], v[24:27]
	v_mfma_f32_16x16x32_bf16 v[16:19], v[182:185], v[214:217], v[16:19]
	v_mfma_f32_16x16x32_bf16 v[8:11], v[190:193], v[214:217], v[8:11]
	v_mfma_f32_16x16x32_bf16 v[4:7], v[182:185], v[222:225], v[4:7]
	v_mfma_f32_16x16x32_bf16 v[0:3], v[190:193], v[222:225], v[0:3]
	v_mfma_f32_16x16x32_bf16 v[48:51], v[186:189], v[202:205], v[48:51]
	v_mfma_f32_16x16x32_bf16 v[40:43], v[194:197], v[202:205], v[40:43]
	v_mfma_f32_16x16x32_bf16 v[32:35], v[186:189], v[210:213], v[32:35]
	v_mfma_f32_16x16x32_bf16 v[24:27], v[194:197], v[210:213], v[24:27]
	v_mfma_f32_16x16x32_bf16 v[16:19], v[186:189], v[218:221], v[16:19]
	v_mfma_f32_16x16x32_bf16 v[8:11], v[194:197], v[218:221], v[8:11]
	v_mfma_f32_16x16x32_bf16 v[4:7], v[186:189], v[226:229], v[4:7]
	v_mfma_f32_16x16x32_bf16 v[0:3], v[194:197], v[226:229], v[0:3]
	s_setprio 0
	s_barrier
	s_add_i32 s87, s87, 2
	s_add_u32 s8, s8, 0x100
	s_addc_u32 s9, s9, 0
	s_add_u32 s74, s74, 0x100
	s_addc_u32 s75, s75, 0
	s_cmp_gt_u32 s87, 13

; #define PG8_STAGE(bufoff, gbase, voff) do { _Pragma("unroll") for (int _i = 0; _i < 2; ++_i) \
;         __builtin_amdgcn_global_load_lds((const unsigned*)((const char*)(gbase) + (voff)[_i]), (LAS unsigned*)(lds + (bufoff) + ldsw + _i * 8192), 16, 0, 0); } while (0)
; #define PG8_LDA(dst, b, h) do { _Pragma("unroll") for (int m = 0; m < 4; ++m) _Pragma("unroll") for (int k = 0; k < 2; ++k) dst[m][k] = *(const LAS bf16x8*)(lds + PG8_SA(b, h) + aoff + m * 2048 + k * 1024); } while (0)
; #define PG8_LDB(dst, b, h) do { _Pragma("unroll") for (int n = 0; n < 2; ++n) _Pragma("unroll") for (int k = 0; k < 2; ++k) dst[n][k] = *(const LAS bf16x8*)(lds + PG8_SB(b, h) + boff + n * 2048 + k * 1024); } while (0)
; #define PG8_MMA(ai, bj, At, Bt) do { __builtin_amdgcn_s_setprio(1); _Pragma("unroll") for (int m = 0; m < 4; ++m) _Pragma("unroll") for (int n = 0; n < 2; ++n) _Pragma("unroll") for (int k = 0; k < 2; ++k) \
;         acc[ai][bj][m][n] = __builtin_amdgcn_mfma_f32_16x16x32_bf16(Bt[n][k], At[m][k], acc[ai][bj][m][n], 0, 0, 0); __builtin_amdgcn_s_setprio(0); } while (0)
; #define PG8_WAIT_V(n) asm volatile("s_waitcnt vmcnt(" #n ")" ::: "memory")
; template <class Epi>
; __device__ __forceinline__ void gemm_phase(LAS unsigned char* lds, const Gemm g, const StaticOrder& S, const Epi& E) {
;     ...
;         const char* nA = has_next ? (const char*)g.A + (size_t)nxt.pm * tstepA : cA; const char* nB = has_next ? (const char*)g.Bt + (size_t)nxt.pn * tstepB : cB;
; #pragma nounroll
;         for (int t = 0; t < nt; t += 2) {
;             const bool last = (t == nt - 2);
;             const char* a1 = cA + (size_t)(t + 1) * kstep;
;             const char* a2 = last ? nA : cA + (size_t)(t + 2) * kstep; const char* b2 = last ? nB : cB + (size_t)(t + 2) * kstep;
;             const char* a3 = a2 + kstep; const char* b3 = b2 + kstep;
;             PG8_LDB(B0, 0, 0); PG8_LDB(B1, 0, 1); PG8_SCHED; PG8_LDA(At, 0, 0); PG8_STAGE(PG8_SA(1, 1), a1 + hstepA, voffA);
;             PG8_WAIT_V(8); PG8_WAIT_L(0); PG8_BAR; PG8_MMA(0, 0, At, B0); PG8_MMA(0, 1, At, B1); PG8_BAR; PG8_SCHED;
;             PG8_LDA(At, 0, 1); PG8_STAGE(PG8_SB(0, 0), b2, voffB); PG8_STAGE(PG8_SB(0, 1), b2 + hstepB, voffB); PG8_STAGE(PG8_SA(0, 0), a2, voffA);
;             PG8_WAIT_V(8); PG8_WAIT_L(0); PG8_BAR; PG8_MMA(1, 0, At, B0); PG8_MMA(1, 1, At, B1); PG8_BAR; PG8_SCHED;
.LBB0_1648:
	s_add_u32 s0, s0, 0xb0080
	s_addc_u32 s1, s1, 0
	s_add_u32 s61, s20, 0x100
	s_addc_u32 s62, s21, 0
	s_mov_b32 s63, -2
	s_waitcnt lgkmcnt(0)
	ds_read_b128 v[128:131], v182
	ds_read_b128 v[132:135], v182 offset:1024
	ds_read_b128 v[136:139], v182 offset:2048
	ds_read_b128 v[140:143], v182 offset:3072
	ds_read_b128 v[160:163], v183
	ds_read_b128 v[164:167], v183 offset:1024
	ds_read_b128 v[168:171], v183 offset:2048
	ds_read_b128 v[172:175], v183 offset:3072
	s_add_u32 s20, s0, 0xfff50080
	s_addc_u32 s21, s1, -1
	s_cmp_eq_u32 s63, 40
	s_cselect_b32 s23, s7, s21
	s_cselect_b32 s22, s6, s20
	s_cselect_b32 s21, s19, s62
	s_cselect_b32 s20, s18, s61
	v_lshl_add_u64 v[178:179], s[0:1], 0, v[152:153]
	s_add_i32 m0, s33, 0xc000
	ds_read_b128 v[186:189], v184
	ds_read_b128 v[190:193], v184 offset:1024
	ds_read_b128 v[194:197], v184 offset:2048
	ds_read_b128 v[198:201], v184 offset:3072
	ds_read_b128 v[202:205], v184 offset:4096
	ds_read_b128 v[206:209], v184 offset:5120
	ds_read_b128 v[210:213], v184 offset:6144
	ds_read_b128 v[214:217], v184 offset:7168
	global_load_lds_dwordx4 v[178:179], off
	v_lshl_add_u64 v[178:179], s[0:1], 0, v[154:155]
	s_add_i32 m0, s33, 0xe000
	s_nop 0
	global_load_lds_dwordx4 v[178:179], off
	s_waitcnt vmcnt(8)
	s_waitcnt lgkmcnt(0)
	s_barrier
	s_setprio 1
	s_waitcnt lgkmcnt(0)
	v_mfma_f32_16x16x32_bf16 v[124:127], v[128:131], v[186:189], 0
	v_mfma_f32_16x16x32_bf16 v[120:123], v[136:139], v[186:189], 0
	v_mfma_f32_16x16x32_bf16 v[108:111], v[128:131], v[194:197], 0
	v_mfma_f32_16x16x32_bf16 v[104:107], v[136:139], v[194:197], 0
	v_mfma_f32_16x16x32_bf16 v[92:95], v[128:131], v[202:205], 0
	v_mfma_f32_16x16x32_bf16 v[88:91], v[136:139], v[202:205], 0
	v_mfma_f32_16x16x32_bf16 v[76:79], v[128:131], v[210:213], 0
	v_mfma_f32_16x16x32_bf16 v[72:75], v[136:139], v[210:213], 0
	v_mfma_f32_16x16x32_bf16 v[124:127], v[132:135], v[190:193], v[124:127]
	v_mfma_f32_16x16x32_bf16 v[120:123], v[140:143], v[190:193], v[120:123]
	v_mfma_f32_16x16x32_bf16 v[108:111], v[132:135], v[198:201], v[108:111]
	v_mfma_f32_16x16x32_bf16 v[104:107], v[140:143], v[198:201], v[104:107]
	v_mfma_f32_16x16x32_bf16 v[92:95], v[132:135], v[206:209], v[92:95]
	v_mfma_f32_16x16x32_bf16 v[88:91], v[140:143], v[206:209], v[88:91]
	v_mfma_f32_16x16x32_bf16 v[76:79], v[132:135], v[214:217], v[76:79]
	v_mfma_f32_16x16x32_bf16 v[72:75], v[140:143], v[214:217], v[72:75]
	s_setprio 0
	s_setprio 1
	v_mfma_f32_16x16x32_bf16 v[116:119], v[160:163], v[186:189], 0
	v_mfma_f32_16x16x32_bf16 v[112:115], v[168:171], v[186:189], 0
	v_mfma_f32_16x16x32_bf16 v[100:103], v[160:163], v[194:197], 0
	v_mfma_f32_16x16x32_bf16 v[96:99], v[168:171], v[194:197], 0
	v_mfma_f32_16x16x32_bf16 v[84:87], v[160:163], v[202:205], 0
	v_mfma_f32_16x16x32_bf16 v[80:83], v[168:171], v[202:205], 0
	v_mfma_f32_16x16x32_bf16 v[68:71], v[160:163], v[210:213], 0
	v_mfma_f32_16x16x32_bf16 v[64:67], v[168:171], v[210:213], 0
	v_mfma_f32_16x16x32_bf16 v[116:119], v[164:167], v[190:193], v[116:119]
	v_mfma_f32_16x16x32_bf16 v[112:115], v[172:175], v[190:193], v[112:115]
	v_mfma_f32_16x16x32_bf16 v[100:103], v[164:167], v[198:201], v[100:103]
	v_mfma_f32_16x16x32_bf16 v[96:99], v[172:175], v[198:201], v[96:99]
	v_mfma_f32_16x16x32_bf16 v[84:87], v[164:167], v[206:209], v[84:87]
	v_mfma_f32_16x16x32_bf16 v[80:83], v[172:175], v[206:209], v[80:83]
	v_mfma_f32_16x16x32_bf16 v[68:71], v[164:167], v[214:217], v[68:71]
	v_mfma_f32_16x16x32_bf16 v[64:67], v[172:175], v[214:217], v[64:67]
	s_setprio 0
	s_barrier
	s_add_i32 s64, s55, s29
	v_lshl_add_u64 v[178:179], s[20:21], 0, v[146:147]
	s_mov_b32 m0, s64
	ds_read_b128 v[186:189], v184 offset:16384
	ds_read_b128 v[190:193], v184 offset:17408
	ds_read_b128 v[194:197], v184 offset:18432
	ds_read_b128 v[198:201], v184 offset:19456
	ds_read_b128 v[202:205], v184 offset:20480
	ds_read_b128 v[206:209], v184 offset:21504
	ds_read_b128 v[210:213], v184 offset:22528
	ds_read_b128 v[214:217], v184 offset:23552
	global_load_lds_dwordx4 v[178:179], off
	s_add_i32 m0, s64, 0x2000
	s_add_u32 s64, s20, 0xb0000
	v_lshl_add_u64 v[218:219], s[20:21], 0, v[150:151]
	s_addc_u32 s65, s21, 0
	s_add_i32 s66, s56, s29
	global_load_lds_dwordx4 v[218:219], off
	v_lshl_add_u64 v[220:221], s[64:65], 0, v[146:147]
	s_mov_b32 m0, s66
	v_lshl_add_u64 v[222:223], s[22:23], 0, v[148:149]
	global_load_lds_dwordx4 v[220:221], off
	v_lshl_add_u64 v[220:221], s[64:65], 0, v[150:151]
	s_add_i32 m0, s66, 0x2000
	s_nop 0
	global_load_lds_dwordx4 v[220:221], off
	v_lshl_add_u64 v[220:221], s[22:23], 0, v[144:145]
	s_mov_b32 m0, s33
	s_nop 0
	global_load_lds_dwordx4 v[220:221], off
	s_mov_b32 m0, s34
	s_nop 0
	global_load_lds_dwordx4 v[222:223], off
	s_waitcnt vmcnt(8)
	s_waitcnt lgkmcnt(0)
	s_barrier
; #define PG8_STAGE(bufoff, gbase, voff) do { _Pragma("unroll") for (int _i = 0; _i < 2; ++_i) \
;         __builtin_amdgcn_global_load_lds((const unsigned*)((const char*)(gbase) + (voff)[_i]), (LAS unsigned*)(lds + (bufoff) + ldsw + _i * 8192), 16, 0, 0); } while (0)
; #define PG8_LDA(dst, b, h) do { _Pragma("unroll") for (int m = 0; m < 4; ++m) _Pragma("unroll") for (int k = 0; k < 2; ++k) dst[m][k] = *(const LAS bf16x8*)(lds + PG8_SA(b, h) + aoff + m * 2048 + k * 1024); } while (0)
; #define PG8_LDB(dst, b, h) do { _Pragma("unroll") for (int n = 0; n < 2; ++n) _Pragma("unroll") for (int k = 0; k < 2; ++k) dst[n][k] = *(const LAS bf16x8*)(lds + PG8_SB(b, h) + boff + n * 2048 + k * 1024); } while (0)
; #define PG8_MMA(ai, bj, At, Bt) do { __builtin_amdgcn_s_setprio(1); _Pragma("unroll") for (int m = 0; m < 4; ++m) _Pragma("unroll") for (int n = 0; n < 2; ++n) _Pragma("unroll") for (int k = 0; k < 2; ++k) \
;         acc[ai][bj][m][n] = __builtin_amdgcn_mfma_f32_16x16x32_bf16(Bt[n][k], At[m][k], acc[ai][bj][m][n], 0, 0, 0); __builtin_amdgcn_s_setprio(0); } while (0)
; #define PG8_WAIT_V(n) asm volatile("s_waitcnt vmcnt(" #n ")" ::: "memory")
; #define PG8_WAIT_L(n) asm volatile("s_waitcnt lgkmcnt(" #n ")" ::: "memory")
; #define PG8_BAR __builtin_amdgcn_s_barrier()
; #define PG8_SCHED __builtin_amdgcn_sched_barrier(0)
; template <class Epi>
; __device__ __forceinline__ void gemm_phase(LAS unsigned char* lds, const Gemm g, const StaticOrder& S, const Epi& E) {
;     ...
;             PG8_WAIT_V(8); PG8_WAIT_L(0); PG8_BAR; PG8_MMA(1, 0, At, B0); PG8_MMA(1, 1, At, B1); PG8_BAR; PG8_SCHED;
;             PG8_LDB(B0, 1, 0); PG8_LDB(B1, 1, 1); PG8_SCHED; PG8_LDA(At, 1, 0); PG8_STAGE(PG8_SA(0, 1), a2 + hstepA, voffA);
;             PG8_WAIT_V(8); PG8_WAIT_L(0); PG8_BAR; PG8_MMA(0, 0, At, B0); PG8_MMA(0, 1, At, B1); PG8_BAR; PG8_SCHED;
;             PG8_LDA(At, 1, 1); PG8_STAGE(PG8_SB(1, 0), b3, voffB); PG8_STAGE(PG8_SB(1, 1), b3 + hstepB, voffB); PG8_STAGE(PG8_SA(1, 0), a3, voffA);
	s_setprio 1
	s_waitcnt lgkmcnt(0)
	v_mfma_f32_16x16x32_bf16 v[60:63], v[128:131], v[186:189], 0
	v_mfma_f32_16x16x32_bf16 v[56:59], v[136:139], v[186:189], 0
	v_mfma_f32_16x16x32_bf16 v[44:47], v[128:131], v[194:197], 0
	v_mfma_f32_16x16x32_bf16 v[40:43], v[136:139], v[194:197], 0
	v_mfma_f32_16x16x32_bf16 v[28:31], v[128:131], v[202:205], 0
	v_mfma_f32_16x16x32_bf16 v[24:27], v[136:139], v[202:205], 0
	v_mfma_f32_16x16x32_bf16 v[12:15], v[128:131], v[210:213], 0
	v_mfma_f32_16x16x32_bf16 v[8:11], v[136:139], v[210:213], 0
	v_mfma_f32_16x16x32_bf16 v[60:63], v[132:135], v[190:193], v[60:63]
	v_mfma_f32_16x16x32_bf16 v[56:59], v[140:143], v[190:193], v[56:59]
	v_mfma_f32_16x16x32_bf16 v[44:47], v[132:135], v[198:201], v[44:47]
	v_mfma_f32_16x16x32_bf16 v[40:43], v[140:143], v[198:201], v[40:43]
	v_mfma_f32_16x16x32_bf16 v[28:31], v[132:135], v[206:209], v[28:31]
	v_mfma_f32_16x16x32_bf16 v[24:27], v[140:143], v[206:209], v[24:27]
	v_mfma_f32_16x16x32_bf16 v[12:15], v[132:135], v[214:217], v[12:15]
	v_mfma_f32_16x16x32_bf16 v[8:11], v[140:143], v[214:217], v[8:11]
	s_setprio 0
	s_setprio 1
	v_mfma_f32_16x16x32_bf16 v[52:55], v[160:163], v[186:189], 0
	v_mfma_f32_16x16x32_bf16 v[48:51], v[168:171], v[186:189], 0
	v_mfma_f32_16x16x32_bf16 v[36:39], v[160:163], v[194:197], 0
	v_mfma_f32_16x16x32_bf16 v[32:35], v[168:171], v[194:197], 0
	v_mfma_f32_16x16x32_bf16 v[20:23], v[160:163], v[202:205], 0
	v_mfma_f32_16x16x32_bf16 v[16:19], v[168:171], v[202:205], 0
	v_mfma_f32_16x16x32_bf16 v[4:7], v[160:163], v[210:213], 0
	v_mfma_f32_16x16x32_bf16 v[0:3], v[168:171], v[210:213], 0
	v_mfma_f32_16x16x32_bf16 v[52:55], v[164:167], v[190:193], v[52:55]
	v_mfma_f32_16x16x32_bf16 v[48:51], v[172:175], v[190:193], v[48:51]
	v_mfma_f32_16x16x32_bf16 v[36:39], v[164:167], v[198:201], v[36:39]
	v_mfma_f32_16x16x32_bf16 v[32:35], v[172:175], v[198:201], v[32:35]
	v_mfma_f32_16x16x32_bf16 v[20:23], v[164:167], v[206:209], v[20:23]
	v_mfma_f32_16x16x32_bf16 v[16:19], v[172:175], v[206:209], v[16:19]
	v_mfma_f32_16x16x32_bf16 v[4:7], v[164:167], v[214:217], v[4:7]
	v_mfma_f32_16x16x32_bf16 v[0:3], v[172:175], v[214:217], v[0:3]
	s_setprio 0
	s_barrier
	s_add_i32 s64, 0, 0x18000
	s_add_i32 s65, 0, 0x1c000
	v_add_u32_e32 v140, s64, v181
	v_add_u32_e32 v172, s65, v181
	ds_read_b128 v[128:131], v140
	ds_read_b128 v[132:135], v140 offset:1024
	ds_read_b128 v[136:139], v140 offset:2048
	ds_read_b128 v[140:143], v140 offset:3072
	ds_read_b128 v[160:163], v172
	ds_read_b128 v[164:167], v172 offset:1024
	ds_read_b128 v[168:171], v172 offset:2048
	ds_read_b128 v[172:175], v172 offset:3072
	s_add_u32 s22, s22, 0xb0000
	s_addc_u32 s23, s23, 0
	s_mov_b32 m0, s35
	v_lshl_add_u64 v[224:225], s[22:23], 0, v[144:145]
	ds_read_b128 v[186:189], v184 offset:32768
	ds_read_b128 v[190:193], v184 offset:33792
	ds_read_b128 v[194:197], v184 offset:34816
	ds_read_b128 v[198:201], v184 offset:35840
	ds_read_b128 v[202:205], v184 offset:36864
	ds_read_b128 v[206:209], v184 offset:37888
	ds_read_b128 v[210:213], v184 offset:38912
	ds_read_b128 v[214:217], v184 offset:39936
	global_load_lds_dwordx4 v[224:225], off
	v_lshl_add_u64 v[224:225], s[22:23], 0, v[148:149]
	s_mov_b32 m0, s36
	s_nop 0
	global_load_lds_dwordx4 v[224:225], off
	s_waitcnt vmcnt(8)
	s_waitcnt lgkmcnt(0)
	s_barrier
	s_setprio 1
	s_waitcnt lgkmcnt(0)
	v_mfma_f32_16x16x32_bf16 v[124:127], v[128:131], v[186:189], v[124:127]
	v_mfma_f32_16x16x32_bf16 v[120:123], v[136:139], v[186:189], v[120:123]
	v_mfma_f32_16x16x32_bf16 v[108:111], v[128:131], v[194:197], v[108:111]
	v_mfma_f32_16x16x32_bf16 v[104:107], v[136:139], v[194:197], v[104:107]
	v_mfma_f32_16x16x32_bf16 v[92:95], v[128:131], v[202:205], v[92:95]
	v_mfma_f32_16x16x32_bf16 v[88:91], v[136:139], v[202:205], v[88:91]
	v_mfma_f32_16x16x32_bf16 v[76:79], v[128:131], v[210:213], v[76:79]
	v_mfma_f32_16x16x32_bf16 v[72:75], v[136:139], v[210:213], v[72:75]
	v_mfma_f32_16x16x32_bf16 v[124:127], v[132:135], v[190:193], v[124:127]
	v_mfma_f32_16x16x32_bf16 v[120:123], v[140:143], v[190:193], v[120:123]
	v_mfma_f32_16x16x32_bf16 v[108:111], v[132:135], v[198:201], v[108:111]
	v_mfma_f32_16x16x32_bf16 v[104:107], v[140:143], v[198:201], v[104:107]
	v_mfma_f32_16x16x32_bf16 v[92:95], v[132:135], v[206:209], v[92:95]
	v_mfma_f32_16x16x32_bf16 v[88:91], v[140:143], v[206:209], v[88:91]
	v_mfma_f32_16x16x32_bf16 v[76:79], v[132:135], v[214:217], v[76:79]
	v_mfma_f32_16x16x32_bf16 v[72:75], v[140:143], v[214:217], v[72:75]
	s_setprio 0
	s_setprio 1
	v_mfma_f32_16x16x32_bf16 v[116:119], v[160:163], v[186:189], v[116:119]
	v_mfma_f32_16x16x32_bf16 v[112:115], v[168:171], v[186:189], v[112:115]
	v_mfma_f32_16x16x32_bf16 v[100:103], v[160:163], v[194:197], v[100:103]
	v_mfma_f32_16x16x32_bf16 v[96:99], v[168:171], v[194:197], v[96:99]
	v_mfma_f32_16x16x32_bf16 v[84:87], v[160:163], v[202:205], v[84:87]
	v_mfma_f32_16x16x32_bf16 v[80:83], v[168:171], v[202:205], v[80:83]
	v_mfma_f32_16x16x32_bf16 v[68:71], v[160:163], v[210:213], v[68:71]
	v_mfma_f32_16x16x32_bf16 v[64:67], v[168:171], v[210:213], v[64:67]
	v_mfma_f32_16x16x32_bf16 v[116:119], v[164:167], v[190:193], v[116:119]
	v_mfma_f32_16x16x32_bf16 v[112:115], v[172:175], v[190:193], v[112:115]
	v_mfma_f32_16x16x32_bf16 v[100:103], v[164:167], v[198:201], v[100:103]
	v_mfma_f32_16x16x32_bf16 v[96:99], v[172:175], v[198:201], v[96:99]
	v_mfma_f32_16x16x32_bf16 v[84:87], v[164:167], v[206:209], v[84:87]
	v_mfma_f32_16x16x32_bf16 v[80:83], v[172:175], v[206:209], v[80:83]
	v_mfma_f32_16x16x32_bf16 v[68:71], v[164:167], v[214:217], v[68:71]
	v_mfma_f32_16x16x32_bf16 v[64:67], v[172:175], v[214:217], v[64:67]
	s_setprio 0
	s_barrier
; #define PG8_STAGE(bufoff, gbase, voff) do { _Pragma("unroll") for (int _i = 0; _i < 2; ++_i) \
;         __builtin_amdgcn_global_load_lds((const unsigned*)((const char*)(gbase) + (voff)[_i]), (LAS unsigned*)(lds + (bufoff) + ldsw + _i * 8192), 16, 0, 0); } while (0)
; #define PG8_LDA(dst, b, h) do { _Pragma("unroll") for (int m = 0; m < 4; ++m) _Pragma("unroll") for (int k = 0; k < 2; ++k) dst[m][k] = *(const LAS bf16x8*)(lds + PG8_SA(b, h) + aoff + m * 2048 + k * 1024); } while (0)
; #define PG8_LDB(dst, b, h) do { _Pragma("unroll") for (int n = 0; n < 2; ++n) _Pragma("unroll") for (int k = 0; k < 2; ++k) dst[n][k] = *(const LAS bf16x8*)(lds + PG8_SB(b, h) + boff + n * 2048 + k * 1024); } while (0)
; #define PG8_WAIT_V(n) asm volatile("s_waitcnt vmcnt(" #n ")" ::: "memory")
; #define PG8_WAIT_L(n) asm volatile("s_waitcnt lgkmcnt(" #n ")" ::: "memory")
; template <class Epi>
; __device__ __forceinline__ void gemm_phase(LAS unsigned char* lds, const Gemm g, const StaticOrder& S, const Epi& E) {
;     ...
;         for (int t = 0; t < nt; t += 2) {
;             const bool last = (t == nt - 2);
;             const char* a1 = cA + (size_t)(t + 1) * kstep;
;             const char* a2 = last ? nA : cA + (size_t)(t + 2) * kstep; const char* b2 = last ? nB : cB + (size_t)(t + 2) * kstep;
;             const char* a3 = a2 + kstep; const char* b3 = b2 + kstep;
;             PG8_LDB(B0, 0, 0); PG8_LDB(B1, 0, 1); PG8_SCHED; PG8_LDA(At, 0, 0); PG8_STAGE(PG8_SA(1, 1), a1 + hstepA, voffA);
;             PG8_WAIT_V(8); PG8_WAIT_L(0); PG8_BAR; PG8_MMA(0, 0, At, B0); PG8_MMA(0, 1, At, B1); PG8_BAR; PG8_SCHED;
;             PG8_LDA(At, 0, 1); PG8_STAGE(PG8_SB(0, 0), b2, voffB); PG8_STAGE(PG8_SB(0, 1), b2 + hstepB, voffB); PG8_STAGE(PG8_SA(0, 0), a2, voffA);
;             PG8_WAIT_V(8); PG8_WAIT_L(0); PG8_BAR; PG8_MMA(1, 0, At, B0); PG8_MMA(1, 1, At, B1); PG8_BAR; PG8_SCHED;
;             PG8_LDB(B0, 1, 0); PG8_LDB(B1, 1, 1); PG8_SCHED; PG8_LDA(At, 1, 0); PG8_STAGE(PG8_SA(0, 1), a2 + hstepA, voffA);
;             PG8_WAIT_V(8); PG8_WAIT_L(0); PG8_BAR; PG8_MMA(0, 0, At, B0); PG8_MMA(0, 1, At, B1); PG8_BAR; PG8_SCHED;
;             PG8_LDA(At, 1, 1); PG8_STAGE(PG8_SB(1, 0), b3, voffB); PG8_STAGE(PG8_SB(1, 1), b3 + hstepB, voffB); PG8_STAGE(PG8_SA(1, 0), a3, voffA);
;             PG8_WAIT_V(8); PG8_WAIT_L(0); PG8_BAR; PG8_MMA(1, 0, At, B0); PG8_MMA(1, 1, At, B1); PG8_BAR; PG8_SCHED;
	s_add_i32 s22, s64, s29
	v_lshl_add_u64 v[178:179], v[178:179], 0, s[14:15]
	s_mov_b32 m0, s22
	ds_read_b128 v[186:189], v184 offset:49152
	ds_read_b128 v[190:193], v184 offset:50176
	ds_read_b128 v[194:197], v184 offset:51200
	ds_read_b128 v[198:201], v184 offset:52224
	ds_read_b128 v[202:205], v184 offset:53248
	ds_read_b128 v[206:209], v184 offset:54272
	ds_read_b128 v[210:213], v184 offset:55296
	ds_read_b128 v[214:217], v184 offset:56320
	global_load_lds_dwordx4 v[178:179], off
	s_add_i32 m0, s22, 0x2000
	s_add_u32 s20, s20, 0xb0080
	v_lshl_add_u64 v[178:179], v[218:219], 0, s[14:15]
	s_addc_u32 s21, s21, 0
	s_add_i32 s22, s65, s29
	global_load_lds_dwordx4 v[178:179], off
	v_lshl_add_u64 v[178:179], s[20:21], 0, v[146:147]
	s_mov_b32 m0, s22
	s_nop 0
	global_load_lds_dwordx4 v[178:179], off
	v_lshl_add_u64 v[178:179], s[20:21], 0, v[150:151]
	s_add_i32 m0, s22, 0x2000
	s_nop 0
	global_load_lds_dwordx4 v[178:179], off
	v_lshl_add_u64 v[178:179], v[220:221], 0, s[14:15]
	s_mov_b32 m0, s42
	s_nop 0
	global_load_lds_dwordx4 v[178:179], off
	v_lshl_add_u64 v[178:179], v[222:223], 0, s[14:15]
	s_mov_b32 m0, s43
	s_nop 0
	global_load_lds_dwordx4 v[178:179], off
	s_waitcnt vmcnt(8)
	s_waitcnt lgkmcnt(0)
	s_barrier
	s_setprio 1
	s_waitcnt lgkmcnt(0)
	v_mfma_f32_16x16x32_bf16 v[60:63], v[128:131], v[186:189], v[60:63]
	v_mfma_f32_16x16x32_bf16 v[56:59], v[136:139], v[186:189], v[56:59]
	v_mfma_f32_16x16x32_bf16 v[44:47], v[128:131], v[194:197], v[44:47]
	v_mfma_f32_16x16x32_bf16 v[40:43], v[136:139], v[194:197], v[40:43]
	v_mfma_f32_16x16x32_bf16 v[28:31], v[128:131], v[202:205], v[28:31]
	v_mfma_f32_16x16x32_bf16 v[24:27], v[136:139], v[202:205], v[24:27]
	v_mfma_f32_16x16x32_bf16 v[12:15], v[128:131], v[210:213], v[12:15]
	v_mfma_f32_16x16x32_bf16 v[8:11], v[136:139], v[210:213], v[8:11]
	v_mfma_f32_16x16x32_bf16 v[60:63], v[132:135], v[190:193], v[60:63]
	v_mfma_f32_16x16x32_bf16 v[56:59], v[140:143], v[190:193], v[56:59]
	v_mfma_f32_16x16x32_bf16 v[44:47], v[132:135], v[198:201], v[44:47]
	v_mfma_f32_16x16x32_bf16 v[40:43], v[140:143], v[198:201], v[40:43]
	v_mfma_f32_16x16x32_bf16 v[28:31], v[132:135], v[206:209], v[28:31]
	v_mfma_f32_16x16x32_bf16 v[24:27], v[140:143], v[206:209], v[24:27]
	v_mfma_f32_16x16x32_bf16 v[12:15], v[132:135], v[214:217], v[12:15]
	v_mfma_f32_16x16x32_bf16 v[8:11], v[140:143], v[214:217], v[8:11]
	s_setprio 0
	s_setprio 1
	v_mfma_f32_16x16x32_bf16 v[52:55], v[160:163], v[186:189], v[52:55]
	v_mfma_f32_16x16x32_bf16 v[48:51], v[168:171], v[186:189], v[48:51]
	v_mfma_f32_16x16x32_bf16 v[36:39], v[160:163], v[194:197], v[36:39]
	v_mfma_f32_16x16x32_bf16 v[32:35], v[168:171], v[194:197], v[32:35]
	v_mfma_f32_16x16x32_bf16 v[20:23], v[160:163], v[202:205], v[20:23]
	v_mfma_f32_16x16x32_bf16 v[16:19], v[168:171], v[202:205], v[16:19]
	v_mfma_f32_16x16x32_bf16 v[4:7], v[160:163], v[210:213], v[4:7]
	v_mfma_f32_16x16x32_bf16 v[0:3], v[168:171], v[210:213], v[0:3]
	v_mfma_f32_16x16x32_bf16 v[52:55], v[164:167], v[190:193], v[52:55]
	v_mfma_f32_16x16x32_bf16 v[48:51], v[172:175], v[190:193], v[48:51]
	v_mfma_f32_16x16x32_bf16 v[36:39], v[164:167], v[198:201], v[36:39]
	v_mfma_f32_16x16x32_bf16 v[32:35], v[172:175], v[198:201], v[32:35]
	v_mfma_f32_16x16x32_bf16 v[20:23], v[164:167], v[206:209], v[20:23]
	v_mfma_f32_16x16x32_bf16 v[16:19], v[172:175], v[206:209], v[16:19]
	v_mfma_f32_16x16x32_bf16 v[4:7], v[164:167], v[214:217], v[4:7]
	v_mfma_f32_16x16x32_bf16 v[0:3], v[172:175], v[214:217], v[0:3]
	s_setprio 0
	s_barrier
	s_add_i32 s63, s63, 2
	s_add_u32 s0, s0, 0x100
	s_addc_u32 s1, s1, 0
	s_add_u32 s61, s61, 0x100
	s_addc_u32 s62, s62, 0
	s_cmp_gt_u32 s63, 41

; #define PG8_STAGE(bufoff, gbase, voff) do { _Pragma("unroll") for (int _i = 0; _i < 2; ++_i) \
;         __builtin_amdgcn_global_load_lds((const unsigned*)((const char*)(gbase) + (voff)[_i]), (LAS unsigned*)(lds + (bufoff) + ldsw + _i * 8192), 16, 0, 0); } while (0)
; #define PG8_LDA(dst, b, h) do { _Pragma("unroll") for (int m = 0; m < 4; ++m) _Pragma("unroll") for (int k = 0; k < 2; ++k) dst[m][k] = *(const LAS bf16x8*)(lds + PG8_SA(b, h) + aoff + m * 2048 + k * 1024); } while (0)
; #define PG8_LDB(dst, b, h) do { _Pragma("unroll") for (int n = 0; n < 2; ++n) _Pragma("unroll") for (int k = 0; k < 2; ++k) dst[n][k] = *(const LAS bf16x8*)(lds + PG8_SB(b, h) + boff + n * 2048 + k * 1024); } while (0)
; #define PG8_MMA(ai, bj, At, Bt) do { __builtin_amdgcn_s_setprio(1); _Pragma("unroll") for (int m = 0; m < 4; ++m) _Pragma("unroll") for (int n = 0; n < 2; ++n) _Pragma("unroll") for (int k = 0; k < 2; ++k) \
;         acc[ai][bj][m][n] = __builtin_amdgcn_mfma_f32_16x16x32_bf16(Bt[n][k], At[m][k], acc[ai][bj][m][n], 0, 0, 0); __builtin_amdgcn_s_setprio(0); } while (0)
; #define PG8_WAIT_V(n) asm volatile("s_waitcnt vmcnt(" #n ")" ::: "memory")
; template <class Epi>
; __device__ __forceinline__ void gemm_phase(LAS unsigned char* lds, const Gemm g, const StaticOrder& S, const Epi& E) {
;     ...
;         const char* nA = has_next ? (const char*)g.A + (size_t)nxt.pm * tstepA : cA; const char* nB = has_next ? (const char*)g.Bt + (size_t)nxt.pn * tstepB : cB;
; #pragma nounroll
;         for (int t = 0; t < nt; t += 2) {
;             const bool last = (t == nt - 2);
;             const char* a1 = cA + (size_t)(t + 1) * kstep;
;             const char* a2 = last ? nA : cA + (size_t)(t + 2) * kstep; const char* b2 = last ? nB : cB + (size_t)(t + 2) * kstep;
;             const char* a3 = a2 + kstep; const char* b3 = b2 + kstep;
;             PG8_LDB(B0, 0, 0); PG8_LDB(B1, 0, 1); PG8_SCHED; PG8_LDA(At, 0, 0); PG8_STAGE(PG8_SA(1, 1), a1 + hstepA, voffA);
;             PG8_WAIT_V(8); PG8_WAIT_L(0); PG8_BAR; PG8_MMA(0, 0, At, B0); PG8_MMA(0, 1, At, B1); PG8_BAR; PG8_SCHED;
;             PG8_LDA(At, 0, 1); PG8_STAGE(PG8_SB(0, 0), b2, voffB); PG8_STAGE(PG8_SB(0, 1), b2 + hstepB, voffB); PG8_STAGE(PG8_SA(0, 0), a2, voffA);
;             PG8_WAIT_V(8); PG8_WAIT_L(0); PG8_BAR; PG8_MMA(1, 0, At, B0); PG8_MMA(1, 1, At, B1); PG8_BAR; PG8_SCHED;
.LBB0_1745:
	s_ashr_i32 s35, s34, 31
	s_lshl_b64 s[36:37], s[34:35], 19
	s_add_u32 s36, s30, s36
	s_addc_u32 s37, s31, s37
	s_and_b64 s[38:39], s[4:5], exec
	s_cselect_b32 s7, s37, s43
	s_cselect_b32 s9, s36, s42
	s_ashr_i32 s29, s28, 31
	s_lshl_b64 s[38:39], s[28:29], 19
	s_add_u32 s38, s3, s38
	s_addc_u32 s39, s33, s39
	s_and_b64 s[44:45], s[4:5], exec
	s_cselect_b32 s29, s39, s53
	s_cselect_b32 s35, s38, s52
	s_add_u32 s42, s42, 0x40080
	s_addc_u32 s43, s43, 0
	s_add_u32 s69, s52, 0x100
	s_addc_u32 s70, s53, 0
	s_mov_b32 s71, -2
	s_waitcnt lgkmcnt(0)
	ds_read_b128 v[40:43], v208
	ds_read_b128 v[44:47], v208 offset:1024
	ds_read_b128 v[56:59], v208 offset:2048
	ds_read_b128 v[60:63], v208 offset:3072
	ds_read_b128 v[144:147], v209
	ds_read_b128 v[148:151], v209 offset:1024
	ds_read_b128 v[152:155], v209 offset:2048
	ds_read_b128 v[156:159], v209 offset:3072
	s_add_u32 s44, s42, 0xfffc0080
	s_addc_u32 s45, s43, -1
	s_cmp_eq_u32 s71, 12
	s_cselect_b32 s53, s7, s45
	s_cselect_b32 s52, s9, s44
	s_cselect_b32 s45, s29, s70
	s_cselect_b32 s44, s35, s69
	v_lshl_add_u64 v[218:219], s[42:43], 0, v[178:179]
	s_add_i32 m0, s55, 0xc000
	ds_read_b128 v[160:163], v210
	ds_read_b128 v[164:167], v210 offset:1024
	ds_read_b128 v[186:189], v210 offset:2048
	ds_read_b128 v[190:193], v210 offset:3072
	ds_read_b128 v[194:197], v210 offset:4096
	ds_read_b128 v[198:201], v210 offset:5120
	ds_read_b128 v[202:205], v210 offset:6144
	ds_read_b128 v[214:217], v210 offset:7168
	global_load_lds_dwordx4 v[218:219], off
	v_lshl_add_u64 v[218:219], s[42:43], 0, v[180:181]
	s_add_i32 m0, s55, 0xe000
	s_nop 0
	global_load_lds_dwordx4 v[218:219], off
	s_waitcnt vmcnt(8)
	s_waitcnt lgkmcnt(0)
	s_barrier
	s_setprio 1
	s_waitcnt lgkmcnt(0)
	v_mfma_f32_16x16x32_bf16 v[140:143], v[40:43], v[160:163], 0
	v_mfma_f32_16x16x32_bf16 v[136:139], v[56:59], v[160:163], 0
	v_mfma_f32_16x16x32_bf16 v[124:127], v[40:43], v[186:189], 0
	v_mfma_f32_16x16x32_bf16 v[120:123], v[56:59], v[186:189], 0
	v_mfma_f32_16x16x32_bf16 v[108:111], v[40:43], v[194:197], 0
	v_mfma_f32_16x16x32_bf16 v[104:107], v[56:59], v[194:197], 0
	v_mfma_f32_16x16x32_bf16 v[92:95], v[40:43], v[202:205], 0
	v_mfma_f32_16x16x32_bf16 v[88:91], v[56:59], v[202:205], 0
	v_mfma_f32_16x16x32_bf16 v[140:143], v[44:47], v[164:167], v[140:143]
	v_mfma_f32_16x16x32_bf16 v[136:139], v[60:63], v[164:167], v[136:139]
	v_mfma_f32_16x16x32_bf16 v[124:127], v[44:47], v[190:193], v[124:127]
	v_mfma_f32_16x16x32_bf16 v[120:123], v[60:63], v[190:193], v[120:123]
	v_mfma_f32_16x16x32_bf16 v[108:111], v[44:47], v[198:201], v[108:111]
	v_mfma_f32_16x16x32_bf16 v[104:107], v[60:63], v[198:201], v[104:107]
	v_mfma_f32_16x16x32_bf16 v[92:95], v[44:47], v[214:217], v[92:95]
	v_mfma_f32_16x16x32_bf16 v[88:91], v[60:63], v[214:217], v[88:91]
	s_setprio 0
	s_setprio 1
	v_mfma_f32_16x16x32_bf16 v[132:135], v[144:147], v[160:163], 0
	v_mfma_f32_16x16x32_bf16 v[128:131], v[152:155], v[160:163], 0
	v_mfma_f32_16x16x32_bf16 v[116:119], v[144:147], v[186:189], 0
	v_mfma_f32_16x16x32_bf16 v[112:115], v[152:155], v[186:189], 0
	v_mfma_f32_16x16x32_bf16 v[100:103], v[144:147], v[194:197], 0
	v_mfma_f32_16x16x32_bf16 v[96:99], v[152:155], v[194:197], 0
	v_mfma_f32_16x16x32_bf16 v[84:87], v[144:147], v[202:205], 0
	v_mfma_f32_16x16x32_bf16 v[80:83], v[152:155], v[202:205], 0
	v_mfma_f32_16x16x32_bf16 v[132:135], v[148:151], v[164:167], v[132:135]
	v_mfma_f32_16x16x32_bf16 v[128:131], v[156:159], v[164:167], v[128:131]
	v_mfma_f32_16x16x32_bf16 v[116:119], v[148:151], v[190:193], v[116:119]
	v_mfma_f32_16x16x32_bf16 v[112:115], v[156:159], v[190:193], v[112:115]
	v_mfma_f32_16x16x32_bf16 v[100:103], v[148:151], v[198:201], v[100:103]
	v_mfma_f32_16x16x32_bf16 v[96:99], v[156:159], v[198:201], v[96:99]
	v_mfma_f32_16x16x32_bf16 v[84:87], v[148:151], v[214:217], v[84:87]
	v_mfma_f32_16x16x32_bf16 v[80:83], v[156:159], v[214:217], v[80:83]
	s_setprio 0
	s_barrier
	s_add_i32 s72, s67, s54
	v_lshl_add_u64 v[218:219], s[44:45], 0, v[170:171]
	s_mov_b32 m0, s72
	ds_read_b128 v[160:163], v210 offset:16384
	ds_read_b128 v[164:167], v210 offset:17408
	ds_read_b128 v[186:189], v210 offset:18432
	ds_read_b128 v[190:193], v210 offset:19456
	ds_read_b128 v[194:197], v210 offset:20480
	ds_read_b128 v[198:201], v210 offset:21504
	ds_read_b128 v[202:205], v210 offset:22528
	ds_read_b128 v[214:217], v210 offset:23552
	global_load_lds_dwordx4 v[218:219], off
	s_add_i32 m0, s72, 0x2000
	s_add_u32 s72, s44, 0x40000
	v_lshl_add_u64 v[220:221], s[44:45], 0, v[174:175]
	s_addc_u32 s73, s45, 0
	s_add_i32 s74, s68, s54
	global_load_lds_dwordx4 v[220:221], off
	v_lshl_add_u64 v[222:223], s[72:73], 0, v[170:171]
	s_mov_b32 m0, s74
	v_lshl_add_u64 v[224:225], s[52:53], 0, v[172:173]
	global_load_lds_dwordx4 v[222:223], off
	v_lshl_add_u64 v[222:223], s[72:73], 0, v[174:175]
	s_add_i32 m0, s74, 0x2000
	s_nop 0
	global_load_lds_dwordx4 v[222:223], off
	v_lshl_add_u64 v[222:223], s[52:53], 0, v[168:169]
	s_mov_b32 m0, s55
	s_nop 0
	global_load_lds_dwordx4 v[222:223], off
	s_mov_b32 m0, s56
	s_nop 0
	global_load_lds_dwordx4 v[224:225], off
	s_waitcnt vmcnt(8)
	s_waitcnt lgkmcnt(0)
	s_barrier
; #define PG8_STAGE(bufoff, gbase, voff) do { _Pragma("unroll") for (int _i = 0; _i < 2; ++_i) \
;         __builtin_amdgcn_global_load_lds((const unsigned*)((const char*)(gbase) + (voff)[_i]), (LAS unsigned*)(lds + (bufoff) + ldsw + _i * 8192), 16, 0, 0); } while (0)
; #define PG8_LDA(dst, b, h) do { _Pragma("unroll") for (int m = 0; m < 4; ++m) _Pragma("unroll") for (int k = 0; k < 2; ++k) dst[m][k] = *(const LAS bf16x8*)(lds + PG8_SA(b, h) + aoff + m * 2048 + k * 1024); } while (0)
; #define PG8_LDB(dst, b, h) do { _Pragma("unroll") for (int n = 0; n < 2; ++n) _Pragma("unroll") for (int k = 0; k < 2; ++k) dst[n][k] = *(const LAS bf16x8*)(lds + PG8_SB(b, h) + boff + n * 2048 + k * 1024); } while (0)
; #define PG8_MMA(ai, bj, At, Bt) do { __builtin_amdgcn_s_setprio(1); _Pragma("unroll") for (int m = 0; m < 4; ++m) _Pragma("unroll") for (int n = 0; n < 2; ++n) _Pragma("unroll") for (int k = 0; k < 2; ++k) \
;         acc[ai][bj][m][n] = __builtin_amdgcn_mfma_f32_16x16x32_bf16(Bt[n][k], At[m][k], acc[ai][bj][m][n], 0, 0, 0); __builtin_amdgcn_s_setprio(0); } while (0)
; #define PG8_WAIT_V(n) asm volatile("s_waitcnt vmcnt(" #n ")" ::: "memory")
; #define PG8_WAIT_L(n) asm volatile("s_waitcnt lgkmcnt(" #n ")" ::: "memory")
; #define PG8_BAR __builtin_amdgcn_s_barrier()
; #define PG8_SCHED __builtin_amdgcn_sched_barrier(0)
; template <class Epi>
; __device__ __forceinline__ void gemm_phase(LAS unsigned char* lds, const Gemm g, const StaticOrder& S, const Epi& E) {
;     ...
;             PG8_WAIT_V(8); PG8_WAIT_L(0); PG8_BAR; PG8_MMA(1, 0, At, B0); PG8_MMA(1, 1, At, B1); PG8_BAR; PG8_SCHED;
;             PG8_LDB(B0, 1, 0); PG8_LDB(B1, 1, 1); PG8_SCHED; PG8_LDA(At, 1, 0); PG8_STAGE(PG8_SA(0, 1), a2 + hstepA, voffA);
;             PG8_WAIT_V(8); PG8_WAIT_L(0); PG8_BAR; PG8_MMA(0, 0, At, B0); PG8_MMA(0, 1, At, B1); PG8_BAR; PG8_SCHED;
;             PG8_LDA(At, 1, 1); PG8_STAGE(PG8_SB(1, 0), b3, voffB); PG8_STAGE(PG8_SB(1, 1), b3 + hstepB, voffB); PG8_STAGE(PG8_SA(1, 0), a3, voffA);
	s_setprio 1
	s_waitcnt lgkmcnt(0)
	v_mfma_f32_16x16x32_bf16 v[76:79], v[40:43], v[160:163], 0
	v_mfma_f32_16x16x32_bf16 v[72:75], v[56:59], v[160:163], 0
	v_mfma_f32_16x16x32_bf16 v[52:55], v[40:43], v[186:189], 0
	v_mfma_f32_16x16x32_bf16 v[48:51], v[56:59], v[186:189], 0
	v_mfma_f32_16x16x32_bf16 v[28:31], v[40:43], v[194:197], 0
	v_mfma_f32_16x16x32_bf16 v[24:27], v[56:59], v[194:197], 0
	v_mfma_f32_16x16x32_bf16 v[12:15], v[40:43], v[202:205], 0
	v_mfma_f32_16x16x32_bf16 v[8:11], v[56:59], v[202:205], 0
	v_mfma_f32_16x16x32_bf16 v[76:79], v[44:47], v[164:167], v[76:79]
	v_mfma_f32_16x16x32_bf16 v[72:75], v[60:63], v[164:167], v[72:75]
	v_mfma_f32_16x16x32_bf16 v[52:55], v[44:47], v[190:193], v[52:55]
	v_mfma_f32_16x16x32_bf16 v[48:51], v[60:63], v[190:193], v[48:51]
	v_mfma_f32_16x16x32_bf16 v[28:31], v[44:47], v[198:201], v[28:31]
	v_mfma_f32_16x16x32_bf16 v[24:27], v[60:63], v[198:201], v[24:27]
	v_mfma_f32_16x16x32_bf16 v[12:15], v[44:47], v[214:217], v[12:15]
	v_mfma_f32_16x16x32_bf16 v[8:11], v[60:63], v[214:217], v[8:11]
	s_setprio 0
	s_setprio 1
	v_mfma_f32_16x16x32_bf16 v[36:39], v[144:147], v[186:189], 0
	v_mfma_f32_16x16x32_bf16 v[32:35], v[152:155], v[186:189], 0
	v_mfma_f32_16x16x32_bf16 v[20:23], v[144:147], v[194:197], 0
	v_mfma_f32_16x16x32_bf16 v[16:19], v[152:155], v[194:197], 0
	v_mfma_f32_16x16x32_bf16 v[4:7], v[144:147], v[202:205], 0
	v_mfma_f32_16x16x32_bf16 v[0:3], v[152:155], v[202:205], 0
	v_mfma_f32_16x16x32_bf16 v[40:43], v[144:147], v[160:163], 0
	v_mfma_f32_16x16x32_bf16 v[44:47], v[152:155], v[160:163], 0
	v_mfma_f32_16x16x32_bf16 v[36:39], v[148:151], v[190:193], v[36:39]
	v_mfma_f32_16x16x32_bf16 v[32:35], v[156:159], v[190:193], v[32:35]
	v_mfma_f32_16x16x32_bf16 v[20:23], v[148:151], v[198:201], v[20:23]
	v_mfma_f32_16x16x32_bf16 v[16:19], v[156:159], v[198:201], v[16:19]
	v_mfma_f32_16x16x32_bf16 v[4:7], v[148:151], v[214:217], v[4:7]
	v_mfma_f32_16x16x32_bf16 v[0:3], v[156:159], v[214:217], v[0:3]
	v_mfma_f32_16x16x32_bf16 v[40:43], v[148:151], v[164:167], v[40:43]
	v_mfma_f32_16x16x32_bf16 v[44:47], v[156:159], v[164:167], v[44:47]
	s_setprio 0
	s_barrier
	s_add_i32 s72, 0, 0x18000
	s_add_i32 s73, 0, 0x1c000
	v_add_u32_e32 v68, s72, v207
	v_add_u32_e32 v156, s73, v207
	ds_read_b128 v[56:59], v68
	ds_read_b128 v[60:63], v68 offset:1024
	ds_read_b128 v[64:67], v68 offset:2048
	ds_read_b128 v[68:71], v68 offset:3072
	ds_read_b128 v[144:147], v156
	ds_read_b128 v[148:151], v156 offset:1024
	ds_read_b128 v[152:155], v156 offset:2048
	ds_read_b128 v[156:159], v156 offset:3072
	s_add_u32 s52, s52, 0x40000
	s_addc_u32 s53, s53, 0
	s_mov_b32 m0, s57
	v_lshl_add_u64 v[226:227], s[52:53], 0, v[168:169]
	ds_read_b128 v[160:163], v210 offset:32768
	ds_read_b128 v[164:167], v210 offset:33792
	ds_read_b128 v[186:189], v210 offset:34816
	ds_read_b128 v[190:193], v210 offset:35840
	ds_read_b128 v[194:197], v210 offset:36864
	ds_read_b128 v[198:201], v210 offset:37888
	ds_read_b128 v[202:205], v210 offset:38912
	ds_read_b128 v[214:217], v210 offset:39936
	global_load_lds_dwordx4 v[226:227], off
	v_lshl_add_u64 v[226:227], s[52:53], 0, v[172:173]
	s_mov_b32 m0, s58
	s_nop 0
	global_load_lds_dwordx4 v[226:227], off
	s_waitcnt vmcnt(8)
	s_waitcnt lgkmcnt(0)
	s_barrier
	s_setprio 1
	s_waitcnt lgkmcnt(0)
	v_mfma_f32_16x16x32_bf16 v[140:143], v[56:59], v[160:163], v[140:143]
	v_mfma_f32_16x16x32_bf16 v[136:139], v[64:67], v[160:163], v[136:139]
	v_mfma_f32_16x16x32_bf16 v[124:127], v[56:59], v[186:189], v[124:127]
	v_mfma_f32_16x16x32_bf16 v[120:123], v[64:67], v[186:189], v[120:123]
	v_mfma_f32_16x16x32_bf16 v[108:111], v[56:59], v[194:197], v[108:111]
	v_mfma_f32_16x16x32_bf16 v[104:107], v[64:67], v[194:197], v[104:107]
	v_mfma_f32_16x16x32_bf16 v[92:95], v[56:59], v[202:205], v[92:95]
	v_mfma_f32_16x16x32_bf16 v[88:91], v[64:67], v[202:205], v[88:91]
	v_mfma_f32_16x16x32_bf16 v[140:143], v[60:63], v[164:167], v[140:143]
	v_mfma_f32_16x16x32_bf16 v[136:139], v[68:71], v[164:167], v[136:139]
	v_mfma_f32_16x16x32_bf16 v[124:127], v[60:63], v[190:193], v[124:127]
	v_mfma_f32_16x16x32_bf16 v[120:123], v[68:71], v[190:193], v[120:123]
	v_mfma_f32_16x16x32_bf16 v[108:111], v[60:63], v[198:201], v[108:111]
	v_mfma_f32_16x16x32_bf16 v[104:107], v[68:71], v[198:201], v[104:107]
	v_mfma_f32_16x16x32_bf16 v[92:95], v[60:63], v[214:217], v[92:95]
	v_mfma_f32_16x16x32_bf16 v[88:91], v[68:71], v[214:217], v[88:91]
	s_setprio 0
	s_setprio 1
	v_mfma_f32_16x16x32_bf16 v[132:135], v[144:147], v[160:163], v[132:135]
	v_mfma_f32_16x16x32_bf16 v[128:131], v[152:155], v[160:163], v[128:131]
	v_mfma_f32_16x16x32_bf16 v[116:119], v[144:147], v[186:189], v[116:119]
	v_mfma_f32_16x16x32_bf16 v[112:115], v[152:155], v[186:189], v[112:115]
	v_mfma_f32_16x16x32_bf16 v[100:103], v[144:147], v[194:197], v[100:103]
	v_mfma_f32_16x16x32_bf16 v[96:99], v[152:155], v[194:197], v[96:99]
	v_mfma_f32_16x16x32_bf16 v[84:87], v[144:147], v[202:205], v[84:87]
	v_mfma_f32_16x16x32_bf16 v[80:83], v[152:155], v[202:205], v[80:83]
	v_mfma_f32_16x16x32_bf16 v[132:135], v[148:151], v[164:167], v[132:135]
	v_mfma_f32_16x16x32_bf16 v[128:131], v[156:159], v[164:167], v[128:131]
	v_mfma_f32_16x16x32_bf16 v[116:119], v[148:151], v[190:193], v[116:119]
	v_mfma_f32_16x16x32_bf16 v[112:115], v[156:159], v[190:193], v[112:115]
	v_mfma_f32_16x16x32_bf16 v[100:103], v[148:151], v[198:201], v[100:103]
	v_mfma_f32_16x16x32_bf16 v[96:99], v[156:159], v[198:201], v[96:99]
	v_mfma_f32_16x16x32_bf16 v[84:87], v[148:151], v[214:217], v[84:87]
	v_mfma_f32_16x16x32_bf16 v[80:83], v[156:159], v[214:217], v[80:83]
	s_setprio 0
	s_barrier
; #define PG8_STAGE(bufoff, gbase, voff) do { _Pragma("unroll") for (int _i = 0; _i < 2; ++_i) \
;         __builtin_amdgcn_global_load_lds((const unsigned*)((const char*)(gbase) + (voff)[_i]), (LAS unsigned*)(lds + (bufoff) + ldsw + _i * 8192), 16, 0, 0); } while (0)
; #define PG8_LDA(dst, b, h) do { _Pragma("unroll") for (int m = 0; m < 4; ++m) _Pragma("unroll") for (int k = 0; k < 2; ++k) dst[m][k] = *(const LAS bf16x8*)(lds + PG8_SA(b, h) + aoff + m * 2048 + k * 1024); } while (0)
; #define PG8_LDB(dst, b, h) do { _Pragma("unroll") for (int n = 0; n < 2; ++n) _Pragma("unroll") for (int k = 0; k < 2; ++k) dst[n][k] = *(const LAS bf16x8*)(lds + PG8_SB(b, h) + boff + n * 2048 + k * 1024); } while (0)
; #define PG8_WAIT_V(n) asm volatile("s_waitcnt vmcnt(" #n ")" ::: "memory")
; #define PG8_WAIT_L(n) asm volatile("s_waitcnt lgkmcnt(" #n ")" ::: "memory")
; template <class Epi>
; __device__ __forceinline__ void gemm_phase(LAS unsigned char* lds, const Gemm g, const StaticOrder& S, const Epi& E) {
;     ...
;         for (int t = 0; t < nt; t += 2) {
;             const bool last = (t == nt - 2);
;             const char* a1 = cA + (size_t)(t + 1) * kstep;
;             const char* a2 = last ? nA : cA + (size_t)(t + 2) * kstep; const char* b2 = last ? nB : cB + (size_t)(t + 2) * kstep;
;             const char* a3 = a2 + kstep; const char* b3 = b2 + kstep;
;             PG8_LDB(B0, 0, 0); PG8_LDB(B1, 0, 1); PG8_SCHED; PG8_LDA(At, 0, 0); PG8_STAGE(PG8_SA(1, 1), a1 + hstepA, voffA);
;             PG8_WAIT_V(8); PG8_WAIT_L(0); PG8_BAR; PG8_MMA(0, 0, At, B0); PG8_MMA(0, 1, At, B1); PG8_BAR; PG8_SCHED;
;             PG8_LDA(At, 0, 1); PG8_STAGE(PG8_SB(0, 0), b2, voffB); PG8_STAGE(PG8_SB(0, 1), b2 + hstepB, voffB); PG8_STAGE(PG8_SA(0, 0), a2, voffA);
;             PG8_WAIT_V(8); PG8_WAIT_L(0); PG8_BAR; PG8_MMA(1, 0, At, B0); PG8_MMA(1, 1, At, B1); PG8_BAR; PG8_SCHED;
;             PG8_LDB(B0, 1, 0); PG8_LDB(B1, 1, 1); PG8_SCHED; PG8_LDA(At, 1, 0); PG8_STAGE(PG8_SA(0, 1), a2 + hstepA, voffA);
;             PG8_WAIT_V(8); PG8_WAIT_L(0); PG8_BAR; PG8_MMA(0, 0, At, B0); PG8_MMA(0, 1, At, B1); PG8_BAR; PG8_SCHED;
;             PG8_LDA(At, 1, 1); PG8_STAGE(PG8_SB(1, 0), b3, voffB); PG8_STAGE(PG8_SB(1, 1), b3 + hstepB, voffB); PG8_STAGE(PG8_SA(1, 0), a3, voffA);
;             PG8_WAIT_V(8); PG8_WAIT_L(0); PG8_BAR; PG8_MMA(1, 0, At, B0); PG8_MMA(1, 1, At, B1); PG8_BAR; PG8_SCHED;
	s_add_i32 s52, s72, s54
	v_lshl_add_u64 v[218:219], v[218:219], 0, s[20:21]
	s_mov_b32 m0, s52
	ds_read_b128 v[160:163], v210 offset:49152
	ds_read_b128 v[164:167], v210 offset:50176
	ds_read_b128 v[186:189], v210 offset:51200
	ds_read_b128 v[190:193], v210 offset:52224
	ds_read_b128 v[194:197], v210 offset:53248
	ds_read_b128 v[198:201], v210 offset:54272
	ds_read_b128 v[202:205], v210 offset:55296
	ds_read_b128 v[214:217], v210 offset:56320
	global_load_lds_dwordx4 v[218:219], off
	s_add_i32 m0, s52, 0x2000
	s_add_u32 s44, s44, 0x40080
	v_lshl_add_u64 v[218:219], v[220:221], 0, s[20:21]
	s_addc_u32 s45, s45, 0
	s_add_i32 s52, s73, s54
	global_load_lds_dwordx4 v[218:219], off
	v_lshl_add_u64 v[218:219], s[44:45], 0, v[170:171]
	s_mov_b32 m0, s52
	s_nop 0
	global_load_lds_dwordx4 v[218:219], off
	v_lshl_add_u64 v[218:219], s[44:45], 0, v[174:175]
	s_add_i32 m0, s52, 0x2000
	s_nop 0
	global_load_lds_dwordx4 v[218:219], off
	v_lshl_add_u64 v[218:219], v[222:223], 0, s[20:21]
	s_mov_b32 m0, s62
	s_nop 0
	global_load_lds_dwordx4 v[218:219], off
	v_lshl_add_u64 v[218:219], v[224:225], 0, s[20:21]
	s_mov_b32 m0, s63
	s_nop 0
	global_load_lds_dwordx4 v[218:219], off
	s_waitcnt vmcnt(8)
	s_waitcnt lgkmcnt(0)
	s_barrier
	s_setprio 1
	s_waitcnt lgkmcnt(0)
	v_mfma_f32_16x16x32_bf16 v[76:79], v[56:59], v[160:163], v[76:79]
	v_mfma_f32_16x16x32_bf16 v[72:75], v[64:67], v[160:163], v[72:75]
	v_mfma_f32_16x16x32_bf16 v[52:55], v[56:59], v[186:189], v[52:55]
	v_mfma_f32_16x16x32_bf16 v[48:51], v[64:67], v[186:189], v[48:51]
	v_mfma_f32_16x16x32_bf16 v[28:31], v[56:59], v[194:197], v[28:31]
	v_mfma_f32_16x16x32_bf16 v[24:27], v[64:67], v[194:197], v[24:27]
	v_mfma_f32_16x16x32_bf16 v[12:15], v[56:59], v[202:205], v[12:15]
	v_mfma_f32_16x16x32_bf16 v[8:11], v[64:67], v[202:205], v[8:11]
	v_mfma_f32_16x16x32_bf16 v[76:79], v[60:63], v[164:167], v[76:79]
	v_mfma_f32_16x16x32_bf16 v[72:75], v[68:71], v[164:167], v[72:75]
	v_mfma_f32_16x16x32_bf16 v[52:55], v[60:63], v[190:193], v[52:55]
	v_mfma_f32_16x16x32_bf16 v[48:51], v[68:71], v[190:193], v[48:51]
	v_mfma_f32_16x16x32_bf16 v[28:31], v[60:63], v[198:201], v[28:31]
	v_mfma_f32_16x16x32_bf16 v[24:27], v[68:71], v[198:201], v[24:27]
	v_mfma_f32_16x16x32_bf16 v[12:15], v[60:63], v[214:217], v[12:15]
	v_mfma_f32_16x16x32_bf16 v[8:11], v[68:71], v[214:217], v[8:11]
	s_setprio 0
	s_setprio 1
	v_mfma_f32_16x16x32_bf16 v[40:43], v[144:147], v[160:163], v[40:43]
	v_mfma_f32_16x16x32_bf16 v[68:71], v[148:151], v[164:167], v[40:43]
	v_mfma_f32_16x16x32_bf16 v[40:43], v[152:155], v[160:163], v[44:47]
	v_mfma_f32_16x16x32_bf16 v[36:39], v[144:147], v[186:189], v[36:39]
	v_mfma_f32_16x16x32_bf16 v[32:35], v[152:155], v[186:189], v[32:35]
	v_mfma_f32_16x16x32_bf16 v[20:23], v[144:147], v[194:197], v[20:23]
	v_mfma_f32_16x16x32_bf16 v[16:19], v[152:155], v[194:197], v[16:19]
	v_mfma_f32_16x16x32_bf16 v[4:7], v[144:147], v[202:205], v[4:7]
	v_mfma_f32_16x16x32_bf16 v[0:3], v[152:155], v[202:205], v[0:3]
	v_mfma_f32_16x16x32_bf16 v[64:67], v[156:159], v[164:167], v[40:43]
	v_mfma_f32_16x16x32_bf16 v[36:39], v[148:151], v[190:193], v[36:39]
	v_mfma_f32_16x16x32_bf16 v[32:35], v[156:159], v[190:193], v[32:35]
	v_mfma_f32_16x16x32_bf16 v[20:23], v[148:151], v[198:201], v[20:23]
	v_mfma_f32_16x16x32_bf16 v[16:19], v[156:159], v[198:201], v[16:19]
	v_mfma_f32_16x16x32_bf16 v[4:7], v[148:151], v[214:217], v[4:7]
	v_mfma_f32_16x16x32_bf16 v[0:3], v[156:159], v[214:217], v[0:3]
	s_setprio 0
	s_barrier
	s_add_i32 s71, s71, 2
	s_add_u32 s42, s42, 0x100
	s_addc_u32 s43, s43, 0
	s_add_u32 s69, s69, 0x100
	s_addc_u32 s70, s70, 0
	s_cmp_gt_u32 s71, 13
